# epilogue VALU diet: 307 IEEE 1.0/x division expansions (x=1+exp>=1) replaced by v_rcp+Newton step+v_div_fixup (f32), dead denormal rescue removed around 91 clamped exp2 in hgrn prep; MLA attention QK
# speedup vs baseline: 1.0251x; 1.0154x over previous
.LBB0_175:
	s_and_b32 s24, s39, 0xffffffe0
	v_or_b32_e32 v2, s24, v8
	v_mov_b64_e32 v[4:5], s[20:21]
	s_ashr_i32 s26, s40, 1
	v_mad_i64_i32 v[4:5], s[24:25], v2, s41, v[4:5]
	s_lshl_b32 s24, s26, 7
	s_and_b32 s33, s24, 0x380
	v_and_or_b32 v21, s38, 64, v1
	s_lshl_b32 s50, s33, 1
	v_lshl_add_u64 v[4:5], v[4:5], 0, s[50:51]
	v_lshlrev_b32_e32 v2, 1, v21
	v_lshl_add_u64 v[68:69], v[4:5], 0, v[2:3]
	s_movk_i32 s28, 0x2000
	v_add_co_u32_e32 v4, vcc, s28, v68
	s_mov_b32 s28, 0xa000
	s_nop 0
	v_addc_co_u32_e32 v5, vcc, 0, v69, vcc
	v_add_co_u32_e32 v66, vcc, s28, v68
	s_mov_b32 s28, 0x12000
	s_nop 0
	v_addc_co_u32_e32 v67, vcc, 0, v69, vcc
	v_add_co_u32_e32 v64, vcc, s28, v68
	s_mov_b32 s28, 0x1a000
	s_nop 0
	v_addc_co_u32_e32 v65, vcc, 0, v69, vcc
	v_add_co_u32_e32 v62, vcc, s28, v68
	s_mov_b32 s28, 0x23000
	s_nop 0
	v_addc_co_u32_e32 v63, vcc, 0, v69, vcc
	v_add_co_u32_e32 v32, vcc, s28, v68
	s_mov_b32 s28, 0x2b000
	s_nop 0
	v_addc_co_u32_e32 v33, vcc, 0, v69, vcc
	v_add_co_u32_e32 v34, vcc, s28, v68
	s_mov_b32 s28, 0x33000
	s_nop 0
	v_addc_co_u32_e32 v35, vcc, 0, v69, vcc
	v_add_co_u32_e32 v36, vcc, s28, v68
	global_load_dwordx2 v[6:7], v[4:5], off offset:2048
	s_nop 0
	v_addc_co_u32_e32 v37, vcc, 0, v69, vcc
	global_load_dwordx2 v[28:29], v[64:65], off offset:3072
	global_load_dwordx2 v[30:31], v[62:63], off offset:3584
	s_mov_b32 s28, 0x3b000
	global_load_dwordx2 v[32:33], v[32:33], off
	v_add_co_u32_e32 v38, vcc, s28, v68
	global_load_dwordx2 v[34:35], v[34:35], off offset:512
	s_nop 0
	v_addc_co_u32_e32 v39, vcc, 0, v69, vcc
	global_load_dwordx2 v[36:37], v[36:37], off offset:1024
	s_ashr_i32 s27, s26, 31
	global_load_dwordx2 v[4:5], v[66:67], off offset:2560
	s_lshl_b64 s[24:25], s[26:27], 11
	global_load_dwordx2 v[38:39], v[38:39], off offset:1536
	s_lshl_b64 s[26:27], s[26:27], 13
	s_mov_b32 s42, 0xffff0000
	s_add_u32 s28, s34, s26
	s_addc_u32 s29, s35, s27
	v_lshlrev_b32_e32 v72, 6, v21
	v_mov_b32_e32 v73, v3
	v_lshl_add_u64 v[48:49], s[28:29], 0, v[72:73]
	v_lshlrev_b32_e32 v50, 1, v8
	v_mov_b32_e32 v51, v3
	v_lshl_add_u64 v[48:49], v[48:49], 0, v[50:51]
	s_movk_i32 s28, 0x1000
	v_add_co_u32_e32 v82, vcc, s28, v68
	s_add_u32 s24, s36, s24
	s_nop 0
	v_addc_co_u32_e32 v83, vcc, 0, v69, vcc
	s_addc_u32 s25, s37, s25
	v_lshl_add_u64 v[60:61], v[10:11], 0, s[26:27]
	v_lshlrev_b32_e32 v19, 5, v21
	s_waitcnt vmcnt(7)
	v_and_b32_e32 v23, 0xffff, v6
	v_lshrrev_b32_e32 v6, 16, v6
	s_waitcnt vmcnt(1)
	v_lshl_or_b32 v40, v4, 16, v23
	v_and_b32_e32 v23, 0xffff, v28
	v_and_or_b32 v44, v4, s42, v6
	v_lshrrev_b32_e32 v4, 16, v28
	v_lshl_or_b32 v41, v30, 16, v23
	v_and_b32_e32 v23, 0xffff, v32
	v_and_or_b32 v45, v30, s42, v4
	v_lshrrev_b32_e32 v4, 16, v32
	v_lshl_or_b32 v42, v34, 16, v23
	v_and_b32_e32 v23, 0xffff, v36
	v_and_or_b32 v46, v34, s42, v4
	v_lshrrev_b32_e32 v4, 16, v36
	s_waitcnt vmcnt(0)
	v_lshl_or_b32 v43, v38, 16, v23
	v_and_or_b32 v47, v38, s42, v4
	v_and_b32_e32 v4, 0xffff, v7
	global_store_dwordx4 v[48:49], v[40:43], off
	global_store_dwordx4 v[48:49], v[44:47], off offset:64
	v_lshrrev_b32_e32 v6, 16, v33
	v_lshl_or_b32 v40, v5, 16, v4
	v_and_b32_e32 v4, 0xffff, v29
	v_lshl_or_b32 v41, v31, 16, v4
	v_and_b32_e32 v4, 0xffff, v33
	v_lshl_or_b32 v42, v35, 16, v4
	v_and_b32_e32 v4, 0xffff, v37
	v_lshl_or_b32 v43, v39, 16, v4
	v_lshrrev_b32_e32 v4, 16, v7
	v_and_or_b32 v4, v5, s42, v4
	v_lshrrev_b32_e32 v5, 16, v29
	v_lshrrev_b32_e32 v7, 16, v37
	v_and_or_b32 v5, v31, s42, v5
	v_and_or_b32 v6, v35, s42, v6
	v_and_or_b32 v7, v39, s42, v7
	global_store_dwordx4 v[48:49], v[40:43], off offset:128
	global_store_dwordx4 v[48:49], v[4:7], off offset:192
	global_load_dwordx2 v[4:5], v[82:83], off
	s_waitcnt vmcnt(0)
	v_lshlrev_b32_e32 v6, 16, v4
	v_and_b32_e32 v7, 0xffff0000, v4
	v_mul_f32_e32 v4, 0xbfb8aa3b, v6
	v_exp_f32_e32 v28, v4
	v_mul_f32_e32 v4, 0xbfb8aa3b, v7
	v_exp_f32_e32 v29, v4
	s_nop 0
	v_pk_add_f32 v[28:29], v[28:29], 1.0 op_sel_hi:[1,0]
	s_nop 0
	v_rcp_f32_e32 v23, v29
	s_nop 0
	v_fma_f32 v25, -v29, v23, 1.0
	v_fmac_f32_e32 v23, v25, v23
	v_div_fixup_f32 v29, v23, v29, 1.0
	v_rcp_f32_e32 v23, v28
	s_nop 0
	v_fma_f32 v25, -v28, v23, 1.0
	v_fmac_f32_e32 v23, v25, v23
	v_div_fixup_f32 v28, v23, v28, 1.0
	v_lshlrev_b32_e32 v4, 16, v5
	v_and_b32_e32 v5, 0xffff0000, v5
	v_pk_mul_f32 v[46:47], v[28:29], v[6:7]
	v_mul_f32_e32 v6, 0xbfb8aa3b, v4
	v_mul_f32_e32 v7, 0xbfb8aa3b, v5
	v_exp_f32_e32 v6, v6
	v_exp_f32_e32 v7, v7
	s_nop 0
	v_pk_add_f32 v[6:7], v[6:7], 1.0 op_sel_hi:[1,0]
	s_nop 0
	v_rcp_f32_e32 v25, v7
	s_nop 0
	v_fma_f32 v27, -v7, v25, 1.0
	v_fmac_f32_e32 v25, v27, v25
	v_div_fixup_f32 v7, v25, v7, 1.0
	v_rcp_f32_e32 v25, v6
	s_mov_b32 s28, 0x9000
	v_fma_f32 v27, -v6, v25, 1.0
	v_fmac_f32_e32 v25, v27, v25
	v_add_co_u32_e32 v78, vcc, s28, v68
	v_div_fixup_f32 v6, v25, v6, 1.0
	s_nop 0
	v_addc_co_u32_e32 v79, vcc, 0, v69, vcc
	v_pk_mul_f32 v[30:31], v[6:7], v[4:5]
	global_load_dwordx2 v[4:5], v[78:79], off offset:512
	s_waitcnt vmcnt(0)
	v_lshlrev_b32_e32 v6, 16, v4
	v_and_b32_e32 v7, 0xffff0000, v4
	v_mul_f32_e32 v4, 0xbfb8aa3b, v6
	v_exp_f32_e32 v28, v4
	v_mul_f32_e32 v4, 0xbfb8aa3b, v7
	v_exp_f32_e32 v29, v4
	s_nop 0
	v_pk_add_f32 v[28:29], v[28:29], 1.0 op_sel_hi:[1,0]
	s_nop 0
	v_rcp_f32_e32 v23, v29
	s_nop 0
	v_fma_f32 v25, -v29, v23, 1.0
	v_fmac_f32_e32 v23, v25, v23
	v_div_fixup_f32 v29, v23, v29, 1.0
	v_rcp_f32_e32 v23, v28
	s_nop 0
	v_fma_f32 v25, -v28, v23, 1.0
	v_fmac_f32_e32 v23, v25, v23
	v_div_fixup_f32 v28, v23, v28, 1.0
	v_lshlrev_b32_e32 v4, 16, v5
	v_and_b32_e32 v5, 0xffff0000, v5
	v_pk_mul_f32 v[44:45], v[28:29], v[6:7]
	v_mul_f32_e32 v6, 0xbfb8aa3b, v4
	v_mul_f32_e32 v7, 0xbfb8aa3b, v5
	v_exp_f32_e32 v6, v6
	v_exp_f32_e32 v7, v7
	s_nop 0
	v_pk_add_f32 v[6:7], v[6:7], 1.0 op_sel_hi:[1,0]
	s_nop 0
	v_rcp_f32_e32 v25, v7
	s_nop 0
	v_fma_f32 v27, -v7, v25, 1.0
	v_fmac_f32_e32 v25, v27, v25
	v_div_fixup_f32 v7, v25, v7, 1.0
	v_rcp_f32_e32 v25, v6
	s_mov_b32 s28, 0x11000
	v_fma_f32 v27, -v6, v25, 1.0
	v_fmac_f32_e32 v25, v27, v25
	v_add_co_u32_e32 v80, vcc, s28, v68
	v_div_fixup_f32 v6, v25, v6, 1.0
	s_nop 0
	v_addc_co_u32_e32 v81, vcc, 0, v69, vcc
	v_pk_mul_f32 v[28:29], v[6:7], v[4:5]
	global_load_dwordx2 v[4:5], v[80:81], off offset:1024
	s_waitcnt vmcnt(0)
	v_lshlrev_b32_e32 v6, 16, v4
	v_and_b32_e32 v7, 0xffff0000, v4
	v_mul_f32_e32 v4, 0xbfb8aa3b, v6
	v_exp_f32_e32 v32, v4
	v_mul_f32_e32 v4, 0xbfb8aa3b, v7
	v_exp_f32_e32 v33, v4
	s_nop 0
	v_pk_add_f32 v[32:33], v[32:33], 1.0 op_sel_hi:[1,0]
	s_nop 0
	v_rcp_f32_e32 v23, v33
	s_nop 0
	v_fma_f32 v25, -v33, v23, 1.0
	v_fmac_f32_e32 v23, v25, v23
	v_div_fixup_f32 v33, v23, v33, 1.0
	v_rcp_f32_e32 v23, v32
	s_nop 0
	v_fma_f32 v25, -v32, v23, 1.0
	v_fmac_f32_e32 v23, v25, v23
	v_div_fixup_f32 v32, v23, v32, 1.0
	v_lshlrev_b32_e32 v4, 16, v5
	v_and_b32_e32 v5, 0xffff0000, v5
	v_pk_mul_f32 v[58:59], v[32:33], v[6:7]
	v_mul_f32_e32 v6, 0xbfb8aa3b, v4
	v_mul_f32_e32 v7, 0xbfb8aa3b, v5
	v_exp_f32_e32 v6, v6
	v_exp_f32_e32 v7, v7
	s_nop 0
	v_pk_add_f32 v[6:7], v[6:7], 1.0 op_sel_hi:[1,0]
	s_nop 0
	v_rcp_f32_e32 v25, v7
	s_nop 0
	v_fma_f32 v27, -v7, v25, 1.0
	v_fmac_f32_e32 v25, v27, v25
	v_div_fixup_f32 v7, v25, v7, 1.0
	v_rcp_f32_e32 v25, v6
	s_mov_b32 s28, 0x19000
	v_fma_f32 v27, -v6, v25, 1.0
	v_fmac_f32_e32 v25, v27, v25
	v_add_co_u32_e32 v76, vcc, s28, v68
	v_div_fixup_f32 v6, v25, v6, 1.0
	s_nop 0
	v_addc_co_u32_e32 v77, vcc, 0, v69, vcc
	v_pk_mul_f32 v[42:43], v[6:7], v[4:5]
	global_load_dwordx2 v[4:5], v[76:77], off offset:1536
	s_waitcnt vmcnt(0)
	v_lshlrev_b32_e32 v6, 16, v4
	v_and_b32_e32 v7, 0xffff0000, v4
	v_mul_f32_e32 v4, 0xbfb8aa3b, v6
	v_exp_f32_e32 v32, v4
	v_mul_f32_e32 v4, 0xbfb8aa3b, v7
	v_exp_f32_e32 v33, v4
	s_nop 0
	v_pk_add_f32 v[32:33], v[32:33], 1.0 op_sel_hi:[1,0]
	s_nop 0
	v_rcp_f32_e32 v23, v33
	s_nop 0
	v_fma_f32 v25, -v33, v23, 1.0
	v_fmac_f32_e32 v23, v25, v23
	v_div_fixup_f32 v33, v23, v33, 1.0
	v_rcp_f32_e32 v23, v32
	s_nop 0
	v_fma_f32 v25, -v32, v23, 1.0
	v_fmac_f32_e32 v23, v25, v23
	v_div_fixup_f32 v32, v23, v32, 1.0
	v_lshlrev_b32_e32 v4, 16, v5
	v_and_b32_e32 v5, 0xffff0000, v5
	v_pk_mul_f32 v[56:57], v[32:33], v[6:7]
	v_mul_f32_e32 v6, 0xbfb8aa3b, v4
	v_mul_f32_e32 v7, 0xbfb8aa3b, v5
	v_exp_f32_e32 v6, v6
	v_exp_f32_e32 v7, v7
	s_nop 0
	v_pk_add_f32 v[6:7], v[6:7], 1.0 op_sel_hi:[1,0]
	s_nop 0
	v_rcp_f32_e32 v25, v7
	s_nop 0
	v_fma_f32 v27, -v7, v25, 1.0
	v_fmac_f32_e32 v25, v27, v25
	v_div_fixup_f32 v7, v25, v7, 1.0
	v_rcp_f32_e32 v25, v6
	s_mov_b32 s28, 0x21000
	v_fma_f32 v27, -v6, v25, 1.0
	v_fmac_f32_e32 v25, v27, v25
	v_div_fixup_f32 v6, v25, v6, 1.0
	v_pk_mul_f32 v[40:41], v[6:7], v[4:5]
	v_add_co_u32_e32 v4, vcc, s28, v68
	s_nop 1
	v_addc_co_u32_e32 v5, vcc, 0, v69, vcc
	global_load_dwordx2 v[4:5], v[4:5], off offset:2048
	s_waitcnt vmcnt(0)
	v_lshlrev_b32_e32 v6, 16, v4
	v_and_b32_e32 v7, 0xffff0000, v4
	v_mul_f32_e32 v4, 0xbfb8aa3b, v6
	v_exp_f32_e32 v32, v4
	v_mul_f32_e32 v4, 0xbfb8aa3b, v7
	v_exp_f32_e32 v33, v4
	s_nop 0
	v_pk_add_f32 v[32:33], v[32:33], 1.0 op_sel_hi:[1,0]
	s_nop 0
	v_rcp_f32_e32 v23, v33
	s_nop 0
	v_fma_f32 v25, -v33, v23, 1.0
	v_fmac_f32_e32 v23, v25, v23
	v_div_fixup_f32 v33, v23, v33, 1.0
	v_rcp_f32_e32 v23, v32
	s_nop 0
	v_fma_f32 v25, -v32, v23, 1.0
	v_fmac_f32_e32 v23, v25, v23
	v_div_fixup_f32 v32, v23, v32, 1.0
	v_lshlrev_b32_e32 v4, 16, v5
	v_and_b32_e32 v5, 0xffff0000, v5
	v_pk_mul_f32 v[54:55], v[32:33], v[6:7]
	v_mul_f32_e32 v6, 0xbfb8aa3b, v4
	v_mul_f32_e32 v7, 0xbfb8aa3b, v5
	v_exp_f32_e32 v6, v6
	v_exp_f32_e32 v7, v7
	s_nop 0
	v_pk_add_f32 v[6:7], v[6:7], 1.0 op_sel_hi:[1,0]
	s_nop 0
	v_rcp_f32_e32 v25, v7
	s_nop 0
	v_fma_f32 v27, -v7, v25, 1.0
	v_fmac_f32_e32 v25, v27, v25
	v_div_fixup_f32 v7, v25, v7, 1.0
	v_rcp_f32_e32 v25, v6
	s_mov_b32 s28, 0x29000
	v_fma_f32 v27, -v6, v25, 1.0
	v_fmac_f32_e32 v25, v27, v25
	v_div_fixup_f32 v6, v25, v6, 1.0
	v_pk_mul_f32 v[38:39], v[6:7], v[4:5]
	v_add_co_u32_e32 v4, vcc, s28, v68
	s_nop 1
	v_addc_co_u32_e32 v5, vcc, 0, v69, vcc
	global_load_dwordx2 v[4:5], v[4:5], off offset:2560
	s_waitcnt vmcnt(0)
	v_lshlrev_b32_e32 v6, 16, v4
	v_and_b32_e32 v7, 0xffff0000, v4
	v_mul_f32_e32 v4, 0xbfb8aa3b, v6
	v_exp_f32_e32 v32, v4
	v_mul_f32_e32 v4, 0xbfb8aa3b, v7
	v_exp_f32_e32 v33, v4
	s_nop 0
	v_pk_add_f32 v[32:33], v[32:33], 1.0 op_sel_hi:[1,0]
	s_nop 0
	v_rcp_f32_e32 v23, v33
	s_nop 0
	v_fma_f32 v25, -v33, v23, 1.0
	v_fmac_f32_e32 v23, v25, v23
	v_div_fixup_f32 v33, v23, v33, 1.0
	v_rcp_f32_e32 v23, v32
	s_nop 0
	v_fma_f32 v25, -v32, v23, 1.0
	v_fmac_f32_e32 v23, v25, v23
	v_div_fixup_f32 v32, v23, v32, 1.0
	v_lshlrev_b32_e32 v4, 16, v5
	v_and_b32_e32 v5, 0xffff0000, v5
	v_pk_mul_f32 v[52:53], v[32:33], v[6:7]
	v_mul_f32_e32 v6, 0xbfb8aa3b, v4
	v_mul_f32_e32 v7, 0xbfb8aa3b, v5
	v_exp_f32_e32 v6, v6
	v_exp_f32_e32 v7, v7
	s_nop 0
	v_pk_add_f32 v[6:7], v[6:7], 1.0 op_sel_hi:[1,0]
	s_nop 0
	v_rcp_f32_e32 v25, v7
	s_nop 0
	v_fma_f32 v27, -v7, v25, 1.0
	v_fmac_f32_e32 v25, v27, v25
	v_div_fixup_f32 v7, v25, v7, 1.0
	v_rcp_f32_e32 v25, v6
	s_mov_b32 s28, 0x31000
	v_fma_f32 v27, -v6, v25, 1.0
	v_fmac_f32_e32 v25, v27, v25
	v_div_fixup_f32 v6, v25, v6, 1.0
	v_pk_mul_f32 v[36:37], v[6:7], v[4:5]
	v_add_co_u32_e32 v4, vcc, s28, v68
	s_nop 1
	v_addc_co_u32_e32 v5, vcc, 0, v69, vcc
	global_load_dwordx2 v[4:5], v[4:5], off offset:3072
	s_waitcnt vmcnt(0)
	v_lshlrev_b32_e32 v6, 16, v4
	v_and_b32_e32 v7, 0xffff0000, v4
	v_mul_f32_e32 v4, 0xbfb8aa3b, v6
	v_exp_f32_e32 v32, v4
	v_mul_f32_e32 v4, 0xbfb8aa3b, v7
	v_exp_f32_e32 v33, v4
	s_nop 0
	v_pk_add_f32 v[32:33], v[32:33], 1.0 op_sel_hi:[1,0]
	s_nop 0
	v_rcp_f32_e32 v23, v33
	s_nop 0
	v_fma_f32 v25, -v33, v23, 1.0
	v_fmac_f32_e32 v23, v25, v23
	v_div_fixup_f32 v33, v23, v33, 1.0
	v_rcp_f32_e32 v23, v32
	s_nop 0
	v_fma_f32 v25, -v32, v23, 1.0
	v_fmac_f32_e32 v23, v25, v23
	v_div_fixup_f32 v32, v23, v32, 1.0
	v_lshlrev_b32_e32 v4, 16, v5
	v_and_b32_e32 v5, 0xffff0000, v5
	v_pk_mul_f32 v[50:51], v[32:33], v[6:7]
	v_mul_f32_e32 v6, 0xbfb8aa3b, v4
	v_mul_f32_e32 v7, 0xbfb8aa3b, v5
	v_exp_f32_e32 v6, v6
	v_exp_f32_e32 v7, v7
	s_nop 0
	v_pk_add_f32 v[6:7], v[6:7], 1.0 op_sel_hi:[1,0]
	s_nop 0
	v_rcp_f32_e32 v25, v7
	s_nop 0
	v_fma_f32 v27, -v7, v25, 1.0
	v_fmac_f32_e32 v25, v27, v25
	v_div_fixup_f32 v7, v25, v7, 1.0
	v_rcp_f32_e32 v25, v6
	s_mov_b32 s28, 0x39000
	v_fma_f32 v27, -v6, v25, 1.0
	v_fmac_f32_e32 v25, v27, v25
	v_div_fixup_f32 v6, v25, v6, 1.0
	v_pk_mul_f32 v[34:35], v[6:7], v[4:5]
	v_add_co_u32_e32 v4, vcc, s28, v68
	s_nop 1
	v_addc_co_u32_e32 v5, vcc, 0, v69, vcc
	global_load_dwordx2 v[4:5], v[4:5], off offset:3584
	s_waitcnt vmcnt(0)
	v_lshlrev_b32_e32 v6, 16, v4
	v_and_b32_e32 v7, 0xffff0000, v4
	v_mul_f32_e32 v4, 0xbfb8aa3b, v6
	v_exp_f32_e32 v32, v4
	v_mul_f32_e32 v4, 0xbfb8aa3b, v7
	v_exp_f32_e32 v33, v4
	s_nop 0
	v_pk_add_f32 v[32:33], v[32:33], 1.0 op_sel_hi:[1,0]
	s_nop 0
	v_rcp_f32_e32 v23, v33
	s_nop 0
	v_fma_f32 v25, -v33, v23, 1.0
	v_fmac_f32_e32 v23, v25, v23
	v_div_fixup_f32 v33, v23, v33, 1.0
	v_rcp_f32_e32 v23, v32
	s_nop 0
	v_fma_f32 v25, -v32, v23, 1.0
	v_fmac_f32_e32 v23, v25, v23
	v_div_fixup_f32 v32, v23, v32, 1.0
	v_lshlrev_b32_e32 v4, 16, v5
	v_and_b32_e32 v5, 0xffff0000, v5
	v_pk_mul_f32 v[48:49], v[32:33], v[6:7]
	v_mul_f32_e32 v6, 0xbfb8aa3b, v4
	v_mul_f32_e32 v7, 0xbfb8aa3b, v5
	v_exp_f32_e32 v6, v6
	v_exp_f32_e32 v7, v7
	s_nop 0
	v_pk_add_f32 v[6:7], v[6:7], 1.0 op_sel_hi:[1,0]
	s_nop 0
	v_rcp_f32_e32 v25, v7
	s_nop 0
	v_fma_f32 v27, -v7, v25, 1.0
	v_fmac_f32_e32 v25, v27, v25
	v_div_fixup_f32 v7, v25, v7, 1.0
	v_rcp_f32_e32 v25, v6
	s_lshl_b32 s28, s33, 2
	s_add_u32 s28, s30, s28
	s_addc_u32 s29, s31, 0
	v_fma_f32 v27, -v6, v25, 1.0
	v_fmac_f32_e32 v25, v27, v25
	v_div_fixup_f32 v6, v25, v6, 1.0
	v_pk_mul_f32 v[32:33], v[6:7], v[4:5]
	v_lshlrev_b32_e32 v4, 2, v21
	v_mov_b32_e32 v5, v3
	v_lshl_add_u64 v[4:5], s[28:29], 0, v[4:5]
	v_lshl_add_u64 v[74:75], s[0:1], 2, v[4:5]
	global_load_dwordx4 v[4:7], v[74:75], off
	s_nop 0
	global_load_dwordx2 v[82:83], v[82:83], off offset:2048
	s_add_u32 s28, s22, s26
	global_load_dwordx2 v[78:79], v[78:79], off offset:2560
	s_addc_u32 s29, s23, s27
	v_lshl_add_u64 v[70:71], s[28:29], 0, v[2:3]
	global_load_dwordx2 v[76:77], v[76:77], off offset:3584
	s_mov_b32 s28, 0xc2480000
	s_mov_b32 s33, 0xc2fc0000
	v_and_or_b32 v21, v21, s83, v17
	v_lshlrev_b32_e32 v21, 2, v21
	s_waitcnt vmcnt(3)
	v_pk_add_f32 v[134:135], v[4:5], 1.0 op_sel_hi:[1,0] neg_lo:[1,0] neg_hi:[1,0]
	s_waitcnt vmcnt(2)
	v_lshlrev_b32_e32 v2, 16, v82
	v_mul_f32_e32 v2, 0xbfb8aa3b, v2
	v_exp_f32_e32 v2, v2
	v_and_b32_e32 v23, 0xffff0000, v82
	v_lshlrev_b32_e32 v25, 16, v83
	v_and_b32_e32 v82, 0xffff0000, v83
	v_add_f32_e32 v27, 1.0, v2
	v_rcp_f32_e32 v84, v27
	s_nop 0
	v_fma_f32 v85, -v27, v84, 1.0
	v_fmac_f32_e32 v84, v85, v84
	v_div_fixup_f32 v107, v84, v27, 1.0
	v_mul_f32_e32 v105, v2, v107
	v_mul_f32_e32 v2, 0xbfb8aa3b, v23
	v_exp_f32_e32 v2, v2
	v_fma_f32 v107, v134, v107, v4
	v_log_f32_e32 v107, v107
	v_mul_f32_e32 v154, v134, v105
	v_add_f32_e32 v23, 1.0, v2
	v_rcp_f32_e32 v83, v23
	v_max_f32_e32 v132, 0xc2c80000, v107
	v_fma_f32 v84, -v23, v83, 1.0
	v_fmac_f32_e32 v83, v84, v83
	v_div_fixup_f32 v108, v83, v23, 1.0
	v_mul_f32_e32 v106, v2, v108
	v_mul_f32_e32 v2, 0xbfb8aa3b, v25
	v_exp_f32_e32 v2, v2
	v_fma_f32 v105, v135, v108, v5
	v_log_f32_e32 v105, v105
	v_mul_f32_e32 v150, v135, v106
	v_add_f32_e32 v23, 1.0, v2
	v_rcp_f32_e32 v27, v23
	v_max_f32_e32 v124, 0xc2c80000, v105
	v_fma_f32 v83, -v23, v27, 1.0
	v_fmac_f32_e32 v27, v83, v27
	v_div_fixup_f32 v27, v27, v23, 1.0
	v_mul_f32_e32 v23, v2, v27
	v_mul_f32_e32 v2, 0xbfb8aa3b, v82
	v_exp_f32_e32 v2, v2
	s_nop 0
	v_add_f32_e32 v25, 1.0, v2
	v_rcp_f32_e32 v83, v25
	s_nop 0
	v_fma_f32 v84, -v25, v83, 1.0
	v_fmac_f32_e32 v83, v84, v83
	v_div_fixup_f32 v104, v83, v25, 1.0
	v_mul_f32_e32 v25, v2, v104
	s_waitcnt vmcnt(1)
	v_lshlrev_b32_e32 v2, 16, v78
	v_and_b32_e32 v78, 0xffff0000, v78
	v_mul_f32_e32 v2, 0xbfb8aa3b, v2
	v_lshlrev_b32_e32 v82, 16, v79
	v_exp_f32_e32 v86, v2
	v_mul_f32_e32 v2, 0xbfb8aa3b, v78
	v_and_b32_e32 v79, 0xffff0000, v79
	v_exp_f32_e32 v87, v2
	v_mul_f32_e32 v2, 0xbfb8aa3b, v82
	v_exp_f32_e32 v84, v2
	v_mul_f32_e32 v2, 0xbfb8aa3b, v79
	global_load_dwordx2 v[78:79], v[80:81], off offset:3072
	v_exp_f32_e32 v85, v2
	v_pk_add_f32 v[106:107], v[86:87], 1.0 op_sel_hi:[1,0]
	s_waitcnt vmcnt(0)
	v_lshlrev_b32_e32 v2, 16, v78
	v_mul_f32_e32 v2, 0xbfb8aa3b, v2
	v_exp_f32_e32 v2, v2
	v_and_b32_e32 v78, 0xffff0000, v78
	v_lshlrev_b32_e32 v80, 16, v79
	v_and_b32_e32 v79, 0xffff0000, v79
	v_add_f32_e32 v81, 1.0, v2
	v_rcp_f32_e32 v83, v81
	s_nop 0
	v_fma_f32 v88, -v81, v83, 1.0
	v_fmac_f32_e32 v83, v88, v83
	v_div_fixup_f32 v115, v83, v81, 1.0
	v_mul_f32_e32 v114, v2, v115
	v_mul_f32_e32 v2, 0xbfb8aa3b, v78
	v_exp_f32_e32 v2, v2
	v_mul_f32_e32 v152, v134, v114
	v_add_f32_e32 v78, 1.0, v2
	v_rcp_f32_e32 v82, v78
	s_nop 0
	v_fma_f32 v83, -v78, v82, 1.0
	v_fmac_f32_e32 v82, v83, v82
	v_div_fixup_f32 v116, v82, v78, 1.0
	v_mul_f32_e32 v110, v2, v116
	v_mul_f32_e32 v2, 0xbfb8aa3b, v80
	v_exp_f32_e32 v2, v2
	v_mul_f32_e32 v148, v135, v110
	v_add_f32_e32 v78, 1.0, v2
	v_rcp_f32_e32 v81, v78
	s_nop 0
	v_fma_f32 v82, -v78, v81, 1.0
	v_fmac_f32_e32 v81, v82, v81
	v_div_fixup_f32 v112, v81, v78, 1.0
	v_mul_f32_e32 v111, v2, v112
	v_mul_f32_e32 v2, 0xbfb8aa3b, v79
	v_exp_f32_e32 v2, v2
	s_nop 0
	v_add_f32_e32 v78, 1.0, v2
	v_rcp_f32_e32 v80, v78
	s_mov_b32 s26, 0x22000
	v_fma_f32 v81, -v78, v80, 1.0
	v_fmac_f32_e32 v80, v81, v80
	v_div_fixup_f32 v113, v80, v78, 1.0
	v_mul_f32_e32 v109, v2, v113
	v_lshlrev_b32_e32 v2, 16, v76
	v_and_b32_e32 v76, 0xffff0000, v76
	v_mul_f32_e32 v2, 0xbfb8aa3b, v2
	v_lshlrev_b32_e32 v78, 16, v77
	v_exp_f32_e32 v90, v2
	v_mul_f32_e32 v2, 0xbfb8aa3b, v76
	v_and_b32_e32 v77, 0xffff0000, v77
	v_exp_f32_e32 v91, v2
	v_mul_f32_e32 v2, 0xbfb8aa3b, v78
	v_add_co_u32_e32 v76, vcc, s26, v68
	v_exp_f32_e32 v88, v2
	v_mul_f32_e32 v2, 0xbfb8aa3b, v77
	v_addc_co_u32_e32 v77, vcc, 0, v69, vcc
	global_load_dwordx2 v[78:79], v[76:77], off
	v_exp_f32_e32 v89, v2
	s_waitcnt vmcnt(0)
	v_lshlrev_b32_e32 v2, 16, v78
	v_mul_f32_e32 v2, 0xbfb8aa3b, v2
	v_exp_f32_e32 v2, v2
	v_and_b32_e32 v78, 0xffff0000, v78
	v_lshlrev_b32_e32 v80, 16, v79
	v_and_b32_e32 v79, 0xffff0000, v79
	v_add_f32_e32 v81, 1.0, v2
	v_rcp_f32_e32 v83, v81
	s_nop 0
	v_fma_f32 v92, -v81, v83, 1.0
	v_fmac_f32_e32 v83, v92, v83
	v_div_fixup_f32 v123, v83, v81, 1.0
	v_mul_f32_e32 v122, v2, v123
	v_mul_f32_e32 v2, 0xbfb8aa3b, v78
	v_exp_f32_e32 v2, v2
	v_mul_f32_e32 v146, v134, v122
	v_add_f32_e32 v78, 1.0, v2
	v_rcp_f32_e32 v82, v78
	s_nop 0
	v_fma_f32 v83, -v78, v82, 1.0
	v_fmac_f32_e32 v82, v83, v82
	v_div_fixup_f32 v125, v82, v78, 1.0
	v_mul_f32_e32 v117, v2, v125
	v_mul_f32_e32 v2, 0xbfb8aa3b, v80
	v_exp_f32_e32 v2, v2
	v_mul_f32_e32 v144, v135, v117
	v_add_f32_e32 v78, 1.0, v2
	v_rcp_f32_e32 v81, v78
	s_nop 0
	v_fma_f32 v82, -v78, v81, 1.0
	v_fmac_f32_e32 v81, v82, v81
	v_div_fixup_f32 v120, v81, v78, 1.0
	v_mul_f32_e32 v119, v2, v120
	v_mul_f32_e32 v2, 0xbfb8aa3b, v79
	v_exp_f32_e32 v2, v2
	s_nop 0
	v_add_f32_e32 v78, 1.0, v2
	v_rcp_f32_e32 v80, v78
	s_mov_b32 s26, 0x2a000
	v_fma_f32 v81, -v78, v80, 1.0
	v_fmac_f32_e32 v80, v81, v80
	v_add_co_u32_e32 v82, vcc, s26, v68
	v_div_fixup_f32 v121, v80, v78, 1.0
	s_nop 0
	v_addc_co_u32_e32 v83, vcc, 0, v69, vcc
	global_load_dwordx2 v[78:79], v[82:83], off offset:512
	v_mul_f32_e32 v118, v2, v121
	s_mov_b32 s26, 0x32000
	s_waitcnt vmcnt(0)
	v_lshlrev_b32_e32 v2, 16, v78
	v_and_b32_e32 v78, 0xffff0000, v78
	v_mul_f32_e32 v2, 0xbfb8aa3b, v2
	v_lshlrev_b32_e32 v80, 16, v79
	v_exp_f32_e32 v100, v2
	v_mul_f32_e32 v2, 0xbfb8aa3b, v78
	v_exp_f32_e32 v101, v2
	v_mul_f32_e32 v2, 0xbfb8aa3b, v80
	v_add_co_u32_e32 v80, vcc, s26, v68
	v_and_b32_e32 v79, 0xffff0000, v79
	s_nop 0
	v_addc_co_u32_e32 v81, vcc, 0, v69, vcc
	v_exp_f32_e32 v98, v2
	v_mul_f32_e32 v2, 0xbfb8aa3b, v79
	global_load_dwordx2 v[78:79], v[80:81], off offset:1024
	v_exp_f32_e32 v99, v2
	s_waitcnt vmcnt(0)
	v_lshlrev_b32_e32 v2, 16, v78
	v_mul_f32_e32 v2, 0xbfb8aa3b, v2
	v_exp_f32_e32 v2, v2
	v_and_b32_e32 v78, 0xffff0000, v78
	v_lshlrev_b32_e32 v92, 16, v79
	v_and_b32_e32 v79, 0xffff0000, v79
	v_add_f32_e32 v93, 1.0, v2
	v_rcp_f32_e32 v95, v93
	s_nop 0
	v_fma_f32 v96, -v93, v95, 1.0
	v_fmac_f32_e32 v95, v96, v95
	v_div_fixup_f32 v139, v95, v93, 1.0
	v_mul_f32_e32 v138, v2, v139
	v_mul_f32_e32 v2, 0xbfb8aa3b, v78
	v_exp_f32_e32 v2, v2
	v_mul_f32_e32 v142, v134, v138
	v_add_f32_e32 v78, 1.0, v2
	v_rcp_f32_e32 v94, v78
	s_nop 0
	v_fma_f32 v95, -v78, v94, 1.0
	v_fmac_f32_e32 v94, v95, v94
	v_div_fixup_f32 v140, v94, v78, 1.0
	v_mul_f32_e32 v133, v2, v140
	v_mul_f32_e32 v2, 0xbfb8aa3b, v92
	v_exp_f32_e32 v2, v2
	s_nop 0
	v_add_f32_e32 v78, 1.0, v2
	v_rcp_f32_e32 v93, v78
	s_nop 0
	v_fma_f32 v94, -v78, v93, 1.0
	v_fmac_f32_e32 v93, v94, v93
	v_div_fixup_f32 v128, v93, v78, 1.0
	v_mul_f32_e32 v127, v2, v128
	v_mul_f32_e32 v2, 0xbfb8aa3b, v79
	v_exp_f32_e32 v2, v2
	s_nop 0
	v_add_f32_e32 v78, 1.0, v2
	v_rcp_f32_e32 v92, v78
	s_mov_b32 s26, 0x3a000
	v_fma_f32 v93, -v78, v92, 1.0
	v_fmac_f32_e32 v92, v93, v92
	v_div_fixup_f32 v129, v92, v78, 1.0
	v_add_co_u32_e32 v78, vcc, s26, v68
	v_mul_f32_e32 v126, v2, v129
	s_nop 0
	v_addc_co_u32_e32 v79, vcc, 0, v69, vcc
	global_load_dwordx2 v[92:93], v[78:79], off offset:1536
	s_mov_b64 s[26:27], 0x3000000
	s_waitcnt vmcnt(0)
	v_lshlrev_b32_e32 v2, 16, v92
	v_and_b32_e32 v92, 0xffff0000, v92
	v_mul_f32_e32 v2, 0xbfb8aa3b, v2
	v_lshlrev_b32_e32 v94, 16, v93
	v_exp_f32_e32 v136, v2
	v_mul_f32_e32 v2, 0xbfb8aa3b, v92
	v_exp_f32_e32 v137, v2
	v_mul_f32_e32 v2, 0xbfb8aa3b, v94
	v_lshl_add_u64 v[94:95], v[70:71], 0, s[26:27]
	v_rcp_f32_e32 v108, v107
	v_pk_add_f32 v[168:169], v[136:137], 1.0 op_sel_hi:[1,0]
	v_and_b32_e32 v93, 0xffff0000, v93
	v_exp_f32_e32 v102, v2
	v_fma_f32 v130, -v107, v108, 1.0
	v_fmac_f32_e32 v108, v130, v108
	v_div_fixup_f32 v107, v108, v107, 1.0
	v_rcp_f32_e32 v108, v106
	v_mul_f32_e32 v2, 0xbfb8aa3b, v93
	v_exp_f32_e32 v103, v2
	v_lshlrev_b32_e32 v2, 1, v12
	v_fma_f32 v130, -v106, v108, 1.0
	v_fmac_f32_e32 v108, v130, v108
	v_div_fixup_f32 v106, v108, v106, 1.0
	v_pk_mul_f32 v[130:131], v[134:135], v[106:107]
	v_pk_mul_f32 v[86:87], v[86:87], v[106:107]
	v_fma_f32 v106, v134, v123, v4
	v_log_f32_e32 v106, v106
	v_add_f32_e32 v105, v4, v130
	v_add_f32_e32 v108, v5, v131
	v_log_f32_e32 v105, v105
	v_max_f32_e32 v141, 0xc2c80000, v106
	v_fma_f32 v106, v135, v125, v5
	v_log_f32_e32 v106, v106
	v_log_f32_e32 v108, v108
	v_pk_mul_f32 v[130:131], v[134:135], v[86:87]
	v_fma_f32 v86, v134, v115, v4
	v_max_f32_e32 v162, 0xc2c80000, v106
	v_fma_f32 v106, v134, v139, v4
	v_log_f32_e32 v106, v106
	v_fma_f32 v87, v135, v116, v5
	v_log_f32_e32 v86, v86
	v_log_f32_e32 v87, v87
	v_pk_add_f32 v[116:117], v[6:7], 1.0 op_sel_hi:[1,0] neg_lo:[1,0] neg_hi:[1,0]
	v_max_f32_e32 v122, 0xc2c80000, v106
	v_fma_f32 v106, v135, v140, v5
	v_mul_f32_e32 v151, v116, v23
	v_fma_f32 v23, v117, v104, v7
	v_log_f32_e32 v106, v106
	v_log_f32_e32 v23, v23
	v_max_f32_e32 v105, 0xc2c80000, v105
	v_max_f32_e32 v108, 0xc2c80000, v108
	v_max_f32_e32 v86, 0xc2c80000, v86
	v_max_f32_e32 v87, 0xc2c80000, v87
	v_add_f32_e32 v161, v132, v105
	v_add_f32_e32 v160, v124, v108
	v_add_f32_e32 v158, v161, v86
	v_add_f32_e32 v156, v160, v87
	v_pk_add_f32 v[86:87], v[84:85], 1.0 op_sel_hi:[1,0]
	v_max_f32_e32 v123, 0xc2c80000, v106
	v_fma_f32 v27, v116, v27, v6
	v_max_f32_e32 v106, 0xc2c80000, v23
	v_log_f32_e32 v27, v27
	v_mul_f32_e32 v147, v117, v25
	v_rcp_f32_e32 v25, v87
	v_mul_f32_e32 v149, v116, v111
	v_max_f32_e32 v110, 0xc2c80000, v27
	v_mul_f32_e32 v143, v116, v119
	v_fma_f32 v27, -v87, v25, 1.0
	v_fmac_f32_e32 v25, v27, v25
	v_div_fixup_f32 v87, v25, v87, 1.0
	v_rcp_f32_e32 v25, v86
	v_mul_f32_e32 v107, v135, v133
	v_mul_f32_e32 v145, v117, v109
	v_lshl_add_u64 v[96:97], v[94:95], 0, v[2:3]
	v_fma_f32 v27, -v86, v25, 1.0
	v_fmac_f32_e32 v25, v27, v25
	v_div_fixup_f32 v86, v25, v86, 1.0
	v_pk_mul_f32 v[104:105], v[116:117], v[86:87]
	v_pk_mul_f32 v[84:85], v[84:85], v[86:87]
	v_add_f32_e32 v23, v6, v104
	v_log_f32_e32 v23, v23
	v_mul_f32_e32 v27, v117, v118
	v_mul_f32_e32 v25, v116, v127
	v_lshlrev_b32_e32 v86, 1, v16
	v_max_f32_e32 v108, 0xc2c80000, v23
	v_add_f32_e32 v23, v7, v105
	v_log_f32_e32 v23, v23
	v_pk_mul_f32 v[104:105], v[116:117], v[84:85]
	v_add_f32_e32 v159, v110, v108
	v_mov_b32_e32 v87, v3
	v_max_f32_e32 v114, 0xc2c80000, v23
	v_fma_f32 v23, v116, v112, v6
	v_log_f32_e32 v23, v23
	v_add_f32_e32 v157, v106, v114
	v_pk_add_f32 v[114:115], v[90:91], 1.0 op_sel_hi:[1,0]
	v_lshl_add_u64 v[108:109], v[94:95], 0, v[86:87]
	v_max_f32_e32 v84, 0xc2c80000, v23
	v_fma_f32 v23, v117, v113, v7
	v_log_f32_e32 v23, v23
	v_div_scale_f32 v111, s[26:27], v115, v115, 1.0
	v_rcp_f32_e32 v118, v111
	v_max_f32_e32 v85, 0xc2c80000, v23
	v_fma_f32 v23, v116, v120, v6
	v_log_f32_e32 v23, v23
	v_fma_f32 v119, -v111, v118, 1.0
	v_fmac_f32_e32 v118, v119, v118
	v_div_scale_f32 v119, vcc, 1.0, v115, 1.0
	v_max_f32_e32 v120, 0xc2c80000, v23
	v_fma_f32 v23, v117, v121, v7
	v_log_f32_e32 v23, v23
	v_add_f32_e32 v155, v159, v84
	v_add_f32_e32 v153, v157, v85
	v_lshlrev_b32_e32 v84, 1, v14
	v_max_f32_e32 v121, 0xc2c80000, v23
	v_fma_f32 v23, v116, v128, v6
	v_log_f32_e32 v23, v23
	v_mov_b32_e32 v85, v3
	v_lshl_add_u64 v[112:113], v[94:95], 0, v[84:85]
	v_lshl_add_u64 v[92:93], v[70:71], 0, v[2:3]
	v_max_f32_e32 v125, 0xc2c80000, v23
	v_fma_f32 v23, v117, v129, v7
	v_log_f32_e32 v23, v23
	s_nop 0
	v_max_f32_e32 v133, 0xc2c80000, v23
	v_mul_f32_e32 v23, v117, v126
	v_mul_f32_e32 v126, v119, v118
	v_fma_f32 v127, -v111, v126, v119
	v_fmac_f32_e32 v126, v127, v118
	v_fma_f32 v111, -v111, v126, v119
	v_div_fmas_f32 v111, v111, v118, v126
	v_div_fixup_f32 v115, v111, v115, 1.0
	v_rcp_f32_e32 v118, v114
	s_nop 0
	v_fma_f32 v119, -v114, v118, 1.0
	v_fmac_f32_e32 v118, v119, v118
	v_div_fixup_f32 v114, v118, v114, 1.0
	v_pk_mul_f32 v[90:91], v[90:91], v[114:115]
	v_pk_mul_f32 v[114:115], v[134:135], v[114:115]
	v_pk_mul_f32 v[138:139], v[134:135], v[90:91]
	v_add_f32_e32 v111, v4, v114
	v_add_f32_e32 v114, v5, v115
	v_log_f32_e32 v114, v114
	v_pk_add_f32 v[90:91], v[88:89], 1.0 op_sel_hi:[1,0]
	v_log_f32_e32 v111, v111
	v_max_f32_e32 v114, 0xc2c80000, v114
	v_add_f32_e32 v165, v156, v114
	v_rcp_f32_e32 v115, v91
	v_max_f32_e32 v111, 0xc2c80000, v111
	v_add_f32_e32 v192, v158, v111
	v_add_f32_e32 v163, v192, v141
	v_fma_f32 v118, -v91, v115, 1.0
	v_fmac_f32_e32 v115, v118, v115
	v_div_fixup_f32 v91, v115, v91, 1.0
	v_rcp_f32_e32 v115, v90
	v_add_f32_e32 v111, v165, v162
	v_fma_f32 v118, -v90, v115, 1.0
	v_fmac_f32_e32 v115, v118, v115
	v_pk_add_f32 v[126:127], v[100:101], 1.0 op_sel_hi:[1,0]
	v_rcp_f32_e32 v129, v127
	v_div_fixup_f32 v90, v115, v90, 1.0
	v_pk_mul_f32 v[88:89], v[88:89], v[90:91]
	v_fma_f32 v140, -v127, v129, 1.0
	v_fmac_f32_e32 v129, v140, v129
	v_div_fixup_f32 v127, v129, v127, 1.0
	v_rcp_f32_e32 v129, v126
	v_pk_mul_f32 v[90:91], v[116:117], v[90:91]
	v_pk_mul_f32 v[118:119], v[116:117], v[88:89]
	v_add_f32_e32 v90, v6, v90
	v_fma_f32 v140, -v126, v129, 1.0
	v_fmac_f32_e32 v129, v140, v129
	v_div_fixup_f32 v126, v129, v126, 1.0
	v_pk_mul_f32 v[100:101], v[100:101], v[126:127]
	v_pk_mul_f32 v[126:127], v[134:135], v[126:127]
	v_pk_mul_f32 v[140:141], v[134:135], v[100:101]
	v_add_f32_e32 v126, v4, v126
	v_log_f32_e32 v126, v126
	v_add_f32_e32 v127, v5, v127
	v_log_f32_e32 v127, v127
	v_pk_add_f32 v[100:101], v[98:99], 1.0 op_sel_hi:[1,0]
	v_max_f32_e32 v126, 0xc2c80000, v126
	v_add_f32_e32 v196, v163, v126
	v_max_f32_e32 v127, 0xc2c80000, v127
	v_add_f32_e32 v195, v111, v127
	v_add_f32_e32 v194, v196, v122
	v_add_f32_e32 v167, v195, v123
	v_rcp_f32_e32 v123, v101
	v_log_f32_e32 v90, v90
	v_add_f32_e32 v91, v7, v91
	v_log_f32_e32 v91, v91
	v_fma_f32 v126, -v101, v123, 1.0
	v_fmac_f32_e32 v123, v126, v123
	v_div_fixup_f32 v101, v123, v101, 1.0
	v_rcp_f32_e32 v123, v100
	v_max_f32_e32 v90, 0xc2c80000, v90
	v_max_f32_e32 v91, 0xc2c80000, v91
	v_add_f32_e32 v186, v155, v90
	v_fma_f32 v126, -v100, v123, 1.0
	v_fmac_f32_e32 v123, v126, v123
	v_div_fixup_f32 v100, v123, v100, 1.0
	v_pk_mul_f32 v[98:99], v[98:99], v[100:101]
	v_pk_mul_f32 v[100:101], v[116:117], v[100:101]
	v_add_f32_e32 v183, v153, v91
	v_add_f32_e32 v100, v6, v100
	v_log_f32_e32 v100, v100
	v_add_f32_e32 v101, v7, v101
	v_log_f32_e32 v101, v101
	v_add_f32_e32 v178, v186, v120
	v_max_f32_e32 v100, 0xc2c80000, v100
	v_add_f32_e32 v172, v183, v121
	v_max_f32_e32 v101, 0xc2c80000, v101
	v_add_f32_e32 v189, v178, v100
	v_add_f32_e32 v188, v172, v101
	v_add_f32_e32 v187, v189, v125
	v_add_f32_e32 v184, v188, v133
	v_rcp_f32_e32 v133, v169
	v_pk_mul_f32 v[128:129], v[116:117], v[98:99]
	v_lshlrev_b32_e32 v90, 1, v20
	v_mov_b32_e32 v91, v3
	v_fma_f32 v162, -v169, v133, 1.0
	v_fmac_f32_e32 v133, v162, v133
	v_div_fixup_f32 v169, v133, v169, 1.0
	v_rcp_f32_e32 v133, v168
	v_lshlrev_b32_e32 v88, 1, v18
	v_mov_b32_e32 v89, v3
	v_lshl_add_u64 v[114:115], v[94:95], 0, v[90:91]
	v_fma_f32 v162, -v168, v133, 1.0
	v_fmac_f32_e32 v133, v162, v133
	v_div_fixup_f32 v168, v133, v168, 1.0
	v_pk_mul_f32 v[136:137], v[136:137], v[168:169]
	v_pk_mul_f32 v[168:169], v[134:135], v[168:169]
	v_pk_mul_f32 v[136:137], v[134:135], v[136:137]
	v_add_f32_e32 v4, v4, v168
	v_log_f32_e32 v4, v4
	v_add_f32_e32 v5, v5, v169
	v_log_f32_e32 v5, v5
	v_lshlrev_b32_e32 v98, 1, v22
	v_max_f32_e32 v4, 0xc2c80000, v4
	v_add_f32_e32 v173, v194, v4
	ds_bpermute_b32 v176, v13, v173
	ds_bpermute_b32 v177, v15, v173
	ds_bpermute_b32 v174, v9, v173
	v_max_f32_e32 v5, 0xc2c80000, v5
	v_add_f32_e32 v175, v167, v5
	ds_bpermute_b32 v181, v13, v175
	s_waitcnt lgkmcnt(2)
	v_cndmask_b32_e64 v4, v177, v176, s[4:5]
	s_waitcnt lgkmcnt(1)
	v_cndmask_b32_e64 v4, v4, v174, s[10:11]
	v_cndmask_b32_e64 v179, v4, v173, s[8:9]
	v_cndmask_b32_e64 v4, v177, v176, s[10:11]
	v_cndmask_b32_e64 v4, v4, v174, s[4:5]
	ds_bpermute_b32 v182, v15, v175
	v_cndmask_b32_e64 v169, v4, v173, s[6:7]
	v_cndmask_b32_e64 v4, v177, v176, s[8:9]
	ds_bpermute_b32 v180, v9, v175
	v_cndmask_b32_e64 v4, v4, v174, s[6:7]
	v_cndmask_b32_e64 v133, v4, v173, s[4:5]
	v_cndmask_b32_e64 v4, v4, 0, s[4:5]
	v_cndmask_b32_e64 v5, 0, v169, s[16:17]
	v_add_f32_e32 v4, v4, v5
	v_cndmask_b32_e64 v5, 0, v179, s[18:19]
	v_add_f32_e32 v168, v5, v4
	s_waitcnt lgkmcnt(1)
	v_cndmask_b32_e64 v4, v182, v181, s[4:5]
	s_waitcnt lgkmcnt(0)
	v_cndmask_b32_e64 v4, v4, v180, s[10:11]
	v_cndmask_b32_e64 v185, v4, v175, s[8:9]
	v_cndmask_b32_e64 v4, v182, v181, s[10:11]
	v_cndmask_b32_e64 v4, v4, v180, s[4:5]
	v_cndmask_b32_e64 v171, v4, v175, s[6:7]
	v_cndmask_b32_e64 v4, v182, v181, s[8:9]
	v_cndmask_b32_e64 v4, v4, v180, s[6:7]
	v_cndmask_b32_e64 v125, v4, v175, s[4:5]
	v_cndmask_b32_e64 v4, v4, 0, s[4:5]
	v_cndmask_b32_e64 v5, 0, v171, s[16:17]
	v_add_f32_e32 v4, v4, v5
	v_cndmask_b32_e64 v5, 0, v185, s[18:19]
	v_add_f32_e32 v170, v5, v4
	v_pk_add_f32 v[4:5], v[132:133], v[168:169]
	v_pk_add_f32 v[124:125], v[124:125], v[170:171]
	v_sub_f32_e32 v132, v4, v5
	v_med3_f32 v132, v132, s28, v236
	v_sub_f32_e32 v4, v5, v4
	v_med3_f32 v4, v4, s28, v236
	v_exp_f32_e32 v132, v132
	v_add_f32_e32 v135, v160, v170
	v_exp_f32_e32 v4, v4
	v_add_f32_e32 v111, v111, v170
	v_mov_b32_e32 v99, v3
	v_sub_f32_e32 v133, v124, v125
	v_med3_f32 v133, v133, s28, v236
	v_sub_f32_e32 v124, v125, v124
	v_med3_f32 v124, v124, s28, v236
	v_exp_f32_e32 v133, v133
	v_mul_f32_e32 v4, v154, v4
	v_pk_mul_f32 v[132:133], v[46:47], v[132:133]
	v_exp_f32_e32 v124, v124
	v_cvt_pk_bf16_f32 v166, v132, v133
	v_add_f32_e32 v133, v161, v168
	v_sub_f32_e32 v132, v133, v5
	v_med3_f32 v132, v132, s28, v236
	v_sub_f32_e32 v133, v5, v133
	v_exp_f32_e32 v132, v132
	v_med3_f32 v133, v133, s28, v236
	v_cmp_gt_f32_e32 vcc, s33, v133
	v_mul_f32_e32 v124, v150, v124
	s_nop 1
	v_cndmask_b32_e32 v134, 0, v237, vcc
	v_add_f32_e32 v133, v133, v134
	v_exp_f32_e32 v133, v133
	v_cndmask_b32_e32 v134, 0, v238, vcc
	v_cvt_pk_bf16_f32 v164, v4, v124
	v_lshlrev_b32_e32 v100, 1, v24
	v_ldexp_f32 v134, v133, v134
	v_sub_f32_e32 v133, v135, v125
	v_med3_f32 v133, v133, s28, v236
	v_sub_f32_e32 v135, v125, v135
	v_med3_f32 v135, v135, s28, v236
	v_exp_f32_e32 v133, v133
	v_mov_b32_e32 v101, v3
	v_pk_mul_f32 v[132:133], v[44:45], v[132:133]
	v_exp_f32_e32 v135, v135
	v_cvt_pk_bf16_f32 v162, v132, v133
	v_add_f32_e32 v133, v158, v168
	v_sub_f32_e32 v132, v133, v5
	v_med3_f32 v132, v132, s28, v236
	v_pk_mul_f32 v[130:131], v[130:131], v[134:135]
	v_sub_f32_e32 v133, v5, v133
	v_exp_f32_e32 v132, v132
	v_med3_f32 v133, v133, s28, v236
	v_cvt_pk_bf16_f32 v160, v130, v131
	v_exp_f32_e32 v133, v133
	v_lshl_add_u64 v[120:121], v[94:95], 0, v[88:89]
	v_lshl_add_u64 v[126:127], v[94:95], 0, v[98:99]
	v_add_f32_e32 v134, v156, v170
	v_mul_f32_e32 v190, v152, v133
	v_sub_f32_e32 v133, v134, v125
	v_med3_f32 v133, v133, s28, v236
	v_sub_f32_e32 v134, v125, v134
	v_med3_f32 v134, v134, s28, v236
	v_exp_f32_e32 v133, v133
	v_lshl_add_u64 v[122:123], v[94:95], 0, v[100:101]
	v_pk_mul_f32 v[132:133], v[58:59], v[132:133]
	v_exp_f32_e32 v134, v134
	v_cvt_pk_bf16_f32 v158, v132, v133
	v_add_f32_e32 v133, v192, v168
	v_sub_f32_e32 v132, v133, v5
	v_med3_f32 v132, v132, s28, v236
	v_mul_f32_e32 v191, v148, v134
	v_sub_f32_e32 v133, v5, v133
	v_exp_f32_e32 v132, v132
	v_med3_f32 v133, v133, s28, v236
	v_cmp_gt_f32_e32 vcc, s33, v133
	v_add_f32_e32 v135, v165, v170
	s_nop 1
	v_cndmask_b32_e32 v134, 0, v237, vcc
	v_add_f32_e32 v133, v133, v134
	v_exp_f32_e32 v133, v133
	v_cndmask_b32_e32 v134, 0, v238, vcc
	v_cvt_pk_bf16_f32 v156, v190, v191
	v_ldexp_f32 v134, v133, v134
	v_sub_f32_e32 v133, v135, v125
	v_med3_f32 v133, v133, s28, v236
	s_nop 1
	v_exp_f32_e32 v133, v133
	s_nop 0
	v_pk_mul_f32 v[192:193], v[56:57], v[132:133]
	v_sub_f32_e32 v132, v125, v135
	v_med3_f32 v132, v132, s28, v236
	v_cmp_gt_f32_e32 vcc, s33, v132
	v_cvt_pk_bf16_f32 v154, v192, v193
	s_nop 0
	v_cndmask_b32_e32 v133, 0, v237, vcc
	v_add_f32_e32 v132, v132, v133
	v_exp_f32_e32 v132, v132
	v_cndmask_b32_e32 v133, 0, v238, vcc
	v_ldexp_f32 v135, v132, v133
	v_pk_mul_f32 v[132:133], v[138:139], v[134:135]
	v_add_f32_e32 v135, v163, v168
	v_sub_f32_e32 v134, v135, v5
	v_med3_f32 v134, v134, s28, v236
	v_sub_f32_e32 v135, v5, v135
	v_med3_f32 v135, v135, s28, v236
	v_exp_f32_e32 v134, v134
	v_cvt_pk_bf16_f32 v152, v132, v133
	v_exp_f32_e32 v135, v135
	s_nop 0
	v_mul_f32_e32 v192, v146, v135
	v_sub_f32_e32 v135, v111, v125
	v_med3_f32 v135, v135, s28, v236
	v_sub_f32_e32 v111, v125, v111
	v_med3_f32 v111, v111, s28, v236
	v_exp_f32_e32 v135, v135
	s_nop 0
	v_exp_f32_e32 v111, v111
	v_pk_mul_f32 v[134:135], v[54:55], v[134:135]
	v_mul_f32_e32 v193, v144, v111
	v_add_f32_e32 v111, v196, v168
	v_cvt_pk_bf16_f32 v150, v134, v135
	v_sub_f32_e32 v134, v111, v5
	v_med3_f32 v134, v134, s28, v236
	v_sub_f32_e32 v111, v5, v111
	v_med3_f32 v111, v111, s28, v236
	v_exp_f32_e32 v134, v134
	v_cmp_gt_f32_e32 vcc, s33, v111
	v_cvt_pk_bf16_f32 v148, v192, v193
	s_nop 1
	v_cndmask_b32_e32 v135, 0, v237, vcc
	v_add_f32_e32 v111, v111, v135
	v_exp_f32_e32 v111, v111
	v_cndmask_b32_e32 v135, 0, v238, vcc
	v_ldexp_f32 v138, v111, v135
	v_add_f32_e32 v111, v195, v170
	v_sub_f32_e32 v135, v111, v125
	v_med3_f32 v135, v135, s28, v236
	v_sub_f32_e32 v111, v125, v111
	v_med3_f32 v111, v111, s28, v236
	v_exp_f32_e32 v135, v135
	v_cmp_gt_f32_e32 vcc, s33, v111
	v_pk_mul_f32 v[196:197], v[52:53], v[134:135]
	s_nop 1
	v_cndmask_b32_e32 v134, 0, v237, vcc
	v_add_f32_e32 v111, v111, v134
	v_exp_f32_e32 v111, v111
	v_cndmask_b32_e32 v134, 0, v238, vcc
	v_cvt_pk_bf16_f32 v146, v196, v197
	v_ldexp_f32 v139, v111, v134
	v_add_f32_e32 v111, v194, v168
	v_pk_mul_f32 v[134:135], v[140:141], v[138:139]
	v_sub_f32_e32 v138, v111, v5
	v_med3_f32 v138, v138, s28, v236
	v_sub_f32_e32 v111, v5, v111
	v_med3_f32 v111, v111, s28, v236
	v_exp_f32_e32 v138, v138
	v_cvt_pk_bf16_f32 v144, v134, v135
	v_exp_f32_e32 v111, v111
	s_nop 0
	v_mul_f32_e32 v194, v142, v111
	v_add_f32_e32 v111, v167, v170
	v_sub_f32_e32 v139, v111, v125
	v_med3_f32 v139, v139, s28, v236
	v_sub_f32_e32 v111, v125, v111
	v_med3_f32 v111, v111, s28, v236
	v_exp_f32_e32 v139, v139
	s_nop 0
	v_exp_f32_e32 v111, v111
	v_pk_mul_f32 v[138:139], v[50:51], v[138:139]
	v_mul_f32_e32 v195, v107, v111
	v_add_f32_e32 v107, v173, v168
	v_sub_f32_e32 v111, v107, v5
	v_med3_f32 v111, v111, s28, v236
	v_cmp_gt_f32_e32 vcc, s33, v111
	v_cvt_pk_bf16_f32 v142, v138, v139
	v_sub_f32_e32 v107, v5, v107
	v_cndmask_b32_e32 v138, 0, v237, vcc
	v_add_f32_e32 v111, v111, v138
	v_exp_f32_e32 v111, v111
	v_med3_f32 v107, v107, s28, v236
	v_cndmask_b32_e32 v138, 0, v238, vcc
	v_cmp_gt_f32_e32 vcc, s33, v107
	v_ldexp_f32 v138, v111, v138
	v_cvt_pk_bf16_f32 v140, v194, v195
	v_cndmask_b32_e32 v111, 0, v237, vcc
	v_add_f32_e32 v107, v107, v111
	v_exp_f32_e32 v107, v107
	v_cndmask_b32_e32 v111, 0, v238, vcc
	v_ldexp_f32 v168, v107, v111
	v_add_f32_e32 v107, v175, v170
	v_sub_f32_e32 v111, v107, v125
	v_med3_f32 v111, v111, s28, v236
	v_cmp_gt_f32_e32 vcc, s33, v111
	v_sub_f32_e32 v107, v125, v107
	v_med3_f32 v107, v107, s28, v236
	v_cndmask_b32_e32 v139, 0, v237, vcc
	v_add_f32_e32 v111, v111, v139
	v_exp_f32_e32 v111, v111
	v_cndmask_b32_e32 v139, 0, v238, vcc
	v_cmp_gt_f32_e32 vcc, s33, v107
	v_ldexp_f32 v139, v111, v139
	s_nop 0
	v_cndmask_b32_e32 v111, 0, v237, vcc
	v_add_f32_e32 v107, v107, v111
	v_exp_f32_e32 v107, v107
	v_cndmask_b32_e32 v111, 0, v238, vcc
	v_pk_mul_f32 v[138:139], v[48:49], v[138:139]
	v_ldexp_f32 v169, v107, v111
	v_pk_mul_f32 v[136:137], v[136:137], v[168:169]
	v_pk_add_f32 v[168:169], v[102:103], 1.0 op_sel_hi:[1,0]
	s_nop 0
	v_rcp_f32_e32 v111, v169
	s_nop 0
	v_fma_f32 v141, -v169, v111, 1.0
	v_fmac_f32_e32 v111, v141, v111
	v_div_fixup_f32 v169, v111, v169, 1.0
	v_rcp_f32_e32 v111, v168
	s_mov_b64 s[26:27], 0x6000000
	v_fma_f32 v141, -v168, v111, 1.0
	v_fmac_f32_e32 v111, v141, v111
	v_div_fixup_f32 v168, v111, v168, 1.0
	v_pk_mul_f32 v[102:103], v[102:103], v[168:169]
	v_pk_mul_f32 v[168:169], v[116:117], v[168:169]
	v_pk_mul_f32 v[116:117], v[116:117], v[102:103]
	v_add_f32_e32 v6, v6, v168
	v_log_f32_e32 v6, v6
	v_add_f32_e32 v7, v7, v169
	v_log_f32_e32 v7, v7
	v_max_f32_e32 v6, 0xc2c80000, v6
	v_add_f32_e32 v196, v187, v6
	ds_bpermute_b32 v201, v13, v196
	ds_bpermute_b32 v202, v15, v196
	ds_bpermute_b32 v197, v9, v196
	v_max_f32_e32 v7, 0xc2c80000, v7
	v_add_f32_e32 v200, v184, v7
	ds_bpermute_b32 v205, v13, v200
	s_waitcnt lgkmcnt(2)
	v_cndmask_b32_e64 v6, v202, v201, s[4:5]
	s_waitcnt lgkmcnt(1)
	v_cndmask_b32_e64 v6, v6, v197, s[10:11]
	v_cndmask_b32_e64 v203, v6, v196, s[8:9]
	v_cndmask_b32_e64 v6, v202, v201, s[10:11]
	v_cndmask_b32_e64 v6, v6, v197, s[4:5]
	ds_bpermute_b32 v206, v15, v200
	v_cndmask_b32_e64 v169, v6, v196, s[6:7]
	v_cndmask_b32_e64 v6, v202, v201, s[8:9]
	ds_bpermute_b32 v204, v9, v200
	v_cndmask_b32_e64 v6, v6, v197, s[6:7]
	v_cndmask_b32_e64 v111, v6, v196, s[4:5]
	v_cndmask_b32_e64 v6, v6, 0, s[4:5]
	v_cndmask_b32_e64 v7, 0, v169, s[16:17]
	v_add_f32_e32 v6, v6, v7
	v_cndmask_b32_e64 v7, 0, v203, s[18:19]
	v_add_f32_e32 v168, v7, v6
	s_waitcnt lgkmcnt(1)
	v_cndmask_b32_e64 v6, v206, v205, s[4:5]
	s_waitcnt lgkmcnt(0)
	v_cndmask_b32_e64 v6, v6, v204, s[10:11]
	v_cndmask_b32_e64 v207, v6, v200, s[8:9]
	v_cndmask_b32_e64 v6, v206, v205, s[10:11]
	v_cndmask_b32_e64 v6, v6, v204, s[4:5]
	v_cndmask_b32_e64 v171, v6, v200, s[6:7]
	v_cndmask_b32_e64 v6, v206, v205, s[8:9]
	v_cndmask_b32_e64 v6, v6, v204, s[6:7]
	v_cndmask_b32_e64 v107, v6, v200, s[4:5]
	v_cndmask_b32_e64 v6, v6, 0, s[4:5]
	v_cndmask_b32_e64 v102, 0, v171, s[16:17]
	v_cndmask_b32_e64 v7, 0, v207, s[18:19]
	v_add_f32_e32 v6, v6, v102
	v_add_f32_e32 v170, v7, v6
	v_pk_add_f32 v[6:7], v[110:111], v[168:169]
	s_nop 0
	v_sub_f32_e32 v102, v6, v7
	v_med3_f32 v102, v102, s28, v236
	v_cmp_gt_f32_e32 vcc, s33, v102
	v_sub_f32_e32 v6, v7, v6
	v_med3_f32 v6, v6, s28, v236
	v_cndmask_b32_e32 v103, 0, v237, vcc
	v_add_f32_e32 v102, v102, v103
	v_exp_f32_e32 v102, v102
	v_cndmask_b32_e32 v103, 0, v238, vcc
	v_ldexp_f32 v110, v102, v103
	s_nop 0
	v_exp_f32_e32 v6, v6
	v_pk_add_f32 v[102:103], v[106:107], v[170:171]
	v_mul_f32_e32 v6, v151, v6
	v_sub_f32_e32 v106, v102, v103
	v_med3_f32 v106, v106, s28, v236
	v_cmp_gt_f32_e32 vcc, s33, v106
	v_sub_f32_e32 v102, v103, v102
	v_med3_f32 v102, v102, s28, v236
	v_cndmask_b32_e32 v107, 0, v237, vcc
	v_add_f32_e32 v106, v106, v107
	v_exp_f32_e32 v106, v106
	v_cndmask_b32_e32 v107, 0, v238, vcc
	v_ldexp_f32 v111, v106, v107
	v_pk_mul_f32 v[106:107], v[30:31], v[110:111]
	v_exp_f32_e32 v102, v102
	v_cvt_pk_bf16_f32 v167, v106, v107
	v_add_f32_e32 v107, v157, v170
	v_mul_f32_e32 v102, v147, v102
	v_cvt_pk_bf16_f32 v165, v6, v102
	global_store_dwordx2 v[96:97], v[164:165], off
	v_add_f32_e32 v97, v159, v168
	v_sub_f32_e32 v96, v97, v7
	v_med3_f32 v96, v96, s28, v236
	v_sub_f32_e32 v97, v7, v97
	v_med3_f32 v97, v97, s28, v236
	v_exp_f32_e32 v96, v96
	v_cmp_gt_f32_e32 vcc, s33, v97
	global_store_dwordx2 v[92:93], v[166:167], off
	s_nop 1
	v_cndmask_b32_e32 v106, 0, v237, vcc
	v_add_f32_e32 v97, v97, v106
	v_exp_f32_e32 v97, v97
	v_cndmask_b32_e32 v106, 0, v238, vcc
	v_ldexp_f32 v106, v97, v106
	v_sub_f32_e32 v97, v107, v103
	v_med3_f32 v97, v97, s28, v236
	s_nop 1
	v_exp_f32_e32 v97, v97
	s_nop 0
	v_pk_mul_f32 v[110:111], v[28:29], v[96:97]
	v_sub_f32_e32 v96, v103, v107
	v_med3_f32 v96, v96, s28, v236
	v_cmp_gt_f32_e32 vcc, s33, v96
	v_cvt_pk_bf16_f32 v163, v110, v111
	global_store_dwordx2 v[92:93], v[162:163], off offset:256
	v_cndmask_b32_e32 v97, 0, v237, vcc
	v_add_f32_e32 v96, v96, v97
	v_exp_f32_e32 v96, v96
	v_cndmask_b32_e32 v97, 0, v238, vcc
	v_ldexp_f32 v107, v96, v97
	v_pk_mul_f32 v[96:97], v[104:105], v[106:107]
	v_add_f32_e32 v105, v155, v168
	v_sub_f32_e32 v104, v105, v7
	v_med3_f32 v104, v104, s28, v236
	v_sub_f32_e32 v105, v7, v105
	v_med3_f32 v105, v105, s28, v236
	v_exp_f32_e32 v104, v104
	v_cvt_pk_bf16_f32 v161, v96, v97
	v_exp_f32_e32 v105, v105
	global_store_dwordx2 v[112:113], v[160:161], off
	v_add_f32_e32 v106, v153, v170
	v_mul_f32_e32 v160, v149, v105
	v_sub_f32_e32 v105, v106, v103
	v_med3_f32 v105, v105, s28, v236
	v_sub_f32_e32 v106, v103, v106
	v_med3_f32 v106, v106, s28, v236
	v_exp_f32_e32 v105, v105
	s_nop 0
	v_pk_mul_f32 v[104:105], v[42:43], v[104:105]
	v_exp_f32_e32 v106, v106
	v_cvt_pk_bf16_f32 v159, v104, v105
	v_add_f32_e32 v105, v186, v168
	v_sub_f32_e32 v104, v105, v7
	v_med3_f32 v104, v104, s28, v236
	v_mul_f32_e32 v161, v145, v106
	v_sub_f32_e32 v105, v7, v105
	v_exp_f32_e32 v104, v104
	v_med3_f32 v105, v105, s28, v236
	v_cmp_gt_f32_e32 vcc, s33, v105
	v_add_f32_e32 v107, v183, v170
	s_nop 1
	v_cndmask_b32_e32 v106, 0, v237, vcc
	v_add_f32_e32 v105, v105, v106
	v_exp_f32_e32 v105, v105
	v_cndmask_b32_e32 v106, 0, v238, vcc
	v_cvt_pk_bf16_f32 v157, v160, v161
	global_store_dwordx2 v[108:109], v[156:157], off
	v_ldexp_f32 v106, v105, v106
	v_sub_f32_e32 v105, v107, v103
	v_med3_f32 v105, v105, s28, v236
	global_store_dwordx2 v[92:93], v[158:159], off offset:512
	s_nop 0
	v_exp_f32_e32 v105, v105
	s_nop 0
	v_pk_mul_f32 v[108:109], v[40:41], v[104:105]
	v_sub_f32_e32 v104, v103, v107
	v_med3_f32 v104, v104, s28, v236
	v_cmp_gt_f32_e32 vcc, s33, v104
	v_cvt_pk_bf16_f32 v155, v108, v109
	global_store_dwordx2 v[92:93], v[154:155], off offset:768
	v_cndmask_b32_e32 v105, 0, v237, vcc
	v_add_f32_e32 v104, v104, v105
	v_exp_f32_e32 v104, v104
	v_cndmask_b32_e32 v105, 0, v238, vcc
	v_ldexp_f32 v107, v104, v105
	v_pk_mul_f32 v[104:105], v[118:119], v[106:107]
	v_add_f32_e32 v107, v178, v168
	v_sub_f32_e32 v106, v107, v7
	v_med3_f32 v106, v106, s28, v236
	v_sub_f32_e32 v107, v7, v107
	v_med3_f32 v107, v107, s28, v236
	v_exp_f32_e32 v106, v106
	v_cvt_pk_bf16_f32 v153, v104, v105
	v_exp_f32_e32 v107, v107
	v_cvt_pk_bf16_f32 v105, v161, v105
	global_store_dwordx2 v[120:121], v[152:153], off
	v_add_f32_e32 v108, v172, v170
	v_mul_f32_e32 v118, v143, v107
	v_sub_f32_e32 v107, v108, v103
	v_med3_f32 v107, v107, s28, v236
	v_sub_f32_e32 v108, v103, v108
	v_med3_f32 v108, v108, s28, v236
	v_exp_f32_e32 v107, v107
	s_nop 0
	v_pk_mul_f32 v[106:107], v[38:39], v[106:107]
	v_exp_f32_e32 v108, v108
	v_cvt_pk_bf16_f32 v151, v106, v107
	v_add_f32_e32 v107, v189, v168
	v_sub_f32_e32 v106, v107, v7
	v_med3_f32 v106, v106, s28, v236
	v_mul_f32_e32 v27, v27, v108
	v_sub_f32_e32 v107, v7, v107
	v_exp_f32_e32 v106, v106
	v_med3_f32 v107, v107, s28, v236
	v_cmp_gt_f32_e32 vcc, s33, v107
	v_add_f32_e32 v109, v188, v170
	s_nop 1
	v_cndmask_b32_e32 v108, 0, v237, vcc
	v_add_f32_e32 v107, v107, v108
	v_exp_f32_e32 v107, v107
	v_cndmask_b32_e32 v108, 0, v238, vcc
	global_store_dwordx2 v[92:93], v[150:151], off offset:1024
	v_cvt_pk_bf16_f32 v149, v118, v27
	v_ldexp_f32 v108, v107, v108
	v_sub_f32_e32 v107, v109, v103
	v_med3_f32 v107, v107, s28, v236
	v_sub_f32_e32 v109, v103, v109
	v_med3_f32 v109, v109, s28, v236
	v_exp_f32_e32 v107, v107
	global_store_dwordx2 v[114:115], v[148:149], off
	v_pk_mul_f32 v[106:107], v[36:37], v[106:107]
	v_exp_f32_e32 v109, v109
	v_cvt_pk_bf16_f32 v147, v106, v107
	v_add_f32_e32 v107, v187, v168
	v_sub_f32_e32 v106, v107, v7
	v_med3_f32 v106, v106, s28, v236
	v_pk_mul_f32 v[110:111], v[128:129], v[108:109]
	v_sub_f32_e32 v107, v7, v107
	v_exp_f32_e32 v106, v106
	v_med3_f32 v107, v107, s28, v236
	global_store_dwordx2 v[92:93], v[146:147], off offset:1280
	v_exp_f32_e32 v107, v107
	v_lshl_add_u64 v[114:115], v[60:61], 0, s[26:27]
	v_lshl_add_u64 v[72:73], v[114:115], 0, v[72:73]
	v_add_f32_e32 v108, v184, v170
	v_mul_f32_e32 v25, v25, v107
	v_sub_f32_e32 v107, v108, v103
	v_med3_f32 v107, v107, s28, v236
	v_sub_f32_e32 v108, v103, v108
	v_med3_f32 v108, v108, s28, v236
	v_exp_f32_e32 v107, v107
	v_cvt_pk_bf16_f32 v145, v110, v111
	v_pk_mul_f32 v[106:107], v[34:35], v[106:107]
	v_exp_f32_e32 v108, v108
	v_cvt_pk_bf16_f32 v143, v106, v107
	v_add_f32_e32 v107, v196, v168
	v_sub_f32_e32 v106, v107, v7
	v_med3_f32 v106, v106, s28, v236
	v_mul_f32_e32 v23, v23, v108
	v_sub_f32_e32 v107, v7, v107
	v_exp_f32_e32 v106, v106
	v_med3_f32 v107, v107, s28, v236
	v_cmp_gt_f32_e32 vcc, s33, v107
	v_add_f32_e32 v109, v200, v170
	s_nop 1
	v_cndmask_b32_e32 v108, 0, v237, vcc
	v_add_f32_e32 v107, v107, v108
	v_exp_f32_e32 v107, v107
	v_cndmask_b32_e32 v108, 0, v238, vcc
	global_store_dwordx2 v[92:93], v[142:143], off offset:1536
	v_cvt_pk_bf16_f32 v141, v25, v23
	v_ldexp_f32 v108, v107, v108
	v_sub_f32_e32 v107, v109, v103
	v_med3_f32 v107, v107, s28, v236
	v_sub_f32_e32 v109, v103, v109
	v_med3_f32 v109, v109, s28, v236
	v_exp_f32_e32 v107, v107
	global_store_dwordx2 v[126:127], v[144:145], off
	v_exp_f32_e32 v109, v109
	v_pk_mul_f32 v[106:107], v[32:33], v[106:107]
	global_store_dwordx2 v[122:123], v[140:141], off
	v_pk_mul_f32 v[112:113], v[116:117], v[108:109]
	v_cvt_pk_bf16_f32 v108, v138, v139
	v_cvt_pk_bf16_f32 v109, v106, v107
	global_store_dwordx2 v[92:93], v[108:109], off offset:1792
	v_lshlrev_b32_e32 v92, 1, v26
	v_mov_b32_e32 v93, v3
	v_cvt_pk_bf16_f32 v106, v136, v137
	v_cvt_pk_bf16_f32 v107, v112, v113
	v_lshl_add_u64 v[94:95], v[94:95], 0, v[92:93]
	global_store_dwordx2 v[94:95], v[106:107], off
	v_cvt_pk_bf16_f32 v106, v4, v130
	v_cvt_pk_bf16_f32 v107, v190, v132
	v_cvt_pk_bf16_f32 v108, v192, v134
	v_cvt_pk_bf16_f32 v109, v194, v136
	v_or_b32_e32 v4, 32, v19
	global_store_dwordx4 v[72:73], v[106:109], off
	v_lshlrev_b32_e32 v72, 1, v4
	v_mov_b32_e32 v73, v3
	v_cvt_pk_bf16_f32 v106, v124, v131
	v_cvt_pk_bf16_f32 v107, v191, v133
	v_cvt_pk_bf16_f32 v108, v193, v135
	v_cvt_pk_bf16_f32 v109, v195, v137
	v_lshl_add_u64 v[94:95], v[114:115], 0, v[72:73]
	v_or_b32_e32 v4, 64, v19
	global_store_dwordx4 v[94:95], v[106:109], off
	v_lshlrev_b32_e32 v94, 1, v4
	v_mov_b32_e32 v95, v3
	v_or_b32_e32 v4, 0x60, v19
	v_cvt_pk_bf16_f32 v106, v6, v96
	v_cvt_pk_bf16_f32 v107, v160, v104
	v_cvt_pk_bf16_f32 v108, v118, v110
	v_cvt_pk_bf16_f32 v109, v25, v112
	v_lshl_add_u64 v[116:117], v[114:115], 0, v[94:95]
	v_cvt_pk_bf16_f32 v104, v102, v97
	v_lshlrev_b32_e32 v96, 1, v4
	v_mov_b32_e32 v97, v3
	global_store_dwordx4 v[116:117], v[106:109], off
	s_nop 1
	v_cvt_pk_bf16_f32 v106, v27, v111
	v_cvt_pk_bf16_f32 v107, v23, v113
	v_lshl_add_u64 v[108:109], v[114:115], 0, v[96:97]
	global_store_dwordx4 v[108:109], v[104:107], off
	s_and_saveexec_b64 s[26:27], s[4:5]
	s_cbranch_execz .LBB0_177
	v_cndmask_b32_e64 v6, v202, v201, s[6:7]
	v_cndmask_b32_e64 v6, v6, v197, s[8:9]
	v_cndmask_b32_e64 v6, v6, v196, s[10:11]
	v_add_f32_e32 v23, v203, v7
	v_add_f32_e32 v23, v6, v23
	v_cndmask_b32_e64 v6, v182, v181, s[6:7]
	v_cndmask_b32_e64 v6, v6, v180, s[8:9]
	v_cndmask_b32_e64 v6, v6, v175, s[10:11]
	v_add_f32_e32 v25, v185, v125
	v_add_f32_e32 v6, v6, v25
	v_cndmask_b32_e64 v25, v177, v176, s[6:7]
	v_cndmask_b32_e64 v25, v25, v174, s[8:9]
	v_cndmask_b32_e64 v4, v206, v205, s[6:7]
	v_cndmask_b32_e64 v25, v25, v173, s[10:11]
	v_add_f32_e32 v27, v179, v5
	v_cmp_gt_f32_e32 vcc, s33, v5
	v_cndmask_b32_e64 v4, v4, v204, s[8:9]
	v_add_f32_e32 v25, v25, v27
	v_cndmask_b32_e32 v102, 0, v237, vcc
	v_cndmask_b32_e64 v4, v4, v200, s[10:11]
	v_add_f32_e32 v27, v207, v103
	v_add_f32_e32 v102, v5, v102
	v_sub_f32_e32 v5, v25, v5
	v_add_f32_e32 v27, v4, v27
	v_cndmask_b32_e32 v4, 0, v238, vcc
	v_cmp_gt_f32_e32 vcc, s33, v5
	v_sub_f32_e32 v6, v6, v125
	v_exp_f32_e32 v102, v102
	v_cndmask_b32_e32 v25, 0, v237, vcc
	v_add_f32_e32 v5, v5, v25
	v_exp_f32_e32 v5, v5
	v_cndmask_b32_e32 v25, 0, v238, vcc
	v_cmp_gt_f32_e32 vcc, s33, v125
	v_ldexp_f32 v4, v102, v4
	v_ldexp_f32 v104, v5, v25
	v_cndmask_b32_e32 v25, 0, v237, vcc
	v_add_f32_e32 v25, v125, v25
	v_exp_f32_e32 v25, v25
	v_cndmask_b32_e32 v5, 0, v238, vcc
	v_cmp_gt_f32_e32 vcc, s33, v6
	v_ldexp_f32 v5, v25, v5
	s_nop 0
	v_cndmask_b32_e32 v25, 0, v237, vcc
	v_add_f32_e32 v6, v6, v25
	v_exp_f32_e32 v6, v6
	v_cndmask_b32_e32 v25, 0, v238, vcc
	v_cmp_gt_f32_e32 vcc, s33, v7
	v_ldexp_f32 v105, v6, v25
	s_nop 0
	v_cndmask_b32_e32 v25, 0, v237, vcc
	v_add_f32_e32 v25, v7, v25
	v_sub_f32_e32 v7, v23, v7
	v_cndmask_b32_e32 v6, 0, v238, vcc
	v_cmp_gt_f32_e32 vcc, s33, v7
	v_exp_f32_e32 v25, v25
	s_nop 0
	v_cndmask_b32_e32 v23, 0, v237, vcc
	v_add_f32_e32 v7, v7, v23
	v_exp_f32_e32 v7, v7
	v_cndmask_b32_e32 v23, 0, v238, vcc
	v_cmp_gt_f32_e32 vcc, s33, v103
	v_ldexp_f32 v6, v25, v6
	v_ldexp_f32 v106, v7, v23
	v_cndmask_b32_e32 v23, 0, v237, vcc
	v_add_f32_e32 v23, v103, v23
	v_exp_f32_e32 v23, v23
	v_cndmask_b32_e32 v7, 0, v238, vcc
	v_ldexp_f32 v7, v23, v7
	global_store_dwordx4 v21, v[4:7], s[24:25]
	s_nop 1
	v_sub_f32_e32 v4, v27, v103
	v_cmp_gt_f32_e32 vcc, s33, v4
	s_nop 1
	v_cndmask_b32_e32 v5, 0, v237, vcc
	v_add_f32_e32 v4, v4, v5
	v_exp_f32_e32 v4, v4
	v_cndmask_b32_e32 v5, 0, v238, vcc
	v_ldexp_f32 v107, v4, v5
	global_store_dwordx4 v21, v[104:107], s[24:25] offset:512
.LBB0_177:
	s_or_b64 exec, exec, s[26:27]
	v_add_co_u32_e32 v4, vcc, 0x4000, v74
	global_load_dwordx2 v[62:63], v[62:63], off offset:1536
	s_nop 0
	v_addc_co_u32_e32 v5, vcc, 0, v75, vcc
	v_add_co_u32_e32 v68, vcc, 0x2000, v68
	global_load_dwordx2 v[66:67], v[66:67], off offset:512
	s_nop 0
	v_addc_co_u32_e32 v69, vcc, 0, v69, vcc
	global_load_dwordx2 v[68:69], v[68:69], off
	s_waitcnt vmcnt(0)
	v_lshlrev_b32_e32 v23, 16, v68
	global_load_dwordx2 v[64:65], v[64:65], off offset:1024
	v_mul_f32_e32 v23, 0xbfb8aa3b, v23
	v_exp_f32_e32 v23, v23
	v_and_b32_e32 v25, 0xffff0000, v68
	v_lshlrev_b32_e32 v27, 16, v69
	v_and_b32_e32 v68, 0xffff0000, v69
	v_add_f32_e32 v69, 1.0, v23
	v_rcp_f32_e32 v75, v69
	global_load_dwordx4 v[4:7], v[4:5], off
	v_fma_f32 v102, -v69, v75, 1.0
	v_fmac_f32_e32 v75, v102, v75
	v_div_fixup_f32 v106, v75, v69, 1.0
	v_mul_f32_e32 v105, v23, v106
	v_mul_f32_e32 v23, 0xbfb8aa3b, v25
	v_exp_f32_e32 v23, v23
	s_nop 0
	v_add_f32_e32 v25, 1.0, v23
	v_rcp_f32_e32 v74, v25
	s_nop 0
	v_fma_f32 v75, -v25, v74, 1.0
	v_fmac_f32_e32 v74, v75, v74
	v_div_fixup_f32 v108, v74, v25, 1.0
	v_mul_f32_e32 v107, v23, v108
	v_mul_f32_e32 v23, 0xbfb8aa3b, v27
	v_exp_f32_e32 v23, v23
	s_nop 0
	v_add_f32_e32 v25, 1.0, v23
	v_rcp_f32_e32 v69, v25
	s_nop 0
	v_fma_f32 v74, -v25, v69, 1.0
	v_fmac_f32_e32 v69, v74, v69
	v_div_fixup_f32 v27, v69, v25, 1.0
	v_mul_f32_e32 v25, 0xbfb8aa3b, v68
	v_exp_f32_e32 v25, v25
	v_mul_f32_e32 v23, v23, v27
	v_add_f32_e32 v68, 1.0, v25
	v_rcp_f32_e32 v74, v68
	s_nop 0
	v_fma_f32 v75, -v68, v74, 1.0
	v_fmac_f32_e32 v74, v75, v74
	v_div_fixup_f32 v104, v74, v68, 1.0
	v_lshlrev_b32_e32 v68, 16, v66
	v_and_b32_e32 v66, 0xffff0000, v66
	v_lshlrev_b32_e32 v74, 16, v67
	v_mul_f32_e32 v66, 0xbfb8aa3b, v66
	v_exp_f32_e32 v69, v66
	v_mul_f32_e32 v66, 0xbfb8aa3b, v74
	s_waitcnt vmcnt(1)
	v_lshlrev_b32_e32 v74, 16, v64
	v_mul_f32_e32 v74, 0xbfb8aa3b, v74
	v_exp_f32_e32 v74, v74
	v_and_b32_e32 v64, 0xffff0000, v64
	v_mul_f32_e32 v64, 0xbfb8aa3b, v64
	v_exp_f32_e32 v64, v64
	v_add_f32_e32 v102, 1.0, v74
	v_rcp_f32_e32 v109, v102
	v_lshlrev_b32_e32 v75, 16, v65
	v_and_b32_e32 v65, 0xffff0000, v65
	v_mul_f32_e32 v68, 0xbfb8aa3b, v68
	v_fma_f32 v110, -v102, v109, 1.0
	v_fmac_f32_e32 v109, v110, v109
	v_div_fixup_f32 v116, v109, v102, 1.0
	v_mul_f32_e32 v109, v74, v116
	v_add_f32_e32 v74, 1.0, v64
	v_rcp_f32_e32 v103, v74
	v_exp_f32_e32 v68, v68
	v_and_b32_e32 v67, 0xffff0000, v67
	v_mul_f32_e32 v67, 0xbfb8aa3b, v67
	v_fma_f32 v110, -v74, v103, 1.0
	v_fmac_f32_e32 v103, v110, v103
	v_div_fixup_f32 v115, v103, v74, 1.0
	v_mul_f32_e32 v114, v64, v115
	v_mul_f32_e32 v64, 0xbfb8aa3b, v75
	v_exp_f32_e32 v64, v64
	v_exp_f32_e32 v66, v66
	v_exp_f32_e32 v67, v67
	v_mul_f32_e32 v25, v25, v104
	v_add_f32_e32 v74, 1.0, v64
	v_rcp_f32_e32 v102, v74
	s_nop 0
	v_fma_f32 v103, -v74, v102, 1.0
	v_fmac_f32_e32 v102, v103, v102
	v_div_fixup_f32 v112, v102, v74, 1.0
	v_mul_f32_e32 v111, v64, v112
	v_mul_f32_e32 v64, 0xbfb8aa3b, v65
	v_exp_f32_e32 v64, v64
	s_nop 0
	v_add_f32_e32 v65, 1.0, v64
	v_rcp_f32_e32 v75, v65
	s_nop 0
	v_fma_f32 v102, -v65, v75, 1.0
	v_fmac_f32_e32 v75, v102, v75
	v_div_fixup_f32 v113, v75, v65, 1.0
	v_mul_f32_e32 v110, v64, v113
	v_lshlrev_b32_e32 v64, 16, v62
	v_and_b32_e32 v62, 0xffff0000, v62
	v_lshlrev_b32_e32 v74, 16, v63
	v_mul_f32_e32 v62, 0xbfb8aa3b, v62
	v_exp_f32_e32 v65, v62
	v_mul_f32_e32 v62, 0xbfb8aa3b, v74
	global_load_dwordx2 v[74:75], v[76:77], off offset:2048
	v_mul_f32_e32 v64, 0xbfb8aa3b, v64
	v_exp_f32_e32 v64, v64
	v_and_b32_e32 v63, 0xffff0000, v63
	v_mul_f32_e32 v63, 0xbfb8aa3b, v63
	v_exp_f32_e32 v62, v62
	v_exp_f32_e32 v63, v63
	s_waitcnt vmcnt(0)
	v_lshlrev_b32_e32 v76, 16, v74
	v_mul_f32_e32 v76, 0xbfb8aa3b, v76
	v_exp_f32_e32 v76, v76
	v_and_b32_e32 v74, 0xffff0000, v74
	v_mul_f32_e32 v74, 0xbfb8aa3b, v74
	v_exp_f32_e32 v74, v74
	v_add_f32_e32 v102, 1.0, v76
	v_rcp_f32_e32 v117, v102
	v_lshlrev_b32_e32 v77, 16, v75
	v_and_b32_e32 v75, 0xffff0000, v75
	v_fma_f32 v118, -v102, v117, 1.0
	v_fmac_f32_e32 v117, v118, v117
	v_div_fixup_f32 v130, v117, v102, 1.0
	v_mul_f32_e32 v121, v76, v130
	v_add_f32_e32 v76, 1.0, v74
	v_rcp_f32_e32 v103, v76
	s_nop 0
	v_fma_f32 v117, -v76, v103, 1.0
	v_fmac_f32_e32 v103, v117, v103
	v_div_fixup_f32 v129, v103, v76, 1.0
	v_mul_f32_e32 v128, v74, v129
	v_mul_f32_e32 v74, 0xbfb8aa3b, v77
	v_exp_f32_e32 v74, v74
	s_nop 0
	v_add_f32_e32 v76, 1.0, v74
	v_rcp_f32_e32 v102, v76
	s_nop 0
	v_fma_f32 v103, -v76, v102, 1.0
	v_fmac_f32_e32 v102, v103, v102
	v_div_fixup_f32 v119, v102, v76, 1.0
	v_mul_f32_e32 v118, v74, v119
	v_mul_f32_e32 v74, 0xbfb8aa3b, v75
	v_exp_f32_e32 v74, v74
	s_nop 0
	v_add_f32_e32 v75, 1.0, v74
	v_rcp_f32_e32 v77, v75
	s_nop 0
	v_fma_f32 v102, -v75, v77, 1.0
	v_fmac_f32_e32 v77, v102, v77
	v_div_fixup_f32 v120, v77, v75, 1.0
	v_mul_f32_e32 v117, v74, v120
	global_load_dwordx2 v[74:75], v[82:83], off offset:2560
	s_waitcnt vmcnt(0)
	v_lshlrev_b32_e32 v76, 16, v74
	v_and_b32_e32 v74, 0xffff0000, v74
	v_lshlrev_b32_e32 v77, 16, v75
	v_mul_f32_e32 v74, 0xbfb8aa3b, v74
	v_and_b32_e32 v75, 0xffff0000, v75
	v_exp_f32_e32 v103, v74
	v_mul_f32_e32 v74, 0xbfb8aa3b, v77
	v_exp_f32_e32 v82, v74
	v_mul_f32_e32 v74, 0xbfb8aa3b, v75
	v_exp_f32_e32 v83, v74
	global_load_dwordx2 v[74:75], v[80:81], off offset:3072
	v_mul_f32_e32 v76, 0xbfb8aa3b, v76
	v_exp_f32_e32 v102, v76
	s_waitcnt vmcnt(0)
	v_lshlrev_b32_e32 v76, 16, v74
	v_mul_f32_e32 v76, 0xbfb8aa3b, v76
	v_exp_f32_e32 v76, v76
	v_and_b32_e32 v74, 0xffff0000, v74
	v_mul_f32_e32 v74, 0xbfb8aa3b, v74
	v_exp_f32_e32 v74, v74
	v_add_f32_e32 v80, 1.0, v76
	v_rcp_f32_e32 v122, v80
	v_lshlrev_b32_e32 v77, 16, v75
	v_and_b32_e32 v75, 0xffff0000, v75
	v_fma_f32 v123, -v80, v122, 1.0
	v_fmac_f32_e32 v122, v123, v122
	v_div_fixup_f32 v137, v122, v80, 1.0
	v_mul_f32_e32 v131, v76, v137
	v_add_f32_e32 v76, 1.0, v74
	v_rcp_f32_e32 v81, v76
	s_nop 0
	v_fma_f32 v122, -v76, v81, 1.0
	v_fmac_f32_e32 v81, v122, v81
	v_div_fixup_f32 v135, v81, v76, 1.0
	v_mul_f32_e32 v133, v74, v135
	v_mul_f32_e32 v74, 0xbfb8aa3b, v77
	v_exp_f32_e32 v74, v74
	v_pk_add_f32 v[124:125], v[4:5], 1.0 op_sel_hi:[1,0] neg_lo:[1,0] neg_hi:[1,0]
	v_add_f32_e32 v76, 1.0, v74
	v_rcp_f32_e32 v80, v76
	v_mul_f32_e32 v140, v125, v107
	v_mul_f32_e32 v142, v124, v105
	v_mul_f32_e32 v160, v124, v109
	v_fma_f32 v81, -v76, v80, 1.0
	v_fmac_f32_e32 v80, v81, v80
	v_div_fixup_f32 v136, v80, v76, 1.0
	v_mul_f32_e32 v134, v74, v136
	v_mul_f32_e32 v74, 0xbfb8aa3b, v75
	v_exp_f32_e32 v74, v74
	v_mul_f32_e32 v148, v125, v133
	v_mul_f32_e32 v149, v124, v131
	v_mul_f32_e32 v162, v125, v114
	v_add_f32_e32 v75, 1.0, v74
	v_rcp_f32_e32 v77, v75
	s_mov_b64 s[26:27], 0x9000000
	v_mul_f32_e32 v159, v125, v128
	v_mul_f32_e32 v161, v124, v121
	v_fma_f32 v80, -v75, v77, 1.0
	v_fmac_f32_e32 v77, v80, v77
	v_div_fixup_f32 v138, v77, v75, 1.0
	v_mul_f32_e32 v132, v74, v138
	global_load_dwordx2 v[74:75], v[78:79], off offset:3584
	s_waitcnt vmcnt(0)
	v_lshlrev_b32_e32 v76, 16, v74
	v_and_b32_e32 v74, 0xffff0000, v74
	v_lshlrev_b32_e32 v77, 16, v75
	v_mul_f32_e32 v74, 0xbfb8aa3b, v74
	v_and_b32_e32 v75, 0xffff0000, v75
	v_exp_f32_e32 v127, v74
	v_mul_f32_e32 v74, 0xbfb8aa3b, v77
	v_exp_f32_e32 v80, v74
	v_mul_f32_e32 v74, 0xbfb8aa3b, v75
	v_exp_f32_e32 v81, v74
	v_lshl_add_u64 v[74:75], v[70:71], 0, s[26:27]
	s_mov_b64 s[26:27], 0xc000000
	v_mul_f32_e32 v76, 0xbfb8aa3b, v76
	v_lshl_add_u64 v[70:71], v[70:71], 0, s[26:27]
	v_exp_f32_e32 v126, v76
	v_lshl_add_u64 v[78:79], v[74:75], 0, v[2:3]
	v_lshl_add_u64 v[76:77], v[70:71], 0, v[2:3]
	v_fma_f32 v2, v124, v106, v4
	v_log_f32_e32 v2, v2
	v_pk_add_f32 v[106:107], v[68:69], 1.0 op_sel_hi:[1,0]
	v_max_f32_e32 v152, 0xc2c80000, v2
	v_fma_f32 v2, v125, v108, v5
	v_log_f32_e32 v2, v2
	s_nop 0
	v_max_f32_e32 v153, 0xc2c80000, v2
	v_rcp_f32_e32 v105, v107
	s_nop 0
	v_fma_f32 v108, -v107, v105, 1.0
	v_fmac_f32_e32 v105, v108, v105
	v_div_fixup_f32 v107, v105, v107, 1.0
	v_rcp_f32_e32 v105, v106
	s_nop 0
	v_fma_f32 v108, -v106, v105, 1.0
	v_fmac_f32_e32 v105, v108, v105
	v_div_fixup_f32 v106, v105, v106, 1.0
	v_pk_mul_f32 v[122:123], v[124:125], v[106:107]
	v_pk_add_f32 v[108:109], v[6:7], 1.0 op_sel_hi:[1,0] neg_lo:[1,0] neg_hi:[1,0]
	v_add_f32_e32 v2, v4, v122
	v_log_f32_e32 v2, v2
	v_pk_mul_f32 v[68:69], v[68:69], v[106:107]
	v_mul_f32_e32 v133, v109, v25
	v_lshl_add_u64 v[106:107], v[74:75], 0, v[84:85]
	v_max_f32_e32 v165, 0xc2c80000, v2
	v_add_f32_e32 v2, v5, v123
	v_log_f32_e32 v2, v2
	v_pk_mul_f32 v[122:123], v[124:125], v[68:69]
	v_pk_add_f32 v[68:69], v[66:67], 1.0 op_sel_hi:[1,0]
	v_mul_f32_e32 v131, v109, v110
	v_max_f32_e32 v166, 0xc2c80000, v2
	v_fma_f32 v2, v124, v116, v4
	v_log_f32_e32 v2, v2
	s_nop 0
	v_max_f32_e32 v169, 0xc2c80000, v2
	v_fma_f32 v2, v125, v115, v5
	v_log_f32_e32 v2, v2
	s_nop 0
	v_max_f32_e32 v170, 0xc2c80000, v2
	v_fma_f32 v2, v124, v130, v4
	v_log_f32_e32 v2, v2
	s_nop 0
	v_max_f32_e32 v130, 0xc2c80000, v2
	v_fma_f32 v2, v125, v129, v5
	v_log_f32_e32 v2, v2
	s_nop 0
	v_max_f32_e32 v171, 0xc2c80000, v2
	v_fma_f32 v2, v124, v137, v4
	v_log_f32_e32 v2, v2
	v_mul_f32_e32 v137, v108, v23
	v_max_f32_e32 v172, 0xc2c80000, v2
	v_fma_f32 v2, v125, v135, v5
	v_log_f32_e32 v2, v2
	v_mul_f32_e32 v135, v108, v111
	v_max_f32_e32 v173, 0xc2c80000, v2
	v_fma_f32 v2, v108, v27, v6
	v_log_f32_e32 v2, v2
	s_nop 0
	v_max_f32_e32 v139, 0xc2c80000, v2
	v_fma_f32 v2, v109, v104, v7
	v_log_f32_e32 v2, v2
	s_nop 0
	v_max_f32_e32 v141, 0xc2c80000, v2
	v_rcp_f32_e32 v23, v69
	s_nop 0
	v_fma_f32 v25, -v69, v23, 1.0
	v_fmac_f32_e32 v23, v25, v23
	v_div_fixup_f32 v69, v23, v69, 1.0
	v_rcp_f32_e32 v23, v68
	s_nop 0
	v_fma_f32 v25, -v68, v23, 1.0
	v_fmac_f32_e32 v23, v25, v23
	v_div_fixup_f32 v68, v23, v68, 1.0
	v_pk_mul_f32 v[104:105], v[108:109], v[68:69]
	v_pk_mul_f32 v[66:67], v[66:67], v[68:69]
	v_add_f32_e32 v2, v6, v104
	v_log_f32_e32 v2, v2
	v_lshl_add_u64 v[68:69], v[70:71], 0, v[86:87]
	v_mul_f32_e32 v23, v108, v134
	v_mul_f32_e32 v27, v108, v118
	v_max_f32_e32 v143, 0xc2c80000, v2
	v_add_f32_e32 v2, v7, v105
	v_log_f32_e32 v2, v2
	v_lshl_add_u64 v[104:105], v[70:71], 0, v[84:85]
	v_lshl_add_u64 v[84:85], v[74:75], 0, v[86:87]
	v_pk_add_f32 v[86:87], v[64:65], 1.0 op_sel_hi:[1,0]
	v_max_f32_e32 v150, 0xc2c80000, v2
	v_div_scale_f32 v110, s[26:27], v87, v87, 1.0
	v_fma_f32 v2, v108, v112, v6
	v_rcp_f32_e32 v111, v110
	v_log_f32_e32 v2, v2
	v_mul_f32_e32 v25, v109, v117
	v_pk_mul_f32 v[66:67], v[108:109], v[66:67]
	v_fma_f32 v112, -v110, v111, 1.0
	v_max_f32_e32 v151, 0xc2c80000, v2
	v_fma_f32 v2, v109, v113, v7
	v_fmac_f32_e32 v111, v112, v111
	v_div_scale_f32 v112, vcc, 1.0, v87, 1.0
	v_log_f32_e32 v2, v2
	v_mul_f32_e32 v113, v112, v111
	v_fma_f32 v114, -v110, v113, v112
	v_fmac_f32_e32 v113, v114, v111
	v_fma_f32 v110, -v110, v113, v112
	v_max_f32_e32 v154, 0xc2c80000, v2
	v_fma_f32 v2, v108, v119, v6
	v_div_fmas_f32 v110, v110, v111, v113
	v_log_f32_e32 v2, v2
	v_div_fixup_f32 v87, v110, v87, 1.0
	v_rcp_f32_e32 v111, v86
	v_max_f32_e32 v155, 0xc2c80000, v2
	v_fma_f32 v2, v109, v120, v7
	v_log_f32_e32 v2, v2
	v_fma_f32 v112, -v86, v111, 1.0
	v_fmac_f32_e32 v111, v112, v111
	v_max_f32_e32 v156, 0xc2c80000, v2
	v_fma_f32 v2, v108, v136, v6
	v_log_f32_e32 v2, v2
	v_div_fixup_f32 v86, v111, v86, 1.0
	v_pk_mul_f32 v[64:65], v[64:65], v[86:87]
	v_pk_mul_f32 v[86:87], v[124:125], v[86:87]
	v_max_f32_e32 v157, 0xc2c80000, v2
	v_fma_f32 v2, v109, v138, v7
	v_add_f32_e32 v86, v4, v86
	v_log_f32_e32 v2, v2
	v_log_f32_e32 v86, v86
	v_pk_mul_f32 v[128:129], v[124:125], v[64:65]
	v_pk_add_f32 v[64:65], v[62:63], 1.0 op_sel_hi:[1,0]
	v_max_f32_e32 v158, 0xc2c80000, v2
	v_mul_f32_e32 v2, v109, v132
	v_max_f32_e32 v132, 0xc2c80000, v86
	v_add_f32_e32 v86, v5, v87
	v_log_f32_e32 v86, v86
	v_lshl_add_u64 v[118:119], v[74:75], 0, v[98:99]
	v_max_f32_e32 v134, 0xc2c80000, v86
	v_rcp_f32_e32 v87, v65
	s_nop 0
	v_fma_f32 v110, -v65, v87, 1.0
	v_fmac_f32_e32 v87, v110, v87
	v_div_fixup_f32 v65, v87, v65, 1.0
	v_rcp_f32_e32 v87, v64
	s_nop 0
	v_fma_f32 v110, -v64, v87, 1.0
	v_fmac_f32_e32 v87, v110, v87
	v_div_fixup_f32 v64, v87, v64, 1.0
	v_pk_mul_f32 v[62:63], v[62:63], v[64:65]
	v_pk_mul_f32 v[64:65], v[108:109], v[64:65]
	v_pk_add_f32 v[86:87], v[102:103], 1.0 op_sel_hi:[1,0]
	v_add_f32_e32 v64, v6, v64
	v_log_f32_e32 v64, v64
	v_lshl_add_u64 v[112:113], v[74:75], 0, v[88:89]
	v_lshl_add_u64 v[110:111], v[70:71], 0, v[88:89]
	v_div_scale_f32 v88, s[26:27], v87, v87, 1.0
	v_max_f32_e32 v163, 0xc2c80000, v64
	v_add_f32_e32 v64, v7, v65
	v_log_f32_e32 v64, v64
	v_rcp_f32_e32 v89, v88
	v_pk_mul_f32 v[114:115], v[108:109], v[62:63]
	v_lshl_add_u64 v[62:63], v[70:71], 0, v[90:91]
	v_max_f32_e32 v164, 0xc2c80000, v64
	v_lshl_add_u64 v[64:65], v[74:75], 0, v[90:91]
	v_fma_f32 v90, -v88, v89, 1.0
	v_fmac_f32_e32 v89, v90, v89
	v_div_scale_f32 v90, vcc, 1.0, v87, 1.0
	v_mul_f32_e32 v91, v90, v89
	v_fma_f32 v116, -v88, v91, v90
	v_fmac_f32_e32 v91, v116, v89
	v_fma_f32 v88, -v88, v91, v90
	v_div_fmas_f32 v88, v88, v89, v91
	v_div_fixup_f32 v87, v88, v87, 1.0
	v_rcp_f32_e32 v89, v86
	s_nop 0
	v_fma_f32 v90, -v86, v89, 1.0
	v_fmac_f32_e32 v89, v90, v89
	v_div_fixup_f32 v86, v89, v86, 1.0
	v_pk_mul_f32 v[88:89], v[102:103], v[86:87]
	v_pk_mul_f32 v[86:87], v[124:125], v[86:87]
	v_pk_mul_f32 v[144:145], v[124:125], v[88:89]
	v_add_f32_e32 v86, v4, v86
	v_log_f32_e32 v86, v86
	s_nop 0
	v_max_f32_e32 v102, 0xc2c80000, v86
	v_add_f32_e32 v86, v5, v87
	v_log_f32_e32 v86, v86
	s_nop 0
	v_max_f32_e32 v103, 0xc2c80000, v86
	v_pk_add_f32 v[86:87], v[82:83], 1.0 op_sel_hi:[1,0]
	s_nop 0
	v_rcp_f32_e32 v89, v87
	s_nop 0
	v_fma_f32 v90, -v87, v89, 1.0
	v_fmac_f32_e32 v89, v90, v89
	v_div_fixup_f32 v87, v89, v87, 1.0
	v_rcp_f32_e32 v89, v86
	s_nop 0
	v_fma_f32 v90, -v86, v89, 1.0
	v_fmac_f32_e32 v89, v90, v89
	v_div_fixup_f32 v86, v89, v86, 1.0
	v_pk_mul_f32 v[82:83], v[82:83], v[86:87]
	v_pk_mul_f32 v[86:87], v[108:109], v[86:87]
	v_pk_mul_f32 v[120:121], v[108:109], v[82:83]
	v_add_f32_e32 v86, v6, v86
	v_log_f32_e32 v86, v86
	v_pk_add_f32 v[82:83], v[126:127], 1.0 op_sel_hi:[1,0]
	v_lshl_add_u64 v[116:117], v[70:71], 0, v[98:99]
	v_div_scale_f32 v90, s[26:27], v83, v83, 1.0
	v_rcp_f32_e32 v91, v90
	v_max_f32_e32 v167, 0xc2c80000, v86
	v_add_f32_e32 v86, v7, v87
	v_log_f32_e32 v86, v86
	v_fma_f32 v98, -v90, v91, 1.0
	v_fmac_f32_e32 v91, v98, v91
	v_div_scale_f32 v98, vcc, 1.0, v83, 1.0
	v_mul_f32_e32 v99, v98, v91
	v_max_f32_e32 v168, 0xc2c80000, v86
	v_lshl_add_u64 v[88:89], v[74:75], 0, v[100:101]
	v_lshl_add_u64 v[86:87], v[70:71], 0, v[100:101]
	v_fma_f32 v100, -v90, v99, v98
	v_fmac_f32_e32 v99, v100, v91
	v_fma_f32 v90, -v90, v99, v98
	v_div_fmas_f32 v90, v90, v91, v99
	v_div_fixup_f32 v83, v90, v83, 1.0
	v_rcp_f32_e32 v91, v82
	s_nop 0
	v_fma_f32 v98, -v82, v91, 1.0
	v_fmac_f32_e32 v91, v98, v91
	v_div_fixup_f32 v82, v91, v82, 1.0
	v_pk_mul_f32 v[90:91], v[126:127], v[82:83]
	v_pk_mul_f32 v[82:83], v[124:125], v[82:83]
	v_pk_mul_f32 v[146:147], v[124:125], v[90:91]
	v_add_f32_e32 v4, v4, v82
	v_log_f32_e32 v4, v4
	s_nop 0
	v_max_f32_e32 v174, 0xc2c80000, v4
	v_add_f32_e32 v4, v5, v83
	v_log_f32_e32 v4, v4
	v_add_f32_e32 v172, v172, v174
	v_add_f32_e32 v175, v102, v172
	v_add_f32_e32 v124, v130, v175
	v_add_f32_e32 v130, v132, v124
	v_max_f32_e32 v127, 0xc2c80000, v4
	v_add_f32_e32 v132, v169, v130
	v_add_f32_e32 v125, v173, v127
	v_add_f32_e32 v136, v165, v132
	v_add_f32_e32 v173, v103, v125
	v_add_f32_e32 v4, v152, v136
	v_add_f32_e32 v126, v171, v173
	ds_bpermute_b32 v90, v13, v4
	ds_bpermute_b32 v98, v15, v4
	v_add_f32_e32 v176, v134, v126
	ds_bpermute_b32 v83, v9, v4
	v_add_f32_e32 v134, v170, v176
	v_add_f32_e32 v138, v166, v134
	v_add_f32_e32 v82, v153, v138
	s_waitcnt lgkmcnt(1)
	v_cndmask_b32_e64 v5, v98, v90, s[4:5]
	v_cndmask_b32_e64 v91, v98, v90, s[6:7]
	ds_bpermute_b32 v99, v13, v82
	ds_bpermute_b32 v100, v15, v82
	s_waitcnt lgkmcnt(2)
	v_cndmask_b32_e64 v5, v5, v83, s[10:11]
	v_cndmask_b32_e64 v91, v91, v83, s[8:9]
	v_cndmask_b32_e64 v90, v98, v90, s[10:11]
	ds_bpermute_b32 v98, v9, v82
	v_cndmask_b32_e64 v5, v5, v4, s[8:9]
	v_cndmask_b32_e64 v91, v91, v4, s[10:11]
	v_cndmask_b32_e64 v83, v90, v83, s[4:5]
	v_cndmask_b32_e64 v152, v83, v4, s[6:7]
	v_cndmask_b32_e64 v83, 0, v91, s[12:13]
	v_cndmask_b32_e64 v90, 0, v5, s[14:15]
	v_add_f32_e32 v83, v83, v90
	v_cndmask_b32_e64 v90, 0, v152, s[4:5]
	v_add_f32_e32 v90, v90, v83
	s_waitcnt lgkmcnt(1)
	v_cndmask_b32_e64 v83, v100, v99, s[4:5]
	v_cndmask_b32_e64 v101, v100, v99, s[6:7]
	s_waitcnt lgkmcnt(0)
	v_cndmask_b32_e64 v83, v83, v98, s[10:11]
	v_cndmask_b32_e64 v101, v101, v98, s[8:9]
	v_cndmask_b32_e64 v99, v100, v99, s[10:11]
	v_cndmask_b32_e64 v83, v83, v82, s[8:9]
	v_cndmask_b32_e64 v101, v101, v82, s[10:11]
	v_cndmask_b32_e64 v98, v99, v98, s[4:5]
	v_cndmask_b32_e64 v153, v98, v82, s[6:7]
	v_cndmask_b32_e64 v98, 0, v101, s[12:13]
	v_cndmask_b32_e64 v99, 0, v83, s[14:15]
	v_add_f32_e32 v98, v98, v99
	v_cndmask_b32_e64 v99, 0, v153, s[4:5]
	v_add_f32_e32 v100, v99, v98
	v_pk_add_f32 v[98:99], v[4:5], v[90:91]
	s_nop 0
	v_sub_f32_e32 v102, v98, v99
	v_med3_f32 v102, v102, s28, v236
	v_cmp_gt_f32_e32 vcc, s33, v102
	v_sub_f32_e32 v98, v99, v98
	v_med3_f32 v98, v98, s28, v236
	v_cndmask_b32_e32 v103, 0, v237, vcc
	v_add_f32_e32 v102, v102, v103
	v_exp_f32_e32 v102, v102
	v_cndmask_b32_e32 v103, 0, v238, vcc
	v_ldexp_f32 v170, v102, v103
	s_nop 0
	v_exp_f32_e32 v98, v98
	v_pk_add_f32 v[102:103], v[82:83], v[100:101]
	v_mul_f32_e32 v98, v142, v98
	v_sub_f32_e32 v142, v102, v103
	v_med3_f32 v142, v142, s28, v236
	v_cmp_gt_f32_e32 vcc, s33, v142
	v_sub_f32_e32 v102, v103, v102
	v_med3_f32 v102, v102, s28, v236
	v_cndmask_b32_e32 v165, 0, v237, vcc
	v_add_f32_e32 v142, v142, v165
	v_exp_f32_e32 v142, v142
	v_cndmask_b32_e32 v165, 0, v238, vcc
	v_ldexp_f32 v171, v142, v165
	s_nop 0
	v_exp_f32_e32 v102, v102
	v_pk_mul_f32 v[46:47], v[46:47], v[170:171]
	v_cvt_pk_bf16_f32 v142, v46, v47
	v_add_f32_e32 v47, v136, v90
	v_sub_f32_e32 v46, v47, v99
	v_med3_f32 v46, v46, s28, v236
	v_sub_f32_e32 v47, v99, v47
	v_med3_f32 v47, v47, s28, v236
	v_exp_f32_e32 v46, v46
	v_cmp_gt_f32_e32 vcc, s33, v47
	v_mul_f32_e32 v102, v140, v102
	s_nop 1
	v_cndmask_b32_e32 v136, 0, v237, vcc
	v_add_f32_e32 v47, v47, v136
	v_exp_f32_e32 v47, v47
	v_cndmask_b32_e32 v136, 0, v238, vcc
	v_cvt_pk_bf16_f32 v140, v98, v102
	v_ldexp_f32 v170, v47, v136
	v_add_f32_e32 v136, v138, v100
	v_sub_f32_e32 v47, v136, v103
	v_med3_f32 v47, v47, s28, v236
	s_nop 1
	v_exp_f32_e32 v47, v47
	s_nop 0
	v_pk_mul_f32 v[46:47], v[44:45], v[46:47]
	v_sub_f32_e32 v44, v103, v136
	v_med3_f32 v44, v44, s28, v236
	v_cmp_gt_f32_e32 vcc, s33, v44
	v_cvt_pk_bf16_f32 v138, v46, v47
	v_add_f32_e32 v47, v132, v90
	v_cndmask_b32_e32 v45, 0, v237, vcc
	v_add_f32_e32 v44, v44, v45
	v_exp_f32_e32 v44, v44
	v_sub_f32_e32 v46, v47, v99
	v_cndmask_b32_e32 v45, 0, v238, vcc
	v_med3_f32 v46, v46, s28, v236
	v_ldexp_f32 v171, v44, v45
	v_pk_mul_f32 v[44:45], v[122:123], v[170:171]
	v_sub_f32_e32 v47, v99, v47
	v_exp_f32_e32 v46, v46
	v_med3_f32 v47, v47, s28, v236
	v_cvt_pk_bf16_f32 v136, v44, v45
	v_exp_f32_e32 v47, v47
	v_add_f32_e32 v122, v134, v100
	v_mul_f32_e32 v160, v160, v47
	v_sub_f32_e32 v47, v122, v103
	v_med3_f32 v47, v47, s28, v236
	s_nop 1
	v_exp_f32_e32 v47, v47
	s_nop 0
	v_pk_mul_f32 v[46:47], v[58:59], v[46:47]
	v_sub_f32_e32 v58, v103, v122
	v_med3_f32 v58, v58, s28, v236
	v_cvt_pk_bf16_f32 v134, v46, v47
	v_add_f32_e32 v47, v130, v90
	v_exp_f32_e32 v58, v58
	v_sub_f32_e32 v46, v47, v99
	v_med3_f32 v46, v46, s28, v236
	v_mul_f32_e32 v162, v162, v58
	v_sub_f32_e32 v47, v99, v47
	v_exp_f32_e32 v46, v46
	v_med3_f32 v47, v47, s28, v236
	v_cmp_gt_f32_e32 vcc, s33, v47
	v_add_f32_e32 v59, v176, v100
	s_nop 1
	v_cndmask_b32_e32 v58, 0, v237, vcc
	v_add_f32_e32 v47, v47, v58
	v_exp_f32_e32 v47, v47
	v_cndmask_b32_e32 v58, 0, v238, vcc
	v_cvt_pk_bf16_f32 v132, v160, v162
	v_ldexp_f32 v58, v47, v58
	v_sub_f32_e32 v47, v59, v103
	v_med3_f32 v47, v47, s28, v236
	s_nop 1
	v_exp_f32_e32 v47, v47
	s_nop 0
	v_pk_mul_f32 v[56:57], v[56:57], v[46:47]
	v_sub_f32_e32 v46, v103, v59
	v_med3_f32 v46, v46, s28, v236
	v_cmp_gt_f32_e32 vcc, s33, v46
	v_cvt_pk_bf16_f32 v130, v56, v57
	v_add_f32_e32 v57, v124, v90
	v_cndmask_b32_e32 v47, 0, v237, vcc
	v_add_f32_e32 v46, v46, v47
	v_exp_f32_e32 v46, v46
	v_sub_f32_e32 v56, v57, v99
	v_cndmask_b32_e32 v47, 0, v238, vcc
	v_med3_f32 v56, v56, s28, v236
	v_ldexp_f32 v59, v46, v47
	v_pk_mul_f32 v[46:47], v[128:129], v[58:59]
	v_sub_f32_e32 v57, v99, v57
	v_exp_f32_e32 v56, v56
	v_med3_f32 v57, v57, s28, v236
	v_cvt_pk_bf16_f32 v128, v46, v47
	v_exp_f32_e32 v57, v57
	v_add_f32_e32 v58, v126, v100
	v_mul_f32_e32 v161, v161, v57
	v_sub_f32_e32 v57, v58, v103
	v_med3_f32 v57, v57, s28, v236
	s_nop 1
	v_exp_f32_e32 v57, v57
	s_nop 0
	v_pk_mul_f32 v[54:55], v[54:55], v[56:57]
	v_sub_f32_e32 v56, v103, v58
	v_med3_f32 v56, v56, s28, v236
	v_cvt_pk_bf16_f32 v126, v54, v55
	v_add_f32_e32 v55, v175, v90
	v_exp_f32_e32 v56, v56
	v_sub_f32_e32 v54, v55, v99
	v_med3_f32 v54, v54, s28, v236
	v_mul_f32_e32 v159, v159, v56
	v_sub_f32_e32 v55, v99, v55
	v_exp_f32_e32 v54, v54
	v_med3_f32 v55, v55, s28, v236
	v_cmp_gt_f32_e32 vcc, s33, v55
	v_add_f32_e32 v57, v173, v100
	s_nop 1
	v_cndmask_b32_e32 v56, 0, v237, vcc
	v_add_f32_e32 v55, v55, v56
	v_exp_f32_e32 v55, v55
	v_cndmask_b32_e32 v56, 0, v238, vcc
	v_cvt_pk_bf16_f32 v124, v161, v159
	v_ldexp_f32 v56, v55, v56
	v_sub_f32_e32 v55, v57, v103
	v_med3_f32 v55, v55, s28, v236
	s_nop 1
	v_exp_f32_e32 v55, v55
	s_nop 0
	v_pk_mul_f32 v[54:55], v[52:53], v[54:55]
	v_sub_f32_e32 v52, v103, v57
	v_med3_f32 v52, v52, s28, v236
	v_cmp_gt_f32_e32 vcc, s33, v52
	v_cvt_pk_bf16_f32 v122, v54, v55
	v_add_f32_e32 v55, v172, v90
	v_cndmask_b32_e32 v53, 0, v237, vcc
	v_add_f32_e32 v52, v52, v53
	v_exp_f32_e32 v52, v52
	v_sub_f32_e32 v54, v55, v99
	v_cndmask_b32_e32 v53, 0, v238, vcc
	v_med3_f32 v54, v54, s28, v236
	v_ldexp_f32 v57, v52, v53
	v_pk_mul_f32 v[52:53], v[144:145], v[56:57]
	v_sub_f32_e32 v55, v99, v55
	v_exp_f32_e32 v54, v54
	v_med3_f32 v55, v55, s28, v236
	v_cvt_pk_bf16_f32 v58, v52, v53
	v_exp_f32_e32 v55, v55
	v_add_f32_e32 v56, v125, v100
	v_mul_f32_e32 v165, v149, v55
	v_sub_f32_e32 v55, v56, v103
	v_med3_f32 v55, v55, s28, v236
	s_nop 1
	v_exp_f32_e32 v55, v55
	s_nop 0
	v_pk_mul_f32 v[50:51], v[50:51], v[54:55]
	v_sub_f32_e32 v54, v103, v56
	v_med3_f32 v54, v54, s28, v236
	v_cvt_pk_bf16_f32 v56, v50, v51
	v_add_f32_e32 v51, v174, v90
	v_exp_f32_e32 v54, v54
	v_sub_f32_e32 v50, v51, v99
	v_med3_f32 v50, v50, s28, v236
	v_sub_f32_e32 v51, v99, v51
	v_exp_f32_e32 v50, v50
	v_med3_f32 v51, v51, s28, v236
	v_cmp_gt_f32_e32 vcc, s33, v51
	v_mul_f32_e32 v166, v148, v54
	s_nop 1
	v_cndmask_b32_e32 v55, 0, v237, vcc
	v_add_f32_e32 v51, v51, v55
	v_exp_f32_e32 v51, v51
	v_cndmask_b32_e32 v55, 0, v238, vcc
	v_cvt_pk_bf16_f32 v54, v165, v166
	v_ldexp_f32 v144, v51, v55
	v_add_f32_e32 v55, v127, v100
	v_sub_f32_e32 v51, v55, v103
	v_med3_f32 v51, v51, s28, v236
	s_nop 1
	v_exp_f32_e32 v51, v51
	s_nop 0
	v_pk_mul_f32 v[50:51], v[48:49], v[50:51]
	v_sub_f32_e32 v48, v103, v55
	v_med3_f32 v48, v48, s28, v236
	v_cmp_gt_f32_e32 vcc, s33, v48
	s_nop 1
	v_cndmask_b32_e32 v49, 0, v237, vcc
	v_add_f32_e32 v48, v48, v49
	v_exp_f32_e32 v48, v48
	v_cndmask_b32_e32 v49, 0, v238, vcc
	v_ldexp_f32 v145, v48, v49
	v_pk_mul_f32 v[48:49], v[146:147], v[144:145]
	v_pk_add_f32 v[144:145], v[80:81], 1.0 op_sel_hi:[1,0]
	s_nop 0
	v_rcp_f32_e32 v57, v145
	s_nop 0
	v_fma_f32 v59, -v145, v57, 1.0
	v_fmac_f32_e32 v57, v59, v57
	v_div_fixup_f32 v145, v57, v145, 1.0
	v_rcp_f32_e32 v57, v144
	s_mov_b64 s[26:27], 0xf000000
	v_fma_f32 v59, -v144, v57, 1.0
	v_fmac_f32_e32 v57, v59, v57
	v_div_fixup_f32 v144, v57, v144, 1.0
	v_pk_mul_f32 v[80:81], v[80:81], v[144:145]
	v_pk_mul_f32 v[144:145], v[108:109], v[144:145]
	v_pk_mul_f32 v[148:149], v[108:109], v[80:81]
	v_add_f32_e32 v6, v6, v144
	v_log_f32_e32 v6, v6
	s_nop 0
	v_max_f32_e32 v170, 0xc2c80000, v6
	v_add_f32_e32 v57, v157, v170
	v_add_f32_e32 v123, v167, v57
	v_add_f32_e32 v125, v155, v123
	v_add_f32_e32 v6, v7, v145
	v_add_f32_e32 v129, v163, v125
	v_log_f32_e32 v6, v6
	v_add_f32_e32 v157, v151, v129
	v_add_f32_e32 v163, v143, v157
	v_add_f32_e32 v80, v139, v163
	ds_bpermute_b32 v90, v13, v80
	ds_bpermute_b32 v100, v15, v80
	v_max_f32_e32 v169, 0xc2c80000, v6
	ds_bpermute_b32 v7, v9, v80
	v_add_f32_e32 v55, v158, v169
	v_add_f32_e32 v59, v168, v55
	v_add_f32_e32 v127, v156, v59
	v_add_f32_e32 v156, v164, v127
	s_waitcnt lgkmcnt(1)
	v_cndmask_b32_e64 v81, v100, v90, s[4:5]
	v_cndmask_b32_e64 v108, v100, v90, s[6:7]
	v_add_f32_e32 v158, v154, v156
	s_waitcnt lgkmcnt(0)
	v_cndmask_b32_e64 v81, v81, v7, s[10:11]
	v_cndmask_b32_e64 v108, v108, v7, s[8:9]
	v_cndmask_b32_e64 v90, v100, v90, s[10:11]
	v_add_f32_e32 v164, v150, v158
	v_cndmask_b32_e64 v81, v81, v80, s[8:9]
	v_cndmask_b32_e64 v147, v108, v80, s[10:11]
	v_cndmask_b32_e64 v7, v90, v7, s[4:5]
	v_add_f32_e32 v6, v141, v164
	v_cndmask_b32_e64 v90, v7, v80, s[6:7]
	v_cndmask_b32_e64 v7, 0, v147, s[12:13]
	v_cndmask_b32_e64 v100, 0, v81, s[14:15]
	v_add_f32_e32 v7, v7, v100
	v_cndmask_b32_e64 v100, 0, v90, s[4:5]
	ds_bpermute_b32 v108, v13, v6
	ds_bpermute_b32 v109, v15, v6
	v_add_f32_e32 v146, v100, v7
	ds_bpermute_b32 v100, v9, v6
	s_waitcnt lgkmcnt(1)
	v_cndmask_b32_e64 v7, v109, v108, s[4:5]
	v_cndmask_b32_e64 v139, v109, v108, s[6:7]
	s_waitcnt lgkmcnt(0)
	v_cndmask_b32_e64 v7, v7, v100, s[10:11]
	v_cndmask_b32_e64 v139, v139, v100, s[8:9]
	v_cndmask_b32_e64 v108, v109, v108, s[10:11]
	v_cndmask_b32_e64 v7, v7, v6, s[8:9]
	v_cndmask_b32_e64 v151, v139, v6, s[10:11]
	v_cndmask_b32_e64 v100, v108, v100, s[4:5]
	v_cndmask_b32_e64 v100, v100, v6, s[6:7]
	v_cndmask_b32_e64 v109, 0, v151, s[12:13]
	v_cndmask_b32_e64 v139, 0, v7, s[14:15]
	v_cndmask_b32_e64 v108, 0, v100, s[4:5]
	v_add_f32_e32 v109, v109, v139
	v_add_f32_e32 v150, v108, v109
	v_pk_add_f32 v[108:109], v[80:81], v[146:147]
	v_pk_add_f32 v[144:145], v[6:7], v[150:151]
	v_sub_f32_e32 v139, v108, v109
	v_med3_f32 v139, v139, s28, v236
	v_cmp_gt_f32_e32 vcc, s33, v139
	v_sub_f32_e32 v108, v109, v108
	v_med3_f32 v108, v108, s28, v236
	v_cndmask_b32_e32 v141, 0, v237, vcc
	v_add_f32_e32 v139, v139, v141
	v_exp_f32_e32 v139, v139
	v_cndmask_b32_e32 v141, 0, v238, vcc
	v_ldexp_f32 v154, v139, v141
	s_nop 0
	v_exp_f32_e32 v108, v108
	s_nop 0
	v_mul_f32_e32 v108, v137, v108
	v_sub_f32_e32 v137, v144, v145
	v_med3_f32 v137, v137, s28, v236
	v_cmp_gt_f32_e32 vcc, s33, v137
	s_nop 1
	v_cndmask_b32_e32 v139, 0, v237, vcc
	v_add_f32_e32 v137, v137, v139
	v_exp_f32_e32 v137, v137
	v_cndmask_b32_e32 v139, 0, v238, vcc
	v_ldexp_f32 v155, v137, v139
	v_sub_f32_e32 v137, v145, v144
	v_med3_f32 v137, v137, s28, v236
	v_pk_mul_f32 v[30:31], v[30:31], v[154:155]
	s_nop 0
	v_exp_f32_e32 v137, v137
	v_cvt_pk_bf16_f32 v143, v30, v31
	v_add_f32_e32 v31, v163, v146
	v_sub_f32_e32 v30, v31, v109
	v_mul_f32_e32 v144, v133, v137
	v_med3_f32 v30, v30, s28, v236
	v_cvt_pk_bf16_f32 v141, v108, v144
	global_store_dwordx2 v[76:77], v[140:141], off
	v_sub_f32_e32 v31, v109, v31
	v_exp_f32_e32 v30, v30
	v_med3_f32 v31, v31, s28, v236
	v_cmp_gt_f32_e32 vcc, s33, v31
	v_add_f32_e32 v77, v164, v150
	s_nop 1
	v_cndmask_b32_e32 v76, 0, v237, vcc
	v_add_f32_e32 v31, v31, v76
	v_exp_f32_e32 v31, v31
	v_cndmask_b32_e32 v76, 0, v238, vcc
	global_store_dwordx2 v[78:79], v[142:143], off
	v_ldexp_f32 v76, v31, v76
	v_sub_f32_e32 v31, v77, v145
	v_med3_f32 v31, v31, s28, v236
	s_nop 1
	v_exp_f32_e32 v31, v31
	s_nop 0
	v_pk_mul_f32 v[30:31], v[28:29], v[30:31]
	v_sub_f32_e32 v28, v145, v77
	v_med3_f32 v28, v28, s28, v236
	v_cmp_gt_f32_e32 vcc, s33, v28
	v_cvt_pk_bf16_f32 v139, v30, v31
	v_add_f32_e32 v31, v157, v146
	v_cndmask_b32_e32 v29, 0, v237, vcc
	v_add_f32_e32 v28, v28, v29
	v_exp_f32_e32 v28, v28
	v_sub_f32_e32 v30, v31, v109
	v_cndmask_b32_e32 v29, 0, v238, vcc
	v_med3_f32 v30, v30, s28, v236
	v_ldexp_f32 v77, v28, v29
	v_pk_mul_f32 v[28:29], v[66:67], v[76:77]
	v_sub_f32_e32 v31, v109, v31
	v_exp_f32_e32 v30, v30
	v_med3_f32 v31, v31, s28, v236
	v_add_f32_e32 v67, v158, v150
	v_exp_f32_e32 v31, v31
	v_cvt_pk_bf16_f32 v137, v28, v29
	global_store_dwordx2 v[106:107], v[138:139], off
	v_mul_f32_e32 v66, v135, v31
	v_sub_f32_e32 v31, v67, v145
	v_med3_f32 v31, v31, s28, v236
	global_store_dwordx2 v[104:105], v[136:137], off
	s_nop 0
	v_exp_f32_e32 v31, v31
	s_nop 0
	v_pk_mul_f32 v[30:31], v[42:43], v[30:31]
	v_sub_f32_e32 v42, v145, v67
	v_med3_f32 v42, v42, s28, v236
	v_cvt_pk_bf16_f32 v135, v30, v31
	v_add_f32_e32 v31, v129, v146
	v_exp_f32_e32 v42, v42
	v_sub_f32_e32 v30, v31, v109
	v_med3_f32 v30, v30, s28, v236
	v_mul_f32_e32 v67, v131, v42
	v_sub_f32_e32 v31, v109, v31
	v_exp_f32_e32 v30, v30
	v_med3_f32 v31, v31, s28, v236
	v_cmp_gt_f32_e32 vcc, s33, v31
	v_add_f32_e32 v43, v156, v150
	s_nop 1
	v_cndmask_b32_e32 v42, 0, v237, vcc
	v_add_f32_e32 v31, v31, v42
	v_exp_f32_e32 v31, v31
	v_cndmask_b32_e32 v42, 0, v238, vcc
	v_cvt_pk_bf16_f32 v133, v66, v67
	global_store_dwordx2 v[68:69], v[132:133], off
	v_ldexp_f32 v42, v31, v42
	v_sub_f32_e32 v31, v43, v145
	v_med3_f32 v31, v31, s28, v236
	global_store_dwordx2 v[84:85], v[134:135], off
	s_nop 0
	v_exp_f32_e32 v31, v31
	s_nop 0
	v_pk_mul_f32 v[40:41], v[40:41], v[30:31]
	v_sub_f32_e32 v30, v145, v43
	v_med3_f32 v30, v30, s28, v236
	v_cmp_gt_f32_e32 vcc, s33, v30
	v_cvt_pk_bf16_f32 v131, v40, v41
	v_add_f32_e32 v41, v125, v146
	v_cndmask_b32_e32 v31, 0, v237, vcc
	v_add_f32_e32 v30, v30, v31
	v_exp_f32_e32 v30, v30
	v_sub_f32_e32 v40, v41, v109
	v_cndmask_b32_e32 v31, 0, v238, vcc
	v_med3_f32 v40, v40, s28, v236
	v_ldexp_f32 v43, v30, v31
	v_pk_mul_f32 v[30:31], v[114:115], v[42:43]
	v_sub_f32_e32 v41, v109, v41
	v_exp_f32_e32 v40, v40
	v_med3_f32 v41, v41, s28, v236
	v_cvt_pk_bf16_f32 v129, v30, v31
	v_exp_f32_e32 v41, v41
	global_store_dwordx2 v[112:113], v[130:131], off
	global_store_dwordx2 v[110:111], v[128:129], off
	v_add_f32_e32 v42, v127, v150
	v_mul_f32_e32 v27, v27, v41
	v_sub_f32_e32 v41, v42, v145
	v_med3_f32 v41, v41, s28, v236
	s_nop 1
	v_exp_f32_e32 v41, v41
	s_nop 0
	v_pk_mul_f32 v[38:39], v[38:39], v[40:41]
	v_sub_f32_e32 v40, v145, v42
	v_med3_f32 v40, v40, s28, v236
	v_cvt_pk_bf16_f32 v127, v38, v39
	v_add_f32_e32 v39, v123, v146
	v_exp_f32_e32 v40, v40
	v_sub_f32_e32 v38, v39, v109
	v_med3_f32 v38, v38, s28, v236
	v_mul_f32_e32 v25, v25, v40
	v_sub_f32_e32 v39, v109, v39
	v_exp_f32_e32 v38, v38
	v_med3_f32 v39, v39, s28, v236
	v_cmp_gt_f32_e32 vcc, s33, v39
	v_add_f32_e32 v41, v59, v150
	s_nop 1
	v_cndmask_b32_e32 v40, 0, v237, vcc
	v_add_f32_e32 v39, v39, v40
	v_exp_f32_e32 v39, v39
	v_cndmask_b32_e32 v40, 0, v238, vcc
	v_cvt_pk_bf16_f32 v125, v27, v25
	global_store_dwordx2 v[64:65], v[126:127], off
	v_ldexp_f32 v40, v39, v40
	v_sub_f32_e32 v39, v41, v145
	v_med3_f32 v39, v39, s28, v236
	global_store_dwordx2 v[62:63], v[124:125], off
	s_nop 0
	v_exp_f32_e32 v39, v39
	s_nop 0
	v_pk_mul_f32 v[36:37], v[36:37], v[38:39]
	v_sub_f32_e32 v38, v145, v41
	v_med3_f32 v38, v38, s28, v236
	v_cmp_gt_f32_e32 vcc, s33, v38
	v_cvt_pk_bf16_f32 v123, v36, v37
	v_add_f32_e32 v37, v57, v146
	v_cndmask_b32_e32 v39, 0, v237, vcc
	v_add_f32_e32 v38, v38, v39
	v_exp_f32_e32 v38, v38
	v_sub_f32_e32 v36, v37, v109
	v_cndmask_b32_e32 v39, 0, v238, vcc
	v_med3_f32 v36, v36, s28, v236
	v_ldexp_f32 v41, v38, v39
	v_pk_mul_f32 v[38:39], v[120:121], v[40:41]
	v_sub_f32_e32 v37, v109, v37
	v_exp_f32_e32 v36, v36
	v_med3_f32 v37, v37, s28, v236
	v_cvt_pk_bf16_f32 v59, v38, v39
	v_exp_f32_e32 v37, v37
	global_store_dwordx2 v[116:117], v[58:59], off
	global_store_dwordx2 v[118:119], v[122:123], off
	v_add_f32_e32 v40, v55, v150
	v_mul_f32_e32 v23, v23, v37
	v_sub_f32_e32 v37, v40, v145
	v_med3_f32 v37, v37, s28, v236
	s_nop 1
	v_exp_f32_e32 v37, v37
	s_nop 0
	v_pk_mul_f32 v[34:35], v[34:35], v[36:37]
	v_sub_f32_e32 v36, v145, v40
	v_med3_f32 v36, v36, s28, v236
	v_cvt_pk_bf16_f32 v57, v34, v35
	v_lshl_add_u64 v[40:41], v[60:61], 0, s[26:27]
	v_exp_f32_e32 v36, v36
	global_store_dwordx2 v[88:89], v[56:57], off
	v_mul_f32_e32 v58, v2, v36
	v_add_f32_e32 v2, v170, v146
	v_sub_f32_e32 v34, v2, v109
	v_med3_f32 v34, v34, s28, v236
	v_sub_f32_e32 v2, v109, v2
	v_med3_f32 v2, v2, s28, v236
	v_exp_f32_e32 v34, v34
	v_cmp_gt_f32_e32 vcc, s33, v2
	v_cvt_pk_bf16_f32 v55, v23, v58
	s_nop 1
	v_cndmask_b32_e32 v35, 0, v237, vcc
	v_add_f32_e32 v2, v2, v35
	v_exp_f32_e32 v2, v2
	v_cndmask_b32_e32 v35, 0, v238, vcc
	global_store_dwordx2 v[86:87], v[54:55], off
	v_ldexp_f32 v36, v2, v35
	v_add_f32_e32 v2, v169, v150
	v_sub_f32_e32 v35, v2, v145
	v_med3_f32 v35, v35, s28, v236
	v_sub_f32_e32 v2, v145, v2
	v_med3_f32 v2, v2, s28, v236
	v_exp_f32_e32 v35, v35
	v_cmp_gt_f32_e32 vcc, s33, v2
	v_pk_mul_f32 v[32:33], v[32:33], v[34:35]
	s_nop 1
	v_cndmask_b32_e32 v34, 0, v237, vcc
	v_add_f32_e32 v2, v2, v34
	v_exp_f32_e32 v2, v2
	v_cndmask_b32_e32 v34, 0, v238, vcc
	v_cvt_pk_bf16_f32 v35, v32, v33
	v_lshl_add_u64 v[32:33], v[74:75], 0, v[92:93]
	v_ldexp_f32 v37, v2, v34
	v_pk_mul_f32 v[36:37], v[148:149], v[36:37]
	v_cvt_pk_bf16_f32 v34, v50, v51
	global_store_dwordx2 v[32:33], v[34:35], off
	v_cvt_pk_bf16_f32 v32, v48, v49
	v_cvt_pk_bf16_f32 v33, v36, v37
	v_lshl_add_u64 v[34:35], v[70:71], 0, v[92:93]
	v_lshlrev_b32_e32 v2, 1, v19
	global_store_dwordx2 v[34:35], v[32:33], off
	v_cvt_pk_bf16_f32 v32, v98, v44
	v_cvt_pk_bf16_f32 v33, v160, v46
	v_cvt_pk_bf16_f32 v34, v161, v52
	v_cvt_pk_bf16_f32 v35, v165, v48
	v_lshl_add_u64 v[42:43], v[40:41], 0, v[2:3]
	global_store_dwordx4 v[42:43], v[32:35], off
	v_lshl_add_u64 v[42:43], v[40:41], 0, v[72:73]
	s_nop 0
	v_cvt_pk_bf16_f32 v32, v102, v45
	v_cvt_pk_bf16_f32 v33, v162, v47
	v_cvt_pk_bf16_f32 v34, v159, v53
	v_cvt_pk_bf16_f32 v35, v166, v49
	global_store_dwordx4 v[42:43], v[32:35], off
	v_lshl_add_u64 v[42:43], v[40:41], 0, v[94:95]
	s_nop 0
	v_cvt_pk_bf16_f32 v32, v108, v28
	v_cvt_pk_bf16_f32 v33, v66, v30
	v_cvt_pk_bf16_f32 v34, v27, v38
	v_cvt_pk_bf16_f32 v35, v23, v36
	global_store_dwordx4 v[42:43], v[32:35], off
	v_cvt_pk_bf16_f32 v28, v144, v29
	v_cvt_pk_bf16_f32 v29, v67, v31
	v_cvt_pk_bf16_f32 v30, v25, v39
	v_cvt_pk_bf16_f32 v31, v58, v37
	v_lshl_add_u64 v[32:33], v[40:41], 0, v[96:97]
	global_store_dwordx4 v[32:33], v[28:31], off
	s_and_saveexec_b64 s[26:27], s[4:5]
	s_cbranch_execz .LBB0_174
	v_add_f32_e32 v4, v4, v152
	s_mov_b32 s28, 0xc2fc0000
	v_add_f32_e32 v4, v5, v4
	v_cmp_gt_f32_e32 vcc, s28, v99
	v_add_f32_e32 v5, v91, v4
	v_add_f32_e32 v4, v6, v100
	v_cndmask_b32_e32 v6, 0, v237, vcc
	v_add_f32_e32 v6, v99, v6
	v_exp_f32_e32 v6, v6
	v_add_f32_e32 v4, v7, v4
	v_sub_f32_e32 v5, v5, v99
	v_add_f32_e32 v23, v151, v4
	v_cndmask_b32_e32 v4, 0, v238, vcc
	v_cmp_gt_f32_e32 vcc, s28, v5
	v_ldexp_f32 v4, v6, v4
	v_add_f32_e32 v19, v82, v153
	v_cndmask_b32_e32 v6, 0, v237, vcc
	v_add_f32_e32 v5, v5, v6
	v_exp_f32_e32 v5, v5
	v_cndmask_b32_e32 v6, 0, v238, vcc
	v_cmp_gt_f32_e32 vcc, s28, v103
	v_add_f32_e32 v19, v83, v19
	v_ldexp_f32 v28, v5, v6
	v_cndmask_b32_e32 v6, 0, v237, vcc
	v_add_f32_e32 v6, v103, v6
	v_exp_f32_e32 v6, v6
	v_add_f32_e32 v19, v101, v19
	v_cndmask_b32_e32 v5, 0, v238, vcc
	v_add_f32_e32 v2, v80, v90
	v_ldexp_f32 v5, v6, v5
	v_sub_f32_e32 v6, v19, v103
	v_cmp_gt_f32_e32 vcc, s28, v6
	v_add_f32_e32 v2, v81, v2
	v_add_f32_e32 v2, v147, v2
	v_cndmask_b32_e32 v7, 0, v237, vcc
	v_add_f32_e32 v6, v6, v7
	v_exp_f32_e32 v6, v6
	v_cndmask_b32_e32 v7, 0, v238, vcc
	v_cmp_gt_f32_e32 vcc, s28, v109
	v_sub_f32_e32 v2, v2, v109
	v_ldexp_f32 v29, v6, v7
	v_cndmask_b32_e32 v7, 0, v237, vcc
	v_add_f32_e32 v7, v109, v7
	v_exp_f32_e32 v7, v7
	v_cndmask_b32_e32 v6, 0, v238, vcc
	v_cmp_gt_f32_e32 vcc, s28, v2
	v_ldexp_f32 v6, v7, v6
	s_nop 0
	v_cndmask_b32_e32 v7, 0, v237, vcc
	v_add_f32_e32 v2, v2, v7
	v_exp_f32_e32 v2, v2
	v_cndmask_b32_e32 v7, 0, v238, vcc
	v_cmp_gt_f32_e32 vcc, s28, v145
	v_ldexp_f32 v30, v2, v7
	s_nop 0
	v_cndmask_b32_e32 v7, 0, v237, vcc
	v_add_f32_e32 v7, v145, v7
	v_exp_f32_e32 v7, v7
	v_cndmask_b32_e32 v2, 0, v238, vcc
	v_ldexp_f32 v7, v7, v2
	v_sub_f32_e32 v2, v23, v145
	v_cmp_gt_f32_e32 vcc, s28, v2
	global_store_dwordx4 v21, v[4:7], s[24:25] offset:1024
	s_nop 1
	v_cndmask_b32_e32 v4, 0, v237, vcc
	v_add_f32_e32 v2, v2, v4
	v_exp_f32_e32 v2, v2
	v_cndmask_b32_e32 v4, 0, v238, vcc
	v_ldexp_f32 v31, v2, v4
	global_store_dwordx4 v21, v[28:31], s[24:25] offset:1536
	s_branch .LBB0_174

.LBB0_495:
	v_add_u32_e32 v12, s59, v1
	v_add_u32_e32 v18, 0x2020, v12
	v_mad_i64_i32 v[24:25], s[14:15], v18, s36, v[16:17]
	v_add_co_u32_e32 v20, vcc, 0x1000, v24
	v_add_u32_e32 v1, 32, v1
	s_nop 0
	v_addc_co_u32_e32 v21, vcc, 0, v25, vcc
	v_add_co_u32_e32 v24, vcc, s74, v24
	global_load_dwordx4 v[12:15], v[20:21], off
	s_nop 0
	global_load_dwordx4 v[20:23], v[20:21], off offset:2048
	v_addc_co_u32_e32 v25, vcc, 0, v25, vcc
	global_load_dwordx4 v[24:27], v[24:25], off
	s_waitcnt vmcnt(2)
	v_lshlrev_b32_e32 v28, 16, v15
	v_and_b32_e32 v29, 0xffff0000, v15
	v_lshlrev_b32_e32 v34, 16, v14
	v_and_b32_e32 v35, 0xffff0000, v14
	s_waitcnt vmcnt(1)
	v_lshlrev_b32_e32 v14, 16, v22
	v_and_b32_e32 v15, 0xffff0000, v22
	s_waitcnt vmcnt(0)
	v_lshlrev_b32_e32 v22, 16, v26
	v_lshlrev_b32_e32 v30, 16, v23
	v_and_b32_e32 v31, 0xffff0000, v23
	v_and_b32_e32 v23, 0xffff0000, v26
	v_mul_f32_e32 v19, 0xbfb8aa3b, v22
	v_pk_add_f32 v[14:15], v[34:35], v[14:15]
	v_exp_f32_e32 v34, v19
	v_mul_f32_e32 v19, 0xbfb8aa3b, v23
	v_exp_f32_e32 v35, v19
	v_lshlrev_b32_e32 v32, 16, v27
	v_and_b32_e32 v33, 0xffff0000, v27
	v_pk_mul_f32 v[26:27], v[14:15], v[14:15]
	v_pk_add_f32 v[34:35], v[34:35], 1.0 op_sel_hi:[1,0]
	v_pk_add_f32 v[28:29], v[28:29], v[30:31]
	v_rcp_f32_e32 v36, v35
	v_pk_mul_f32 v[30:31], v[28:29], v[28:29]
	v_fma_f32 v37, -v35, v36, 1.0
	v_fmac_f32_e32 v36, v37, v36
	v_div_fixup_f32 v35, v36, v35, 1.0
	v_rcp_f32_e32 v36, v34
	s_nop 0
	v_fma_f32 v37, -v34, v36, 1.0
	v_fmac_f32_e32 v36, v37, v36
	v_div_fixup_f32 v34, v36, v34, 1.0
	v_lshlrev_b32_e32 v38, 16, v25
	v_pk_mul_f32 v[22:23], v[34:35], v[22:23]
	v_lshlrev_b32_e32 v34, 16, v13
	v_and_b32_e32 v35, 0xffff0000, v13
	v_and_b32_e32 v39, 0xffff0000, v25
	v_mul_f32_e32 v13, 0xbfb8aa3b, v38
	v_exp_f32_e32 v40, v13
	v_mul_f32_e32 v13, 0xbfb8aa3b, v39
	v_exp_f32_e32 v41, v13
	v_lshlrev_b32_e32 v36, 16, v21
	v_and_b32_e32 v37, 0xffff0000, v21
	v_pk_add_f32 v[34:35], v[34:35], v[36:37]
	v_pk_add_f32 v[40:41], v[40:41], 1.0 op_sel_hi:[1,0]
	v_pk_mul_f32 v[36:37], v[34:35], v[34:35]
	v_rcp_f32_e32 v19, v41
	s_nop 0
	v_fma_f32 v21, -v41, v19, 1.0
	v_fmac_f32_e32 v19, v21, v19
	v_div_fixup_f32 v41, v19, v41, 1.0
	v_rcp_f32_e32 v19, v40
	s_nop 0
	v_fma_f32 v21, -v40, v19, 1.0
	v_fmac_f32_e32 v19, v21, v19
	v_div_fixup_f32 v40, v19, v40, 1.0
	v_pk_mul_f32 v[38:39], v[40:41], v[38:39]
	v_lshlrev_b32_e32 v40, 16, v12
	v_and_b32_e32 v41, 0xffff0000, v12
	v_lshlrev_b32_e32 v12, 16, v20
	v_and_b32_e32 v13, 0xffff0000, v20
	v_lshlrev_b32_e32 v20, 16, v24
	v_and_b32_e32 v21, 0xffff0000, v24
	v_mul_f32_e32 v19, 0xbfb8aa3b, v20
	v_pk_add_f32 v[12:13], v[40:41], v[12:13]
	v_exp_f32_e32 v40, v19
	v_mul_f32_e32 v19, 0xbfb8aa3b, v21
	v_exp_f32_e32 v41, v19
	v_pk_mul_f32 v[24:25], v[12:13], v[12:13]
	v_pk_add_f32 v[40:41], v[40:41], 1.0 op_sel_hi:[1,0]
	s_nop 0
	v_rcp_f32_e32 v42, v41
	s_nop 0
	v_fma_f32 v43, -v41, v42, 1.0
	v_fmac_f32_e32 v42, v43, v42
	v_div_fixup_f32 v41, v42, v41, 1.0
	v_rcp_f32_e32 v42, v40
	s_nop 0
	v_fma_f32 v43, -v40, v42, 1.0
	v_fmac_f32_e32 v42, v43, v42
	v_div_fixup_f32 v40, v42, v40, 1.0
	v_add_f32_e32 v19, v24, v25
	v_add_f32_e32 v19, v36, v19
	v_add_f32_e32 v19, v37, v19
	v_add_f32_e32 v19, v26, v19
	v_add_f32_e32 v19, v27, v19
	v_add_f32_e32 v19, v30, v19
	v_add_f32_e32 v19, v31, v19
	v_pk_mul_f32 v[20:21], v[40:41], v[20:21]
	s_nop 0
	v_add_f32_dpp v19, v19, v19 quad_perm:[1,0,3,2] row_mask:0xf bank_mask:0xf bound_ctrl:1
	s_nop 1
	v_add_f32_dpp v19, v19, v19 quad_perm:[2,3,0,1] row_mask:0xf bank_mask:0xf bound_ctrl:1
	s_nop 1
	v_add_f32_dpp v19, v19, v19 row_half_mirror row_mask:0xf bank_mask:0xf bound_ctrl:1
	s_nop 1
	v_add_f32_dpp v19, v19, v19 row_mirror row_mask:0xf bank_mask:0xf bound_ctrl:1
	v_fmamk_f32 v19, v19, 0x3c000000, v198
	v_cmp_gt_f32_e32 vcc, s19, v19
	v_mul_f32_e32 v24, 0x4b800000, v19
	s_nop 0
	v_cndmask_b32_e32 v19, v19, v24, vcc
	v_rsq_f32_e32 v19, v19
	s_nop 0
	v_mul_f32_e32 v24, 0x45800000, v19
	v_cndmask_b32_e32 v24, v19, v24, vcc
	v_pk_mul_f32 v[14:15], v[14:15], v[24:25] op_sel_hi:[1,0]
	v_mul_f32_e32 v19, 0xbfb8aa3b, v32
	v_pk_mul_f32 v[14:15], v[4:5], v[14:15]
	v_pk_mul_f32 v[12:13], v[12:13], v[24:25] op_sel_hi:[1,0]
	v_pk_mul_f32 v[14:15], v[22:23], v[14:15]
	v_exp_f32_e32 v22, v19
	v_mul_f32_e32 v19, 0xbfb8aa3b, v33
	v_exp_f32_e32 v23, v19
	v_pk_mul_f32 v[12:13], v[8:9], v[12:13]
	v_cvt_pk_bf16_f32 v14, v14, v15
	v_pk_mul_f32 v[12:13], v[20:21], v[12:13]
	v_pk_add_f32 v[22:23], v[22:23], 1.0 op_sel_hi:[1,0]
	v_pk_mul_f32 v[20:21], v[34:35], v[24:25] op_sel_hi:[1,0]
	v_div_scale_f32 v19, s[14:15], v23, v23, 1.0
	v_rcp_f32_e32 v26, v19
	v_pk_mul_f32 v[24:25], v[28:29], v[24:25] op_sel_hi:[1,0]
	v_pk_mul_f32 v[20:21], v[10:11], v[20:21]
	v_cvt_pk_bf16_f32 v12, v12, v13
	v_fma_f32 v27, -v19, v26, 1.0
	v_fmac_f32_e32 v26, v27, v26
	v_div_scale_f32 v27, vcc, 1.0, v23, 1.0
	v_mul_f32_e32 v28, v27, v26
	v_fma_f32 v29, -v19, v28, v27
	v_fmac_f32_e32 v28, v29, v26
	v_fma_f32 v19, -v19, v28, v27
	v_div_fmas_f32 v19, v19, v26, v28
	v_div_fixup_f32 v23, v19, v23, 1.0
	v_rcp_f32_e32 v26, v22
	v_pk_mul_f32 v[20:21], v[38:39], v[20:21]
	v_pk_mul_f32 v[24:25], v[6:7], v[24:25]
	v_cvt_pk_bf16_f32 v13, v20, v21
	v_fma_f32 v27, -v22, v26, 1.0
	v_fmac_f32_e32 v26, v27, v26
	v_mov_b64_e32 v[20:21], s[20:21]
	v_div_fixup_f32 v22, v26, v22, 1.0
	v_mad_i64_i32 v[18:19], s[14:15], v18, s18, v[20:21]
	v_lshl_add_u64 v[18:19], v[18:19], 0, s[84:85]
	v_lshl_add_u64 v[18:19], v[18:19], 0, v[2:3]
	v_add_co_u32_e32 v18, vcc, 0x6eb8a000, v18
	v_pk_mul_f32 v[22:23], v[22:23], v[32:33]
	s_nop 0
	v_addc_co_u32_e32 v19, vcc, 0, v19, vcc
	s_movk_i32 s14, 0xfdf
	v_pk_mul_f32 v[22:23], v[22:23], v[24:25]
	v_cmp_lt_i32_e32 vcc, s14, v1
	v_cvt_pk_bf16_f32 v15, v22, v23
	s_or_b64 s[12:13], vcc, s[12:13]
	global_store_dwordx4 v[18:19], v[12:15], off offset:2048
	s_andn2_b64 exec, exec, s[12:13]
	s_cbranch_execnz .LBB0_495
	s_branch .LBB0_471

.LBB0_510:
	s_and_b64 vcc, exec, s[4:5]
	s_cbranch_vccz .LBB0_498
	s_lshl_b32 s0, s11, 2
	s_lshr_b32 s1, s18, 4
	s_lshr_b32 s4, s11, 1
	s_and_b32 s0, s0, 4
	v_readlane_b32 s16, v254, 44
	s_or_b32 s19, s1, s0
	s_lshl_b32 s0, s4, 12
	v_readlane_b32 s17, v254, 45
	s_mov_b32 s31, s17
	s_add_i32 s30, s0, 0x2000
	s_lshl_b32 s0, s18, 8
	s_and_b32 s29, s0, 0xf00
	s_lshl_b64 s[0:1], s[30:31], 3
	s_or_b32 s0, s0, s19
	s_mul_i32 s5, s0, 0x180
	s_mul_hi_u32 s0, s0, 0x180
	s_mulk_i32 s1, 0x180
	s_or_b32 s20, s29, s30
	s_add_i32 s0, s0, s1
	v_readlane_b32 s25, v254, 38
	s_add_u32 s16, s25, s5
	v_readlane_b32 s26, v254, 39
	s_addc_u32 s17, s26, s0
	s_lshl_b64 s[0:1], s[30:31], 12
	v_readlane_b32 s27, v254, 40
	s_add_u32 s0, s27, s0
	v_readlane_b32 s28, v254, 41
	s_addc_u32 s1, s28, s1
	s_lshl_b32 s21, s19, 7
	s_lshl_b32 s18, s19, 8
	s_add_u32 s0, s0, s18
	s_addc_u32 s1, s1, 0
	s_add_u32 s23, s0, 0x800
	s_addc_u32 s24, s1, 0
	s_lshl_b32 s4, s4, 9
	s_add_i32 s30, s4, 0x6000
	s_lshl_b64 s[4:5], s[30:31], 3
	s_or_b32 s4, s4, s19
	s_mul_i32 s22, s4, 0x180
	s_mul_hi_u32 s4, s4, 0x180
	s_mulk_i32 s5, 0x180
	s_add_i32 s4, s4, s5
	s_add_u32 s25, s25, s22
	s_addc_u32 s26, s26, s4
	s_lshl_b64 s[4:5], s[30:31], 12
	s_add_u32 s4, s27, s4
	s_addc_u32 s5, s28, s5
	s_add_u32 s4, s4, s18
	s_addc_u32 s5, s5, 0
	s_add_u32 s27, s4, 0x800
	s_addc_u32 s28, s5, 0
	s_mul_i32 s5, s20, 0x8200
	s_mul_hi_u32 s4, s20, 0x8200
	s_add_u32 s18, s39, s5
	v_readlane_b32 s5, v254, 24
	s_addc_u32 s22, s5, s4
	s_mov_b32 s5, s31
	s_mul_i32 s30, s19, 0xc0
	v_writelane_b32 v254, s4, 44
	v_mov_b32_e32 v201, v0
	v_mov_b32_e32 v13, v3
	v_writelane_b32 v254, s5, 45
	s_lshl_b64 s[4:5], s[30:31], 1
	s_add_u32 s18, s18, s4
	v_readfirstlane_b32 s4, v201
	s_addc_u32 s19, s22, s5
	s_ashr_i32 s5, s4, 6
	v_and_b32_e32 v149, 31, v201
	s_lshl_b32 s22, s5, 5
	v_bfe_u32 v1, v201, 5, 1
	v_or_b32_e32 v2, s22, v149
	v_mov_b64_e32 v[4:5], s[18:19]
	v_mad_i64_i32 v[4:5], s[18:19], v2, s36, v[4:5]
	v_lshlrev_b32_e32 v2, 4, v1
	v_lshl_add_u64 v[4:5], v[4:5], 0, v[2:3]
	global_load_dwordx4 v[128:131], v[4:5], off offset:320
	global_load_dwordx4 v[140:143], v[4:5], off offset:352
	global_load_dwordx4 v[164:167], v[4:5], off offset:256
	global_load_dwordx4 v[172:175], v[4:5], off offset:288
	global_load_dwordx4 v[116:119], v[4:5], off
	global_load_dwordx4 v[120:123], v[4:5], off offset:32
	global_load_dwordx4 v[220:223], v[4:5], off offset:64
	global_load_dwordx4 v[212:215], v[4:5], off offset:96
	global_load_dwordx4 v[182:185], v[4:5], off offset:224
	global_load_dwordx4 v[186:189], v[4:5], off offset:192
	global_load_dwordx4 v[204:207], v[4:5], off offset:128
	global_load_dwordx4 v[190:193], v[4:5], off offset:160
	v_or_b32_e32 v14, s29, v149
	v_and_b32_e32 v12, 32, v201
	v_add_u32_e32 v126, s22, v14
	global_load_dwordx4 v[112:115], v12, s[42:43]
	global_load_dwordx4 v[100:103], v12, s[42:43] offset:16
	global_load_dwordx4 v[108:111], v12, s[42:43] offset:64
	global_load_dwordx4 v[104:107], v12, s[42:43] offset:80
	global_load_dwordx4 v[96:99], v12, s[42:43] offset:128
	global_load_dwordx4 v[92:95], v12, s[42:43] offset:144
	global_load_dwordx4 v[88:91], v12, s[42:43] offset:192
	global_load_dwordx4 v[84:87], v12, s[42:43] offset:208
	global_load_dwordx4 v[80:83], v12, s[42:43] offset:256
	global_load_dwordx4 v[76:79], v12, s[42:43] offset:272
	global_load_dwordx4 v[72:75], v12, s[42:43] offset:320
	global_load_dwordx4 v[68:71], v12, s[42:43] offset:336
	global_load_dwordx4 v[64:67], v12, s[42:43] offset:384
	global_load_dwordx4 v[60:63], v12, s[42:43] offset:400
	global_load_dwordx4 v[8:11], v12, s[42:43] offset:448
	global_load_dwordx4 v[4:7], v12, s[42:43] offset:464
	global_load_dwordx4 v[56:59], v12, s[42:43] offset:512
	global_load_dwordx4 v[52:55], v12, s[42:43] offset:528
	global_load_dwordx4 v[48:51], v12, s[42:43] offset:576
	global_load_dwordx4 v[44:47], v12, s[42:43] offset:592
	global_load_dwordx4 v[40:43], v12, s[42:43] offset:640
	global_load_dwordx4 v[36:39], v12, s[42:43] offset:656
	global_load_dwordx4 v[24:27], v12, s[42:43] offset:704
	global_load_dwordx4 v[20:23], v12, s[42:43] offset:720
	v_lshl_add_u64 v[124:125], s[12:13], 0, v[12:13]
	v_lshl_add_u64 v[170:171], s[14:15], 0, v[12:13]
	v_ashrrev_i32_e32 v12, 2, v126
	v_and_b32_e32 v12, -16, v12
	v_ashrrev_i32_e32 v13, 31, v12
	v_lshlrev_b32_e32 v126, 6, v126
	v_lshlrev_b64 v[16:17], 2, v[12:13]
	v_and_b32_e32 v178, 0xfc0, v126
	v_mov_b32_e32 v179, v3
	v_lshl_add_u64 v[18:19], v[124:125], 0, v[16:17]
	v_lshl_add_u64 v[180:181], v[124:125], 0, v[178:179]
	v_lshl_add_u64 v[32:33], v[170:171], 0, v[16:17]
	global_load_dwordx4 v[12:15], v[18:19], off offset:16
	global_load_dwordx4 v[28:31], v[18:19], off
	s_nop 0
	global_load_dwordx4 v[16:19], v[32:33], off offset:16
	s_nop 0
	global_load_dwordx4 v[32:35], v[32:33], off
	s_lshl_b32 s18, s5, 12
	v_and_b32_e32 v202, 63, v201
	s_add_i32 s18, s18, 0
	s_add_i32 s18, s18, 0x14800
	v_lshlrev_b32_e32 v203, 4, v202
	v_add_u32_e32 v200, s18, v203
	s_lshl_b32 s5, s5, 10
	s_add_i32 s29, s5, 0
	s_movk_i32 s5, 0x600
	s_add_i32 m0, s29, 0x8000
	s_mov_b64 s[18:19], 0x800
	s_add_i32 s30, s29, 0x10000
	s_and_b32 s4, s4, 0x3fffffc0
	s_lshl_b32 s4, s4, 2
	s_add_i32 s4, s4, 0
	s_add_i32 s4, s4, 0x14000
	s_waitcnt vmcnt(35)
	v_lshlrev_b32_e32 v232, 16, v118
	s_waitcnt vmcnt(34)
	v_lshlrev_b32_e32 v224, 16, v122
	s_waitcnt vmcnt(33)
	v_lshlrev_b32_e32 v216, 16, v222
	v_lshlrev_b32_e32 v126, 16, v131
	v_and_b32_e32 v127, 0xffff0000, v131
	v_lshlrev_b32_e32 v124, 16, v143
	v_and_b32_e32 v125, 0xffff0000, v143
	v_lshlrev_b32_e32 v136, 16, v130
	v_and_b32_e32 v137, 0xffff0000, v130
	v_lshlrev_b32_e32 v134, 16, v142
	v_and_b32_e32 v135, 0xffff0000, v142
	v_lshlrev_b32_e32 v144, 16, v129
	v_and_b32_e32 v145, 0xffff0000, v129
	v_lshlrev_b32_e32 v138, 16, v141
	v_and_b32_e32 v139, 0xffff0000, v141
	v_lshlrev_b32_e32 v150, 16, v128
	v_and_b32_e32 v151, 0xffff0000, v128
	v_lshlrev_b32_e32 v146, 16, v140
	v_and_b32_e32 v147, 0xffff0000, v140
	v_lshlrev_b32_e32 v154, 16, v167
	v_and_b32_e32 v155, 0xffff0000, v167
	v_lshlrev_b32_e32 v152, 16, v175
	v_and_b32_e32 v153, 0xffff0000, v175
	v_lshlrev_b32_e32 v158, 16, v166
	v_and_b32_e32 v159, 0xffff0000, v166
	v_lshlrev_b32_e32 v156, 16, v174
	v_and_b32_e32 v157, 0xffff0000, v174
	v_lshlrev_b32_e32 v162, 16, v165
	v_and_b32_e32 v163, 0xffff0000, v165
	v_lshlrev_b32_e32 v160, 16, v173
	v_and_b32_e32 v161, 0xffff0000, v173
	v_lshlrev_b32_e32 v166, 16, v164
	v_and_b32_e32 v167, 0xffff0000, v164
	v_lshlrev_b32_e32 v164, 16, v172
	v_and_b32_e32 v165, 0xffff0000, v172
	s_waitcnt vmcnt(31)
	v_lshlrev_b32_e32 v128, 16, v185
	v_and_b32_e32 v129, 0xffff0000, v185
	v_lshlrev_b32_e32 v130, 16, v183
	v_and_b32_e32 v131, 0xffff0000, v183
	v_lshlrev_b32_e32 v140, 16, v184
	v_and_b32_e32 v141, 0xffff0000, v184
	v_lshlrev_b32_e32 v142, 16, v182
	v_and_b32_e32 v143, 0xffff0000, v182
	s_waitcnt vmcnt(30)
	v_lshlrev_b32_e32 v168, 16, v189
	v_and_b32_e32 v169, 0xffff0000, v189
	v_lshlrev_b32_e32 v172, 16, v187
	v_and_b32_e32 v173, 0xffff0000, v187
	v_lshlrev_b32_e32 v174, 16, v188
	v_and_b32_e32 v175, 0xffff0000, v188
	v_lshlrev_b32_e32 v176, 16, v186
	v_and_b32_e32 v177, 0xffff0000, v186
	s_waitcnt vmcnt(28)
	v_lshlrev_b32_e32 v182, 16, v193
	v_and_b32_e32 v183, 0xffff0000, v193
	v_lshlrev_b32_e32 v184, 16, v191
	v_and_b32_e32 v185, 0xffff0000, v191
	v_lshlrev_b32_e32 v186, 16, v192
	v_and_b32_e32 v187, 0xffff0000, v192
	v_lshlrev_b32_e32 v188, 16, v190
	v_and_b32_e32 v189, 0xffff0000, v190
	v_lshlrev_b32_e32 v190, 16, v207
	v_and_b32_e32 v191, 0xffff0000, v207
	v_lshlrev_b32_e32 v192, 16, v205
	v_and_b32_e32 v193, 0xffff0000, v205
	v_lshlrev_b32_e32 v194, 16, v206
	v_and_b32_e32 v195, 0xffff0000, v206
	v_lshlrev_b32_e32 v196, 16, v204
	v_and_b32_e32 v197, 0xffff0000, v204
	v_lshlrev_b32_e32 v204, 16, v215
	v_and_b32_e32 v205, 0xffff0000, v215
	v_lshlrev_b32_e32 v206, 16, v213
	v_and_b32_e32 v207, 0xffff0000, v213
	v_lshlrev_b32_e32 v208, 16, v214
	v_and_b32_e32 v209, 0xffff0000, v214
	v_lshlrev_b32_e32 v210, 16, v212
	v_and_b32_e32 v211, 0xffff0000, v212
	v_lshlrev_b32_e32 v212, 16, v223
	v_and_b32_e32 v213, 0xffff0000, v223
	v_lshlrev_b32_e32 v214, 16, v221
	v_and_b32_e32 v215, 0xffff0000, v221
	v_and_b32_e32 v217, 0xffff0000, v222
	v_lshlrev_b32_e32 v218, 16, v220
	v_and_b32_e32 v219, 0xffff0000, v220
	v_lshlrev_b32_e32 v220, 16, v123
	v_and_b32_e32 v221, 0xffff0000, v123
	v_lshlrev_b32_e32 v222, 16, v121
	v_and_b32_e32 v223, 0xffff0000, v121
	v_and_b32_e32 v225, 0xffff0000, v122
	v_lshlrev_b32_e32 v122, 16, v120
	v_and_b32_e32 v123, 0xffff0000, v120
	v_lshlrev_b32_e32 v120, 16, v119
	v_and_b32_e32 v121, 0xffff0000, v119
	v_and_b32_e32 v119, 0xffff0000, v116
	v_and_b32_e32 v233, 0xffff0000, v118
	v_lshlrev_b32_e32 v118, 16, v116
	v_mul_f32_e32 v116, v119, v119
	v_lshlrev_b32_e32 v230, 16, v117
	v_and_b32_e32 v231, 0xffff0000, v117
	v_pk_fma_f32 v[116:117], v[118:119], v[118:119], v[116:117] op_sel_hi:[1,1,0]
	v_mul_f32_e32 v226, v231, v231
	v_pk_fma_f32 v[116:117], v[230:231], v[230:231], v[116:117]
	s_nop 0
	v_pk_add_f32 v[116:117], v[226:227], v[116:117] op_sel_hi:[0,1]
	v_pk_fma_f32 v[116:117], v[232:233], v[232:233], v[116:117]
	v_mul_f32_e32 v226, v233, v233
	v_pk_add_f32 v[116:117], v[226:227], v[116:117] op_sel_hi:[0,1]
	v_pk_fma_f32 v[116:117], v[120:121], v[120:121], v[116:117]
	v_mul_f32_e32 v226, v121, v121
	v_pk_add_f32 v[116:117], v[226:227], v[116:117] op_sel_hi:[0,1]
	v_pk_fma_f32 v[116:117], v[122:123], v[122:123], v[116:117]
	v_mul_f32_e32 v226, v123, v123
	v_pk_add_f32 v[116:117], v[226:227], v[116:117] op_sel_hi:[0,1]
	v_pk_fma_f32 v[116:117], v[222:223], v[222:223], v[116:117]
	v_mul_f32_e32 v226, v223, v223
	v_pk_add_f32 v[116:117], v[226:227], v[116:117] op_sel_hi:[0,1]
	v_pk_fma_f32 v[116:117], v[224:225], v[224:225], v[116:117]
	v_mul_f32_e32 v226, v225, v225
	v_pk_add_f32 v[116:117], v[226:227], v[116:117] op_sel_hi:[0,1]
	v_pk_fma_f32 v[116:117], v[220:221], v[220:221], v[116:117]
	v_mul_f32_e32 v226, v221, v221
	v_pk_add_f32 v[116:117], v[226:227], v[116:117] op_sel_hi:[0,1]
	v_pk_fma_f32 v[116:117], v[218:219], v[218:219], v[116:117]
	v_mul_f32_e32 v226, v219, v219
	v_pk_add_f32 v[116:117], v[226:227], v[116:117] op_sel_hi:[0,1]
	v_pk_fma_f32 v[116:117], v[214:215], v[214:215], v[116:117]
	v_mul_f32_e32 v226, v215, v215
	v_pk_add_f32 v[116:117], v[226:227], v[116:117] op_sel_hi:[0,1]
	v_pk_fma_f32 v[116:117], v[216:217], v[216:217], v[116:117]
	v_mul_f32_e32 v226, v217, v217
	v_pk_add_f32 v[116:117], v[226:227], v[116:117] op_sel_hi:[0,1]
	v_pk_fma_f32 v[116:117], v[212:213], v[212:213], v[116:117]
	v_mul_f32_e32 v226, v213, v213
	v_pk_add_f32 v[116:117], v[226:227], v[116:117] op_sel_hi:[0,1]
	v_pk_fma_f32 v[116:117], v[210:211], v[210:211], v[116:117]
	v_mul_f32_e32 v226, v211, v211
	v_pk_add_f32 v[116:117], v[226:227], v[116:117] op_sel_hi:[0,1]
	v_pk_fma_f32 v[116:117], v[206:207], v[206:207], v[116:117]
	v_mul_f32_e32 v226, v207, v207
	v_pk_add_f32 v[116:117], v[226:227], v[116:117] op_sel_hi:[0,1]
	v_pk_fma_f32 v[116:117], v[208:209], v[208:209], v[116:117]
	v_mul_f32_e32 v226, v209, v209
	v_pk_add_f32 v[116:117], v[226:227], v[116:117] op_sel_hi:[0,1]
	v_pk_fma_f32 v[116:117], v[204:205], v[204:205], v[116:117]
	v_mul_f32_e32 v226, v205, v205
	v_pk_add_f32 v[116:117], v[226:227], v[116:117] op_sel_hi:[0,1]
	v_pk_fma_f32 v[116:117], v[196:197], v[196:197], v[116:117]
	v_mul_f32_e32 v226, v197, v197
	v_pk_add_f32 v[116:117], v[226:227], v[116:117] op_sel_hi:[0,1]
	v_pk_fma_f32 v[116:117], v[192:193], v[192:193], v[116:117]
	v_mul_f32_e32 v226, v193, v193
	v_pk_add_f32 v[116:117], v[226:227], v[116:117] op_sel_hi:[0,1]
	v_pk_fma_f32 v[116:117], v[194:195], v[194:195], v[116:117]
	v_mul_f32_e32 v226, v195, v195
	v_pk_add_f32 v[116:117], v[226:227], v[116:117] op_sel_hi:[0,1]
	v_pk_fma_f32 v[116:117], v[190:191], v[190:191], v[116:117]
	v_mul_f32_e32 v226, v191, v191
	v_pk_add_f32 v[116:117], v[226:227], v[116:117] op_sel_hi:[0,1]
	v_pk_fma_f32 v[116:117], v[188:189], v[188:189], v[116:117]
	v_mul_f32_e32 v226, v189, v189
	v_pk_add_f32 v[116:117], v[226:227], v[116:117] op_sel_hi:[0,1]
	v_pk_fma_f32 v[116:117], v[184:185], v[184:185], v[116:117]
	v_mul_f32_e32 v226, v185, v185
	v_pk_add_f32 v[116:117], v[226:227], v[116:117] op_sel_hi:[0,1]
	v_pk_fma_f32 v[116:117], v[186:187], v[186:187], v[116:117]
	v_mul_f32_e32 v226, v187, v187
	v_pk_add_f32 v[116:117], v[226:227], v[116:117] op_sel_hi:[0,1]
	v_pk_fma_f32 v[116:117], v[182:183], v[182:183], v[116:117]
	v_mul_f32_e32 v226, v183, v183
	v_pk_add_f32 v[116:117], v[226:227], v[116:117] op_sel_hi:[0,1]
	v_pk_fma_f32 v[116:117], v[176:177], v[176:177], v[116:117]
	v_mul_f32_e32 v226, v177, v177
	v_pk_add_f32 v[116:117], v[226:227], v[116:117] op_sel_hi:[0,1]
	v_pk_fma_f32 v[116:117], v[172:173], v[172:173], v[116:117]
	v_mul_f32_e32 v226, v173, v173
	v_pk_add_f32 v[116:117], v[226:227], v[116:117] op_sel_hi:[0,1]
	v_pk_fma_f32 v[116:117], v[174:175], v[174:175], v[116:117]
	v_mul_f32_e32 v226, v175, v175
	v_pk_add_f32 v[116:117], v[226:227], v[116:117] op_sel_hi:[0,1]
	v_pk_fma_f32 v[116:117], v[168:169], v[168:169], v[116:117]
	v_mul_f32_e32 v226, v169, v169
	v_pk_add_f32 v[116:117], v[226:227], v[116:117] op_sel_hi:[0,1]
	v_pk_fma_f32 v[116:117], v[142:143], v[142:143], v[116:117]
	v_mul_f32_e32 v226, v143, v143
	v_pk_add_f32 v[116:117], v[226:227], v[116:117] op_sel_hi:[0,1]
	v_pk_fma_f32 v[116:117], v[130:131], v[130:131], v[116:117]
	v_mul_f32_e32 v226, v131, v131
	v_pk_add_f32 v[116:117], v[226:227], v[116:117] op_sel_hi:[0,1]
	v_pk_fma_f32 v[116:117], v[140:141], v[140:141], v[116:117]
	v_mul_f32_e32 v226, v141, v141
	v_pk_add_f32 v[116:117], v[226:227], v[116:117] op_sel_hi:[0,1]
	v_pk_fma_f32 v[116:117], v[128:129], v[128:129], v[116:117]
	v_mul_f32_e32 v226, v129, v129
	v_pk_add_f32 v[116:117], v[226:227], v[116:117] op_sel_hi:[0,1]
	v_pk_fma_f32 v[116:117], v[166:167], v[166:167], v[116:117]
	v_mul_f32_e32 v226, v167, v167
	v_pk_add_f32 v[116:117], v[226:227], v[116:117] op_sel_hi:[0,1]
	v_pk_fma_f32 v[116:117], v[162:163], v[162:163], v[116:117]
	v_mul_f32_e32 v226, v163, v163
	v_pk_add_f32 v[116:117], v[226:227], v[116:117] op_sel_hi:[0,1]
	v_pk_fma_f32 v[116:117], v[158:159], v[158:159], v[116:117]
	v_mul_f32_e32 v226, v159, v159
	v_pk_add_f32 v[116:117], v[226:227], v[116:117] op_sel_hi:[0,1]
	v_pk_fma_f32 v[116:117], v[154:155], v[154:155], v[116:117]
	v_mul_f32_e32 v226, v155, v155
	v_pk_add_f32 v[116:117], v[226:227], v[116:117] op_sel_hi:[0,1]
	v_pk_fma_f32 v[116:117], v[164:165], v[164:165], v[116:117]
	v_mul_f32_e32 v226, v165, v165
	v_pk_add_f32 v[116:117], v[226:227], v[116:117] op_sel_hi:[0,1]
	v_pk_fma_f32 v[116:117], v[160:161], v[160:161], v[116:117]
	v_mul_f32_e32 v226, v161, v161
	v_pk_add_f32 v[116:117], v[226:227], v[116:117] op_sel_hi:[0,1]
	v_pk_fma_f32 v[116:117], v[156:157], v[156:157], v[116:117]
	v_mul_f32_e32 v226, v157, v157
	v_pk_add_f32 v[116:117], v[226:227], v[116:117] op_sel_hi:[0,1]
	v_pk_fma_f32 v[116:117], v[152:153], v[152:153], v[116:117]
	v_mul_f32_e32 v226, v153, v153
	v_pk_add_f32 v[116:117], v[226:227], v[116:117] op_sel_hi:[0,1]
	v_pk_fma_f32 v[116:117], v[150:151], v[150:151], v[116:117]
	v_mul_f32_e32 v226, v151, v151
	v_pk_add_f32 v[116:117], v[226:227], v[116:117] op_sel_hi:[0,1]
	v_pk_fma_f32 v[116:117], v[144:145], v[144:145], v[116:117]
	v_mul_f32_e32 v226, v145, v145
	v_pk_add_f32 v[116:117], v[226:227], v[116:117] op_sel_hi:[0,1]
	v_pk_fma_f32 v[116:117], v[136:137], v[136:137], v[116:117]
	v_mul_f32_e32 v226, v137, v137
	v_pk_add_f32 v[116:117], v[226:227], v[116:117] op_sel_hi:[0,1]
	v_pk_fma_f32 v[116:117], v[126:127], v[126:127], v[116:117]
	v_mul_f32_e32 v226, v127, v127
	v_pk_add_f32 v[116:117], v[226:227], v[116:117] op_sel_hi:[0,1]
	v_pk_fma_f32 v[116:117], v[146:147], v[146:147], v[116:117]
	v_mul_f32_e32 v226, v147, v147
	v_pk_add_f32 v[116:117], v[226:227], v[116:117] op_sel_hi:[0,1]
	v_pk_fma_f32 v[116:117], v[138:139], v[138:139], v[116:117]
	v_mul_f32_e32 v226, v139, v139
	v_pk_add_f32 v[116:117], v[226:227], v[116:117] op_sel_hi:[0,1]
	v_pk_fma_f32 v[116:117], v[134:135], v[134:135], v[116:117]
	v_mul_f32_e32 v226, v135, v135
	v_pk_add_f32 v[116:117], v[226:227], v[116:117] op_sel_hi:[0,1]
	v_pk_fma_f32 v[116:117], v[124:125], v[124:125], v[116:117]
	v_mul_f32_e32 v226, v125, v125
	v_pk_add_f32 v[116:117], v[226:227], v[116:117] op_sel_hi:[0,1]
	v_mov_b32_e32 v117, v116
	s_nop 1
	v_permlane32_swap_b32_e32 v116, v117
	v_add_f32_e32 v116, v116, v117
	v_fmamk_f32 v116, v116, 0x3baaaaab, v198
	v_mul_f32_e32 v117, 0x4b800000, v116
	v_cmp_gt_f32_e32 vcc, s38, v116
	s_nop 1
	v_cndmask_b32_e32 v116, v116, v117, vcc
	v_rsq_f32_e32 v234, v116
	v_lshl_add_u64 v[116:117], v[170:171], 0, v[178:179]
	global_load_dwordx4 v[226:229], v[180:181], off offset:16
	s_nop 0
	global_load_dwordx4 v[178:181], v[180:181], off
	v_mul_f32_e32 v170, 0x45800000, v234
	v_cndmask_b32_e32 v170, v234, v170, vcc
	v_pk_mul_f32 v[118:119], v[170:171], v[118:119] op_sel_hi:[0,1]
	s_waitcnt vmcnt(29)
	v_pk_mul_f32 v[112:113], v[112:113], v[118:119]
	v_pk_mul_f32 v[118:119], v[170:171], v[230:231] op_sel_hi:[0,1]
	v_pk_mul_f32 v[114:115], v[114:115], v[118:119]
	v_pk_mul_f32 v[118:119], v[170:171], v[232:233] op_sel_hi:[0,1]
	global_load_dwordx4 v[230:233], v[116:117], off offset:16
	global_load_dwordx4 v[240:243], v[116:117], off
	s_waitcnt vmcnt(30)
	v_pk_mul_f32 v[118:119], v[100:101], v[118:119]
	v_pk_mul_f32 v[100:101], v[170:171], v[120:121] op_sel_hi:[0,1]
	v_pk_mul_f32 v[120:121], v[102:103], v[100:101]
	v_cvt_pk_bf16_f32 v100, v112, v113
	v_pk_mul_f32 v[112:113], v[170:171], v[122:123] op_sel_hi:[0,1]
	s_waitcnt vmcnt(29)
	v_pk_mul_f32 v[108:109], v[108:109], v[112:113]
	v_pk_mul_f32 v[112:113], v[170:171], v[224:225] op_sel_hi:[0,1]
	s_waitcnt vmcnt(28)
	v_pk_mul_f32 v[112:113], v[104:105], v[112:113]
	v_pk_mul_f32 v[104:105], v[170:171], v[222:223] op_sel_hi:[0,1]
	v_pk_mul_f32 v[110:111], v[110:111], v[104:105]
	v_pk_mul_f32 v[104:105], v[170:171], v[220:221] op_sel_hi:[0,1]
	v_cvt_pk_bf16_f32 v101, v114, v115
	v_pk_mul_f32 v[114:115], v[106:107], v[104:105]
	v_cvt_pk_bf16_f32 v104, v108, v109
	v_pk_mul_f32 v[108:109], v[170:171], v[218:219] op_sel_hi:[0,1]
	s_waitcnt vmcnt(27)
	v_pk_mul_f32 v[96:97], v[96:97], v[108:109]
	v_pk_mul_f32 v[108:109], v[170:171], v[216:217] op_sel_hi:[0,1]
	s_waitcnt vmcnt(26)
	v_pk_mul_f32 v[92:93], v[92:93], v[108:109]
	v_cvt_pk_bf16_f32 v105, v110, v111
	v_cvt_pk_bf16_f32 v110, v92, v93
	v_pk_mul_f32 v[92:93], v[170:171], v[210:211] op_sel_hi:[0,1]
	s_waitcnt vmcnt(25)
	v_pk_mul_f32 v[88:89], v[88:89], v[92:93]
	v_pk_mul_f32 v[92:93], v[170:171], v[208:209] op_sel_hi:[0,1]
	s_waitcnt vmcnt(24)
	v_pk_mul_f32 v[84:85], v[84:85], v[92:93]
	v_cvt_pk_bf16_f32 v107, v114, v115
	v_cvt_pk_bf16_f32 v114, v84, v85
	v_pk_mul_f32 v[84:85], v[170:171], v[196:197] op_sel_hi:[0,1]
	s_waitcnt vmcnt(23)
	v_pk_mul_f32 v[80:81], v[80:81], v[84:85]
	v_pk_mul_f32 v[84:85], v[170:171], v[194:195] op_sel_hi:[0,1]
	s_waitcnt vmcnt(22)
	v_pk_mul_f32 v[76:77], v[76:77], v[84:85]
	v_cvt_pk_bf16_f32 v102, v118, v119
	v_cvt_pk_bf16_f32 v118, v76, v77
	v_pk_mul_f32 v[76:77], v[170:171], v[188:189] op_sel_hi:[0,1]
	s_waitcnt vmcnt(21)
	v_pk_mul_f32 v[72:73], v[76:77], v[72:73]
	v_pk_mul_f32 v[76:77], v[170:171], v[186:187] op_sel_hi:[0,1]
	s_waitcnt vmcnt(20)
	v_pk_mul_f32 v[68:69], v[76:77], v[68:69]
	v_pk_mul_f32 v[108:109], v[170:171], v[214:215] op_sel_hi:[0,1]
	v_cvt_pk_bf16_f32 v122, v68, v69
	v_pk_mul_f32 v[68:69], v[170:171], v[176:177] op_sel_hi:[0,1]
	s_waitcnt vmcnt(19)
	v_pk_mul_f32 v[64:65], v[68:69], v[64:65]
	v_pk_mul_f32 v[68:69], v[170:171], v[174:175] op_sel_hi:[0,1]
	s_waitcnt vmcnt(18)
	v_pk_mul_f32 v[60:61], v[68:69], v[60:61]
	v_pk_mul_f32 v[68:69], v[170:171], v[172:173] op_sel_hi:[0,1]
	v_pk_mul_f32 v[66:67], v[68:69], v[66:67]
	v_pk_mul_f32 v[68:69], v[170:171], v[168:169] op_sel_hi:[0,1]
	v_pk_mul_f32 v[62:63], v[68:69], v[62:63]
	v_pk_mul_f32 v[68:69], v[170:171], v[166:167] op_sel_hi:[0,1]
	s_waitcnt vmcnt(15)
	v_pk_mul_f32 v[56:57], v[68:69], v[56:57]
	v_pk_mul_f32 v[68:69], v[170:171], v[158:159] op_sel_hi:[0,1]
	s_waitcnt vmcnt(14)
	v_pk_mul_f32 v[52:53], v[68:69], v[52:53]
	v_pk_mul_f32 v[68:69], v[170:171], v[162:163] op_sel_hi:[0,1]
	v_pk_mul_f32 v[58:59], v[68:69], v[58:59]
	v_pk_mul_f32 v[68:69], v[170:171], v[154:155] op_sel_hi:[0,1]
	v_pk_mul_f32 v[54:55], v[68:69], v[54:55]
	v_pk_mul_f32 v[68:69], v[170:171], v[164:165] op_sel_hi:[0,1]
	s_waitcnt vmcnt(13)
	v_pk_mul_f32 v[48:49], v[68:69], v[48:49]
	v_pk_mul_f32 v[68:69], v[170:171], v[156:157] op_sel_hi:[0,1]
	s_waitcnt vmcnt(12)
	v_pk_mul_f32 v[44:45], v[68:69], v[44:45]
	v_pk_mul_f32 v[68:69], v[170:171], v[160:161] op_sel_hi:[0,1]
	v_pk_mul_f32 v[50:51], v[68:69], v[50:51]
	v_pk_mul_f32 v[68:69], v[170:171], v[152:153] op_sel_hi:[0,1]
	v_pk_mul_f32 v[46:47], v[68:69], v[46:47]
	v_pk_mul_f32 v[68:69], v[170:171], v[150:151] op_sel_hi:[0,1]
	s_waitcnt vmcnt(11)
	v_pk_mul_f32 v[40:41], v[68:69], v[40:41]
	v_pk_mul_f32 v[68:69], v[170:171], v[136:137] op_sel_hi:[0,1]
	s_waitcnt vmcnt(10)
	v_pk_mul_f32 v[36:37], v[68:69], v[36:37]
	v_pk_mul_f32 v[68:69], v[170:171], v[144:145] op_sel_hi:[0,1]
	v_pk_mul_f32 v[42:43], v[68:69], v[42:43]
	v_pk_mul_f32 v[68:69], v[170:171], v[126:127] op_sel_hi:[0,1]
	v_pk_mul_f32 v[38:39], v[68:69], v[38:39]
	v_pk_mul_f32 v[68:69], v[170:171], v[146:147] op_sel_hi:[0,1]
	s_waitcnt vmcnt(9)
	v_pk_mul_f32 v[24:25], v[68:69], v[24:25]
	v_pk_mul_f32 v[68:69], v[170:171], v[134:135] op_sel_hi:[0,1]
	s_waitcnt vmcnt(8)
	v_pk_mul_f32 v[20:21], v[68:69], v[20:21]
	v_pk_mul_f32 v[68:69], v[170:171], v[138:139] op_sel_hi:[0,1]
	v_pk_mul_f32 v[26:27], v[68:69], v[26:27]
	v_pk_mul_f32 v[68:69], v[170:171], v[124:125] op_sel_hi:[0,1]
	v_pk_mul_f32 v[22:23], v[68:69], v[22:23]
	s_waitcnt vmcnt(4)
	v_pk_mul_f32 v[68:69], v[56:57], v[32:33]
	v_pk_mul_f32 v[32:33], v[48:49], v[32:33]
	v_pk_fma_f32 v[68:69], v[48:49], v[28:29], v[68:69]
	v_pk_fma_f32 v[28:29], v[56:57], v[28:29], v[32:33] neg_lo:[0,0,1] neg_hi:[0,0,1]
	v_pk_mul_f32 v[32:33], v[58:59], v[34:35]
	v_pk_mul_f32 v[34:35], v[50:51], v[34:35]
	v_pk_fma_f32 v[32:33], v[50:51], v[30:31], v[32:33]
	v_pk_fma_f32 v[30:31], v[58:59], v[30:31], v[34:35] neg_lo:[0,0,1] neg_hi:[0,0,1]
	v_pk_mul_f32 v[34:35], v[52:53], v[16:17]
	v_pk_mul_f32 v[16:17], v[44:45], v[16:17]
	v_pk_fma_f32 v[34:35], v[44:45], v[12:13], v[34:35]
	v_pk_fma_f32 v[16:17], v[52:53], v[12:13], v[16:17] neg_lo:[0,0,1] neg_hi:[0,0,1]
	v_pk_mul_f32 v[12:13], v[54:55], v[18:19]
	v_pk_mul_f32 v[92:93], v[170:171], v[206:207] op_sel_hi:[0,1]
	v_pk_fma_f32 v[44:45], v[46:47], v[14:15], v[12:13]
	v_pk_mul_f32 v[12:13], v[46:47], v[18:19]
	v_pk_mul_f32 v[84:85], v[170:171], v[192:193] op_sel_hi:[0,1]
	v_pk_fma_f32 v[18:19], v[54:55], v[14:15], v[12:13] neg_lo:[0,0,1] neg_hi:[0,0,1]
	s_waitcnt vmcnt(0)
	v_pk_mul_f32 v[12:13], v[40:41], v[240:241]
	v_cvt_pk_bf16_f32 v14, v16, v17
	v_pk_fma_f32 v[46:47], v[24:25], v[178:179], v[12:13]
	v_pk_mul_f32 v[12:13], v[24:25], v[240:241]
	v_cvt_pk_bf16_f32 v15, v18, v19
	v_pk_fma_f32 v[24:25], v[40:41], v[178:179], v[12:13] neg_lo:[0,0,1] neg_hi:[0,0,1]
	v_pk_mul_f32 v[12:13], v[42:43], v[242:243]
	v_lshlrev_b32_e32 v19, 3, v201
	v_pk_fma_f32 v[40:41], v[26:27], v[180:181], v[12:13]
	v_pk_mul_f32 v[12:13], v[26:27], v[242:243]
	v_pk_mul_f32 v[76:77], v[170:171], v[184:185] op_sel_hi:[0,1]
	v_pk_fma_f32 v[26:27], v[42:43], v[180:181], v[12:13] neg_lo:[0,0,1] neg_hi:[0,0,1]
	v_pk_mul_f32 v[12:13], v[36:37], v[230:231]
	v_add_u32_e32 v154, s4, v2
	v_pk_fma_f32 v[42:43], v[20:21], v[226:227], v[12:13]
	v_pk_mul_f32 v[12:13], v[20:21], v[230:231]
	v_pk_mul_f32 v[98:99], v[98:99], v[108:109]
	v_pk_fma_f32 v[20:21], v[36:37], v[226:227], v[12:13] neg_lo:[0,0,1] neg_hi:[0,0,1]
	v_pk_mul_f32 v[12:13], v[38:39], v[232:233]
	v_pk_mul_f32 v[108:109], v[170:171], v[212:213] op_sel_hi:[0,1]
	v_pk_fma_f32 v[36:37], v[22:23], v[228:229], v[12:13]
	v_pk_mul_f32 v[12:13], v[22:23], v[232:233]
	v_pk_mul_f32 v[90:91], v[90:91], v[92:93]
	v_pk_fma_f32 v[22:23], v[38:39], v[228:229], v[12:13] neg_lo:[0,0,1] neg_hi:[0,0,1]
	v_cvt_pk_bf16_f32 v12, v28, v29
	v_cvt_pk_bf16_f32 v13, v30, v31
	ds_write_b128 v200, v[12:15]
	v_cvt_pk_bf16_f32 v12, v68, v69
	v_cvt_pk_bf16_f32 v13, v32, v33
	v_cvt_pk_bf16_f32 v14, v34, v35
	v_cvt_pk_bf16_f32 v15, v44, v45
	ds_write_b128 v200, v[12:15] offset:1024
	v_cvt_pk_bf16_f32 v12, v24, v25
	v_cvt_pk_bf16_f32 v13, v26, v27
	v_cvt_pk_bf16_f32 v14, v20, v21
	v_cvt_pk_bf16_f32 v15, v22, v23
	ds_write_b128 v200, v[12:15] offset:2048
	v_cvt_pk_bf16_f32 v12, v46, v47
	v_cvt_pk_bf16_f32 v13, v40, v41
	v_cvt_pk_bf16_f32 v14, v42, v43
	v_cvt_pk_bf16_f32 v15, v36, v37
	ds_write_b128 v200, v[12:15] offset:3072
	v_bfe_u32 v12, v201, 2, 2
	v_lshrrev_b32_e32 v14, 1, v201
	v_ashrrev_i32_e32 v15, 4, v201
	v_and_or_b32 v14, v14, 8, v12
	v_and_b32_e32 v12, 0x60, v201
	v_lshrrev_b32_e32 v16, 1, v15
	v_and_or_b32 v18, v19, 24, v12
	v_and_b32_e32 v12, -16, v15
	v_and_b32_e32 v16, 4, v16
	v_or3_b32 v12, v16, v12, v14
	v_add_u32_e32 v16, 0x200, v201
	v_ashrrev_i32_e32 v24, 4, v16
	v_and_b32_e32 v13, 15, v201
	v_lshrrev_b32_e32 v16, 1, v24
	v_bitop3_b32 v21, v15, v13, 7 bitop3:0x6c
	v_bitop3_b32 v26, v24, v13, 7 bitop3:0x6c
	v_and_b32_e32 v13, -16, v24
	v_and_b32_e32 v16, 4, v16
	v_ashrrev_i32_e32 v27, 3, v201
	v_mul_i32_i24_sdwa v134, sext(v15), s5 dst_sel:DWORD dst_unused:UNUSED_PAD src0_sel:WORD_0 src1_sel:DWORD
	v_or3_b32 v14, v16, v13, v14
	v_xor_b32_e32 v13, v27, v201
	v_ashrrev_i32_e32 v135, 31, v134
	v_lshlrev_b32_e32 v13, 3, v13
	v_lshl_add_u64 v[16:17], v[134:135], 1, s[16:17]
	v_lshlrev_b32_e32 v22, 4, v21
	v_mov_b32_e32 v23, v3
	v_and_b32_e32 v20, 56, v13
	v_lshl_add_u64 v[16:17], v[16:17], 0, v[22:23]
	v_ashrrev_i32_e32 v13, 31, v12
	global_load_lds_dwordx4 v[16:17], off
	v_lshlrev_b64 v[16:17], 12, v[12:13]
	v_lshl_add_u64 v[16:17], s[0:1], 0, v[16:17]
	v_lshlrev_b32_e32 v22, 1, v18
	v_lshl_add_u64 v[16:17], v[16:17], 0, v[22:23]
	v_mul_i32_i24_sdwa v136, sext(v24), s5 dst_sel:DWORD dst_unused:UNUSED_PAD src0_sel:WORD_0 src1_sel:DWORD
	v_lshl_add_u64 v[16:17], v[16:17], 0, s[18:19]
	s_mov_b32 m0, s29
	v_ashrrev_i32_e32 v137, 31, v136
	global_load_lds_dwordx4 v[16:17], off
	v_lshl_add_u64 v[16:17], v[136:137], 1, s[16:17]
	v_lshlrev_b32_e32 v24, 4, v26
	v_mov_b32_e32 v25, v3
	v_lshl_add_u64 v[16:17], v[16:17], 0, v[24:25]
	s_add_i32 m0, s29, 0xa000
	v_ashrrev_i32_e32 v15, 31, v14
	global_load_lds_dwordx4 v[16:17], off
	v_lshlrev_b64 v[16:17], 12, v[14:15]
	v_lshl_add_u64 v[16:17], s[0:1], 0, v[16:17]
	v_lshl_add_u64 v[16:17], v[16:17], 0, v[22:23]
	v_mul_i32_i24_sdwa v138, sext(v27), s5 dst_sel:DWORD dst_unused:UNUSED_PAD src0_sel:WORD_0 src1_sel:DWORD
	v_lshl_add_u64 v[16:17], v[16:17], 0, s[18:19]
	s_add_i32 m0, s29, 0x2000
	v_ashrrev_i32_e32 v139, 31, v138
	global_load_lds_dwordx4 v[16:17], off
	v_lshl_add_u64 v[16:17], v[138:139], 1, s[16:17]
	v_lshlrev_b32_e32 v22, 1, v20
	v_lshl_add_u64 v[16:17], v[16:17], 0, v[22:23]
	s_mov_b64 s[0:1], 0x100
	v_lshl_add_u64 v[16:17], v[16:17], 0, s[0:1]
	s_mov_b32 m0, s30
	v_lshlrev_b32_e32 v22, 3, v21
	global_load_lds_dwordx4 v[16:17], off
	v_pk_mul_f32 v[16:17], v[170:171], v[142:143] op_sel_hi:[0,1]
	v_pk_mul_f32 v[8:9], v[16:17], v[8:9]
	v_pk_mul_f32 v[16:17], v[170:171], v[140:141] op_sel_hi:[0,1]
	v_pk_mul_f32 v[4:5], v[16:17], v[4:5]
	v_pk_mul_f32 v[16:17], v[170:171], v[130:131] op_sel_hi:[0,1]
	v_pk_mul_f32 v[10:11], v[16:17], v[10:11]
	v_pk_mul_f32 v[16:17], v[170:171], v[128:129] op_sel_hi:[0,1]
	v_pk_mul_f32 v[6:7], v[16:17], v[6:7]
	v_cvt_pk_bf16_f32 v130, v4, v5
	v_cvt_pk_bf16_f32 v131, v6, v7
	v_lshlrev_b32_e32 v4, 1, v201
	v_lshlrev_b32_e32 v6, 4, v201
	v_and_b32_e32 v4, 32, v4
	v_and_b32_e32 v7, 0x70, v6
	v_lshlrev_b32_e32 v24, 3, v26
	v_and_b32_e32 v5, 0xc0, v203
	v_bitop3_b32 v156, v2, v6, s89 bitop3:0x78
	v_bitop3_b32 v157, v2, v7, 32 bitop3:0x36
	v_bitop3_b32 v158, v2, v7, 64 bitop3:0x36
	v_bitop3_b32 v160, v2, v7, s83 bitop3:0x36
	v_bitop3_b32 v161, v2, v7, s86 bitop3:0x36
	v_bitop3_b32 v162, v2, v7, s88 bitop3:0x36
	v_bitop3_b32 v163, v2, v7, s87 bitop3:0x36
	v_bitop3_b32 v164, v2, v7, s90 bitop3:0x36
	v_and_or_b32 v2, v19, s91, v4
	v_mov_b32_e32 v16, v3
	v_mov_b32_e32 v17, v3
	v_pk_mul_f32 v[92:93], v[170:171], v[204:205] op_sel_hi:[0,1]
	v_pk_mul_f32 v[82:83], v[82:83], v[84:85]
	v_pk_mul_f32 v[84:85], v[170:171], v[190:191] op_sel_hi:[0,1]
	v_pk_mul_f32 v[74:75], v[76:77], v[74:75]
	v_pk_mul_f32 v[76:77], v[170:171], v[182:183] op_sel_hi:[0,1]
	v_cvt_pk_bf16_f32 v124, v64, v65
	v_cvt_pk_bf16_f32 v125, v66, v67
	v_cvt_pk_bf16_f32 v126, v60, v61
	v_cvt_pk_bf16_f32 v127, v62, v63
	v_cvt_pk_bf16_f32 v128, v8, v9
	v_cvt_pk_bf16_f32 v129, v10, v11
	v_lshlrev_b64 v[140:141], 11, v[12:13]
	v_lshlrev_b64 v[142:143], 11, v[14:15]
	s_waitcnt vmcnt(0)
	v_add3_u32 v166, v5, 0, v2
	v_mov_b32_e32 v2, v3
	v_mov_b32_e32 v4, v3
	v_mov_b32_e32 v5, v3
	v_mov_b32_e32 v6, v3
	v_mov_b32_e32 v7, v3
	v_mov_b32_e32 v8, v3
	v_mov_b32_e32 v9, v3
	v_mov_b32_e32 v10, v3
	v_mov_b32_e32 v11, v3
	v_mov_b32_e32 v12, v3
	v_mov_b32_e32 v13, v3
	v_mov_b32_e32 v14, v3
	v_mov_b32_e32 v15, v3
	v_lshlrev_b32_e32 v144, 1, v22
	v_lshlrev_b32_e32 v150, 1, v24
	v_lshlrev_b32_e32 v152, 1, v20
	v_mov_b64_e32 v[66:67], v[16:17]
	v_mov_b64_e32 v[50:51], v[16:17]
	v_mov_b64_e32 v[34:35], v[16:17]
	v_pk_mul_f32 v[94:95], v[94:95], v[108:109]
	v_pk_mul_f32 v[86:87], v[86:87], v[92:93]
	v_pk_mul_f32 v[78:79], v[78:79], v[84:85]
	v_pk_mul_f32 v[70:71], v[76:77], v[70:71]
	v_lshlrev_b32_e32 v146, 1, v18
	v_mov_b64_e32 v[64:65], v[14:15]
	v_mov_b64_e32 v[62:63], v[12:13]
	v_mov_b64_e32 v[60:61], v[10:11]
	v_mov_b64_e32 v[58:59], v[8:9]
	v_mov_b64_e32 v[56:57], v[6:7]
	v_mov_b64_e32 v[54:55], v[4:5]
	v_mov_b64_e32 v[52:53], v[2:3]
	v_mov_b64_e32 v[48:49], v[14:15]
	v_mov_b64_e32 v[46:47], v[12:13]
	v_mov_b64_e32 v[44:45], v[10:11]
	v_mov_b64_e32 v[42:43], v[8:9]
	v_mov_b64_e32 v[40:41], v[6:7]
	v_mov_b64_e32 v[38:39], v[4:5]
	v_mov_b64_e32 v[36:37], v[2:3]
	v_mov_b64_e32 v[32:33], v[14:15]
	v_mov_b64_e32 v[30:31], v[12:13]
	v_mov_b64_e32 v[28:29], v[10:11]
	v_mov_b64_e32 v[26:27], v[8:9]
	v_mov_b64_e32 v[24:25], v[6:7]
	v_mov_b64_e32 v[22:23], v[4:5]
	v_mov_b64_e32 v[20:21], v[2:3]
	v_mov_b64_e32 v[18:19], v[16:17]
	v_cvt_pk_bf16_f32 v103, v120, v121
	v_cvt_pk_bf16_f32 v106, v112, v113
	v_cvt_pk_bf16_f32 v108, v96, v97
	v_cvt_pk_bf16_f32 v109, v98, v99
	v_cvt_pk_bf16_f32 v111, v94, v95
	v_cvt_pk_bf16_f32 v112, v88, v89
	v_cvt_pk_bf16_f32 v113, v90, v91
	v_cvt_pk_bf16_f32 v115, v86, v87
	v_cvt_pk_bf16_f32 v116, v80, v81
	v_cvt_pk_bf16_f32 v117, v82, v83
	v_cvt_pk_bf16_f32 v119, v78, v79
	v_cvt_pk_bf16_f32 v120, v72, v73
	v_cvt_pk_bf16_f32 v121, v74, v75
	v_cvt_pk_bf16_f32 v123, v70, v71
	v_lshlrev_b32_e32 v155, 8, v149
	v_lshlrev_b32_e32 v165, 7, v149
	v_cmp_gt_u32_e64 s[0:1], 32, v202
	v_lshl_add_u32 v159, v149, 2, s4
	s_mov_b32 s19, 0
	v_mov_b32_e32 v168, 0
	v_mov_b32_e32 v167, 0xf149f2ca
	v_mov_b64_e32 v[16:17], v[14:15]
	v_mov_b64_e32 v[14:15], v[12:13]
	v_mov_b64_e32 v[12:13], v[10:11]
	v_mov_b64_e32 v[10:11], v[8:9]
	v_mov_b64_e32 v[8:9], v[6:7]
	v_mov_b64_e32 v[6:7], v[4:5]
	v_mov_b64_e32 v[4:5], v[2:3]
	s_waitcnt vmcnt(0) lgkmcnt(0)
	s_barrier
	ds_read_b128 v[186:189], v200
	ds_read_b128 v[190:193], v200 offset:1024
	ds_read_b128 v[194:197], v200 offset:2048
	ds_read_b128 v[204:207], v200 offset:3072
	s_waitcnt lgkmcnt(0)
	s_and_b32 s18, s19, 1
	s_cmpk_lt_u32 s19, 0x47
	s_mov_b64 s[4:5], -1
	s_cbranch_scc1 .LBB0_514
	s_branch .LBB0_513

.LBB0_516:
	s_add_i32 s4, s33, 0
	s_add_i32 s5, s34, 0
	s_add_i32 s5, s5, 0x10000
	v_add3_u32 v2, s4, v156, v155
	v_add3_u32 v145, s4, v157, v155
	ds_read_b128 v[170:173], v2 offset:40960
	ds_read_b128 v[174:177], v145 offset:40960
	ds_read_b128 v[178:181], v145 offset:32768
	ds_read_b128 v[182:185], v2 offset:32768
	s_waitcnt lgkmcnt(2)
	v_mfma_f32_32x32x16_bf16 v[68:83], v[170:173], v[100:103], 0
	v_mfma_f32_32x32x16_bf16 v[68:83], v[174:177], v[104:107], v[68:83]
	v_add3_u32 v2, s4, v158, v155
	v_add3_u32 v145, s4, v160, v155
	ds_read_b128 v[170:173], v2 offset:32768
	ds_read_b128 v[174:177], v145 offset:32768
	s_waitcnt lgkmcnt(2)
	v_mfma_f32_32x32x16_bf16 v[84:99], v[178:181], v[104:107], 0
	v_mfma_f32_32x32x16_bf16 v[84:99], v[182:185], v[100:103], v[84:99]
	ds_read_b128 v[178:181], v145 offset:40960
	ds_read_b128 v[182:185], v2 offset:40960
	s_waitcnt lgkmcnt(2)
	v_mfma_f32_32x32x16_bf16 v[84:99], v[170:173], v[108:111], v[84:99]
	v_mfma_f32_32x32x16_bf16 v[84:99], v[174:177], v[112:115], v[84:99]
	v_add3_u32 v2, s4, v161, v155
	v_add3_u32 v145, s4, v162, v155
	ds_read_b128 v[170:173], v2 offset:40960
	ds_read_b128 v[174:177], v145 offset:40960
	s_waitcnt lgkmcnt(2)
	v_mfma_f32_32x32x16_bf16 v[68:83], v[178:181], v[112:115], v[68:83]
	v_mfma_f32_32x32x16_bf16 v[68:83], v[182:185], v[108:111], v[68:83]
	ds_read_b128 v[178:181], v145 offset:32768
	ds_read_b128 v[182:185], v2 offset:32768
	s_waitcnt lgkmcnt(2)
	v_mfma_f32_32x32x16_bf16 v[68:83], v[170:173], v[116:119], v[68:83]
	v_mfma_f32_32x32x16_bf16 v[68:83], v[174:177], v[120:123], v[68:83]
	v_add3_u32 v2, s4, v163, v155
	v_add3_u32 v145, s4, v164, v155
	ds_read_b128 v[170:173], v2 offset:32768
	ds_read_b128 v[174:177], v145 offset:32768
	s_waitcnt lgkmcnt(2)
	v_mfma_f32_32x32x16_bf16 v[84:99], v[178:181], v[120:123], v[84:99]
	v_mfma_f32_32x32x16_bf16 v[84:99], v[182:185], v[116:119], v[84:99]
	ds_read_b128 v[178:181], v145 offset:40960
	ds_read_b128 v[182:185], v2 offset:40960
	s_waitcnt lgkmcnt(2)
	v_mfma_f32_32x32x16_bf16 v[84:99], v[170:173], v[124:127], v[84:99]
	v_mfma_f32_32x32x16_bf16 v[84:99], v[174:177], v[128:131], v[84:99]
	v_add3_u32 v2, s5, v156, v165
	v_add3_u32 v145, s5, v157, v165
	ds_read_b128 v[170:173], v2 offset:4096
	ds_read_b128 v[174:177], v145 offset:4096
	s_waitcnt lgkmcnt(2)
	v_mfma_f32_32x32x16_bf16 v[68:83], v[178:181], v[128:131], v[68:83]
	v_mfma_f32_32x32x16_bf16 v[68:83], v[182:185], v[124:127], v[68:83]
	ds_read_b128 v[178:181], v145
	ds_read_b128 v[182:185], v2
	s_waitcnt lgkmcnt(2)
	v_mfma_f32_32x32x16_bf16 v[68:83], v[170:173], v[186:189], v[68:83]
	v_mfma_f32_32x32x16_bf16 v[68:83], v[174:177], v[190:193], v[68:83]
	v_add3_u32 v2, s5, v158, v165
	v_add3_u32 v145, s5, v160, v165
	ds_read_b128 v[170:173], v2
	ds_read_b128 v[174:177], v145
	s_waitcnt lgkmcnt(2)
	v_mfma_f32_32x32x16_bf16 v[84:99], v[178:181], v[190:193], v[84:99]
	v_mfma_f32_32x32x16_bf16 v[84:99], v[182:185], v[186:189], v[84:99]
	ds_read_b128 v[178:181], v145 offset:4096
	ds_read_b128 v[182:185], v2 offset:4096
	s_waitcnt lgkmcnt(2)
	v_mfma_f32_32x32x16_bf16 v[84:99], v[170:173], v[194:197], v[84:99]
	v_mfma_f32_32x32x16_bf16 v[84:99], v[174:177], v[204:207], v[84:99]
	s_mov_b32 s4, 0x42ddb3d8
	s_waitcnt lgkmcnt(0)
	v_mfma_f32_32x32x16_bf16 v[68:83], v[178:181], v[204:207], v[68:83]
	v_mfma_f32_32x32x16_bf16 v[68:83], v[182:185], v[194:197], v[68:83]
	s_nop 10
	v_max_f32_e32 v2, v85, v85
	v_max_f32_e32 v145, v84, v84
	v_max_f32_e32 v2, v145, v2
	v_max3_f32 v2, v2, v86, v87
	v_max3_f32 v2, v2, v88, v89
	v_max3_f32 v2, v2, v90, v91
	v_max3_f32 v2, v2, v92, v93
	v_max3_f32 v2, v2, v94, v95
	v_max3_f32 v2, v2, v96, v97
	v_max3_f32 v2, v2, v98, v99
	v_max3_f32 v2, v2, v68, v69
	v_max3_f32 v2, v2, v70, v71
	v_max3_f32 v2, v2, v72, v73
	v_max3_f32 v2, v2, v74, v75
	v_max3_f32 v2, v2, v76, v77
	v_max3_f32 v2, v2, v78, v79
	v_max3_f32 v2, v2, v80, v81
	v_max3_f32 v2, v2, v82, v83
	v_mov_b32_e32 v145, v2
	s_nop 1
	v_permlane32_swap_b32_e32 v2, v145
	v_max_f32_e32 v145, v145, v145
	v_max_f32_e32 v2, v2, v2
	v_max_f32_e32 v2, v2, v145
	v_sub_f32_e32 v145, v2, v167
	v_cmp_ge_f32_e32 vcc, s4, v145
	v_max_f32_e32 v145, v167, v167
	v_max_f32_e32 v145, v145, v2
	v_sub_f32_e32 v2, v167, v145
	v_mul_f32_e32 v2, 0x3dd53b94, v2
	v_exp_f32_e32 v2, v2
	s_cmp_eq_u64 vcc, exec
	s_cselect_b64 s[4:5], -1, 0
	v_cndmask_b32_e64 v2, v2, 1.0, s[4:5]
	v_cmp_gt_f32_e32 vcc, 1.0, v2
	s_cbranch_vccz .LBB0_520
	s_and_saveexec_b64 s[18:19], s[0:1]
	ds_write_b32 v159, v2 offset:128
	s_or_b64 exec, exec, s[18:19]
	s_waitcnt lgkmcnt(0)
	ds_read_b128 v[170:173], v154 offset:224
	ds_read_b128 v[174:177], v154 offset:192
	ds_read_b128 v[178:181], v154 offset:160
	ds_read_b128 v[182:185], v154 offset:128
	s_waitcnt lgkmcnt(0)
	v_pk_mul_f32 v[66:67], v[66:67], v[172:173]
	v_pk_mul_f32 v[62:63], v[62:63], v[176:177]
	v_pk_mul_f32 v[58:59], v[58:59], v[180:181]
	v_pk_mul_f32 v[54:55], v[54:55], v[184:185]
	v_pk_mul_f32 v[64:65], v[64:65], v[170:171]
	v_pk_mul_f32 v[60:61], v[60:61], v[174:175]
	v_pk_mul_f32 v[56:57], v[56:57], v[178:179]
	v_pk_mul_f32 v[52:53], v[52:53], v[182:183]
	v_pk_mul_f32 v[50:51], v[50:51], v[172:173]
	v_pk_mul_f32 v[46:47], v[46:47], v[176:177]
	v_pk_mul_f32 v[42:43], v[42:43], v[180:181]
	v_pk_mul_f32 v[38:39], v[38:39], v[184:185]
	v_pk_mul_f32 v[48:49], v[48:49], v[170:171]
	v_pk_mul_f32 v[44:45], v[44:45], v[174:175]
	v_pk_mul_f32 v[40:41], v[40:41], v[178:179]
	v_pk_mul_f32 v[36:37], v[36:37], v[182:183]
	v_pk_mul_f32 v[34:35], v[34:35], v[172:173]
	v_pk_mul_f32 v[30:31], v[30:31], v[176:177]
	v_pk_mul_f32 v[26:27], v[26:27], v[180:181]
	v_pk_mul_f32 v[22:23], v[22:23], v[184:185]
	v_pk_mul_f32 v[32:33], v[32:33], v[170:171]
	v_pk_mul_f32 v[28:29], v[28:29], v[174:175]
	v_pk_mul_f32 v[24:25], v[24:25], v[178:179]
	v_pk_mul_f32 v[20:21], v[20:21], v[182:183]
	v_pk_mul_f32 v[18:19], v[18:19], v[172:173]
	v_pk_mul_f32 v[14:15], v[14:15], v[176:177]
	v_pk_mul_f32 v[10:11], v[10:11], v[180:181]
	v_pk_mul_f32 v[6:7], v[6:7], v[184:185]
	v_pk_mul_f32 v[16:17], v[16:17], v[170:171]
	v_pk_mul_f32 v[12:13], v[12:13], v[174:175]
	v_pk_mul_f32 v[8:9], v[8:9], v[178:179]
	v_pk_mul_f32 v[4:5], v[4:5], v[182:183]

.LBB0_649:
	v_lshl_add_u64 v[24:25], v[18:19], 0, v[100:101]
	v_add_co_u32_e32 v20, vcc, 0x1b38b000, v24
	v_add_u32_e32 v1, 32, v1
	s_nop 0
	v_addc_co_u32_e32 v21, vcc, 0, v25, vcc
	v_add_co_u32_e32 v24, vcc, 0x1b38d000, v24
	global_load_dwordx4 v[12:15], v[20:21], off
	s_nop 0
	global_load_dwordx4 v[20:23], v[20:21], off offset:2048
	v_addc_co_u32_e32 v25, vcc, 0, v25, vcc
	global_load_dwordx4 v[24:27], v[24:25], off
	s_waitcnt vmcnt(2)
	v_lshlrev_b32_e32 v28, 16, v15
	v_and_b32_e32 v29, 0xffff0000, v15
	v_lshlrev_b32_e32 v34, 16, v14
	v_and_b32_e32 v35, 0xffff0000, v14
	s_waitcnt vmcnt(1)
	v_lshlrev_b32_e32 v14, 16, v22
	v_and_b32_e32 v15, 0xffff0000, v22
	s_waitcnt vmcnt(0)
	v_lshlrev_b32_e32 v22, 16, v26
	v_lshlrev_b32_e32 v30, 16, v23
	v_and_b32_e32 v31, 0xffff0000, v23
	v_and_b32_e32 v23, 0xffff0000, v26
	v_mul_f32_e32 v2, 0xbfb8aa3b, v22
	v_pk_add_f32 v[14:15], v[34:35], v[14:15]
	v_exp_f32_e32 v34, v2
	v_mul_f32_e32 v2, 0xbfb8aa3b, v23
	v_exp_f32_e32 v35, v2
	v_lshlrev_b32_e32 v32, 16, v27
	v_and_b32_e32 v33, 0xffff0000, v27
	v_pk_mul_f32 v[26:27], v[14:15], v[14:15]
	v_pk_add_f32 v[34:35], v[34:35], 1.0 op_sel_hi:[1,0]
	v_pk_add_f32 v[28:29], v[28:29], v[30:31]
	v_rcp_f32_e32 v36, v35
	v_pk_mul_f32 v[30:31], v[28:29], v[28:29]
	v_fma_f32 v37, -v35, v36, 1.0
	v_fmac_f32_e32 v36, v37, v36
	v_div_fixup_f32 v35, v36, v35, 1.0
	v_rcp_f32_e32 v36, v34
	s_nop 0
	v_fma_f32 v37, -v34, v36, 1.0
	v_fmac_f32_e32 v36, v37, v36
	v_lshlrev_b32_e32 v38, 16, v25
	v_div_fixup_f32 v34, v36, v34, 1.0
	v_and_b32_e32 v39, 0xffff0000, v25
	v_mul_f32_e32 v2, 0xbfb8aa3b, v38
	v_exp_f32_e32 v40, v2
	v_mul_f32_e32 v2, 0xbfb8aa3b, v39
	v_exp_f32_e32 v41, v2
	v_pk_mul_f32 v[22:23], v[34:35], v[22:23]
	v_lshlrev_b32_e32 v34, 16, v13
	v_and_b32_e32 v35, 0xffff0000, v13
	v_pk_add_f32 v[40:41], v[40:41], 1.0 op_sel_hi:[1,0]
	v_lshlrev_b32_e32 v36, 16, v21
	v_rcp_f32_e32 v13, v41
	v_and_b32_e32 v37, 0xffff0000, v21
	v_pk_add_f32 v[34:35], v[34:35], v[36:37]
	v_fma_f32 v21, -v41, v13, 1.0
	v_fmac_f32_e32 v13, v21, v13
	v_div_fixup_f32 v41, v13, v41, 1.0
	v_rcp_f32_e32 v13, v40
	v_pk_mul_f32 v[36:37], v[34:35], v[34:35]
	v_fma_f32 v21, -v40, v13, 1.0
	v_fmac_f32_e32 v13, v21, v13
	v_div_fixup_f32 v40, v13, v40, 1.0
	v_pk_mul_f32 v[38:39], v[40:41], v[38:39]
	v_lshlrev_b32_e32 v40, 16, v12
	v_and_b32_e32 v41, 0xffff0000, v12
	v_lshlrev_b32_e32 v12, 16, v20
	v_and_b32_e32 v13, 0xffff0000, v20
	v_lshlrev_b32_e32 v20, 16, v24
	v_and_b32_e32 v21, 0xffff0000, v24
	v_mul_f32_e32 v2, 0xbfb8aa3b, v20
	v_pk_add_f32 v[12:13], v[40:41], v[12:13]
	v_exp_f32_e32 v40, v2
	v_mul_f32_e32 v2, 0xbfb8aa3b, v21
	v_exp_f32_e32 v41, v2
	v_pk_mul_f32 v[24:25], v[12:13], v[12:13]
	v_pk_add_f32 v[40:41], v[40:41], 1.0 op_sel_hi:[1,0]
	s_nop 0
	v_rcp_f32_e32 v42, v41
	s_nop 0
	v_fma_f32 v43, -v41, v42, 1.0
	v_fmac_f32_e32 v42, v43, v42
	v_div_fixup_f32 v41, v42, v41, 1.0
	v_rcp_f32_e32 v42, v40
	s_nop 0
	v_fma_f32 v43, -v40, v42, 1.0
	v_fmac_f32_e32 v42, v43, v42
	v_div_fixup_f32 v40, v42, v40, 1.0
	v_add_f32_e32 v2, v24, v25
	v_add_f32_e32 v2, v36, v2
	v_add_f32_e32 v2, v37, v2
	v_add_f32_e32 v2, v26, v2
	v_add_f32_e32 v2, v27, v2
	v_add_f32_e32 v2, v30, v2
	v_add_f32_e32 v2, v31, v2
	v_pk_mul_f32 v[20:21], v[40:41], v[20:21]
	s_nop 0
	v_add_f32_dpp v2, v2, v2 quad_perm:[1,0,3,2] row_mask:0xf bank_mask:0xf bound_ctrl:1
	s_nop 1
	v_add_f32_dpp v2, v2, v2 quad_perm:[2,3,0,1] row_mask:0xf bank_mask:0xf bound_ctrl:1
	s_nop 1
	v_add_f32_dpp v2, v2, v2 row_half_mirror row_mask:0xf bank_mask:0xf bound_ctrl:1
	s_nop 1
	v_add_f32_dpp v2, v2, v2 row_mirror row_mask:0xf bank_mask:0xf bound_ctrl:1
	v_fmamk_f32 v2, v2, 0x3c000000, v198
	v_cmp_gt_f32_e32 vcc, s46, v2
	v_mul_f32_e32 v24, 0x4b800000, v2
	s_nop 0
	v_cndmask_b32_e32 v2, v2, v24, vcc
	v_rsq_f32_e32 v2, v2
	s_nop 0
	v_mul_f32_e32 v24, 0x45800000, v2
	v_cndmask_b32_e32 v2, v2, v24, vcc
	v_pk_mul_f32 v[12:13], v[12:13], v[2:3] op_sel_hi:[1,0]
	v_pk_mul_f32 v[14:15], v[14:15], v[2:3] op_sel_hi:[1,0]
	v_pk_mul_f32 v[12:13], v[8:9], v[12:13]
	v_pk_mul_f32 v[14:15], v[4:5], v[14:15]
	v_pk_mul_f32 v[12:13], v[20:21], v[12:13]
	v_pk_mul_f32 v[20:21], v[34:35], v[2:3] op_sel_hi:[1,0]
	v_pk_mul_f32 v[14:15], v[22:23], v[14:15]
	v_mul_f32_e32 v22, 0xbfb8aa3b, v32
	v_pk_mul_f32 v[24:25], v[28:29], v[2:3] op_sel_hi:[1,0]
	v_mul_f32_e32 v2, 0xbfb8aa3b, v33
	v_exp_f32_e32 v22, v22
	v_exp_f32_e32 v23, v2
	v_pk_mul_f32 v[20:21], v[10:11], v[20:21]
	v_pk_mul_f32 v[24:25], v[6:7], v[24:25]
	v_pk_mul_f32 v[20:21], v[38:39], v[20:21]
	v_pk_add_f32 v[22:23], v[22:23], 1.0 op_sel_hi:[1,0]
	v_cvt_pk_bf16_f32 v12, v12, v13
	v_rcp_f32_e32 v26, v23
	v_cvt_pk_bf16_f32 v13, v20, v21
	v_cvt_pk_bf16_f32 v14, v14, v15
	v_lshl_add_u64 v[20:21], v[16:17], 0, v[100:101]
	v_fma_f32 v27, -v23, v26, 1.0
	v_fmac_f32_e32 v26, v27, v26
	v_div_fixup_f32 v23, v26, v23, 1.0
	v_rcp_f32_e32 v26, v22
	s_mov_b64 s[6:7], 0x104000
	v_lshl_add_u64 v[18:19], v[18:19], 0, s[6:7]
	s_movk_i32 s6, 0xdf
	v_fma_f32 v27, -v22, v26, 1.0
	v_fmac_f32_e32 v26, v27, v26
	v_div_fixup_f32 v22, v26, v22, 1.0
	v_pk_mul_f32 v[22:23], v[22:23], v[32:33]
	v_cmp_lt_i32_e32 vcc, s6, v1
	v_pk_mul_f32 v[22:23], v[22:23], v[24:25]
	v_lshl_add_u64 v[16:17], v[16:17], 0, s[8:9]
	v_cvt_pk_bf16_f32 v15, v22, v23
	s_or_b64 s[4:5], vcc, s[4:5]
	global_store_dwordx4 v[20:21], v[12:15], off
	s_andn2_b64 exec, exec, s[4:5]
	s_cbranch_execnz .LBB0_649
	s_branch .LBB0_631

.LBB0_806:
	v_lshlrev_b64 v[4:5], 1, v[216:217]
	v_lshl_add_u64 v[62:63], s[10:11], 0, v[4:5]
	s_mov_b32 s16, 0x8200
	v_mad_i64_i32 v[64:65], s[14:15], v224, s16, v[62:63]
	v_add_co_u32_e32 v64, vcc, 0x2000, v64
	v_or_b32_e32 v230, 16, v224
	s_nop 0
	v_addc_co_u32_e32 v65, vcc, 0, v65, vcc
	global_load_dwordx4 v[194:197], v[64:65], off
	global_load_dwordx4 v[190:193], v[64:65], off offset:256
	v_mad_i64_i32 v[64:65], s[14:15], v230, s16, v[62:63]
	v_add_co_u32_e32 v64, vcc, 0x2000, v64
	v_or_b32_e32 v228, 32, v224
	s_nop 0
	v_addc_co_u32_e32 v65, vcc, 0, v65, vcc
	global_load_dwordx4 v[186:189], v[64:65], off
	global_load_dwordx4 v[182:185], v[64:65], off offset:256
	v_mad_i64_i32 v[64:65], s[14:15], v228, s16, v[62:63]
	v_add_co_u32_e32 v64, vcc, 0x2000, v64
	v_or_b32_e32 v226, 48, v224
	s_nop 0
	v_addc_co_u32_e32 v65, vcc, 0, v65, vcc
	global_load_dwordx4 v[178:181], v[64:65], off
	global_load_dwordx4 v[174:177], v[64:65], off offset:256
	v_mad_i64_i32 v[64:65], s[14:15], v226, s16, v[62:63]
	v_add_co_u32_e32 v64, vcc, 0x2000, v64
	v_add_u32_e32 v222, 0x80, v224
	s_nop 0
	v_addc_co_u32_e32 v65, vcc, 0, v65, vcc
	global_load_dwordx4 v[162:165], v[64:65], off
	global_load_dwordx4 v[150:153], v[64:65], off offset:256
	v_mad_i64_i32 v[64:65], s[14:15], v222, s16, v[62:63]
	v_add_co_u32_e32 v64, vcc, 0x2000, v64
	v_add_u32_e32 v220, 0x90, v224
	s_nop 0
	v_addc_co_u32_e32 v65, vcc, 0, v65, vcc
	global_load_dwordx4 v[142:145], v[64:65], off
	global_load_dwordx4 v[130:133], v[64:65], off offset:256
	v_mad_i64_i32 v[64:65], s[14:15], v220, s16, v[62:63]
	v_add_co_u32_e32 v64, vcc, 0x2000, v64
	v_add_u32_e32 v218, 0xa0, v224
	s_nop 0
	v_addc_co_u32_e32 v65, vcc, 0, v65, vcc
	global_load_dwordx4 v[118:121], v[64:65], off
	global_load_dwordx4 v[106:109], v[64:65], off offset:256
	v_mad_i64_i32 v[64:65], s[14:15], v218, s16, v[62:63]
	v_add_co_u32_e32 v64, vcc, 0x2000, v64
	v_add_u32_e32 v216, 0xb0, v224
	s_nop 0
	v_addc_co_u32_e32 v65, vcc, 0, v65, vcc
	v_mad_i64_i32 v[62:63], s[14:15], v216, s16, v[62:63]
	v_add_co_u32_e32 v62, vcc, 0x2000, v62
	v_ashrrev_i32_e32 v225, 31, v224
	s_nop 0
	v_addc_co_u32_e32 v63, vcc, 0, v63, vcc
	v_lshlrev_b64 v[224:225], 12, v[224:225]
	global_load_dwordx4 v[94:97], v[64:65], off
	global_load_dwordx4 v[82:85], v[64:65], off offset:256
	global_load_dwordx4 v[74:77], v[62:63], off
	s_nop 0
	global_load_dwordx4 v[62:65], v[62:63], off offset:256
	v_ashrrev_i32_e32 v231, 31, v230
	v_ashrrev_i32_e32 v229, 31, v228
	v_ashrrev_i32_e32 v227, 31, v226
	v_ashrrev_i32_e32 v223, 31, v222
	v_ashrrev_i32_e32 v221, 31, v220
	v_ashrrev_i32_e32 v219, 31, v218
	v_ashrrev_i32_e32 v217, 31, v216
	s_mov_b32 s41, 0x8200
	s_mov_b32 s18, s39
	s_mov_b32 s19, s40
	s_mov_b64 s[16:17], s[0:1]
	s_waitcnt vmcnt(0)
	v_lshlrev_b32_e32 v2, 16, v194
	v_mul_f32_e32 v2, 0xbfb8aa3b, v2
	v_exp_f32_e32 v232, v2
	v_and_b32_e32 v2, 0xffff0000, v194
	v_mul_f32_e32 v2, 0xbfb8aa3b, v2
	v_exp_f32_e32 v233, v2
	s_nop 0
	v_pk_add_f32 v[232:233], v[232:233], 1.0 op_sel_hi:[1,0]
	s_nop 0
	v_rcp_f32_e32 v194, v233
	s_nop 0
	v_fma_f32 v203, -v233, v194, 1.0
	v_fmac_f32_e32 v194, v203, v194
	v_div_fixup_f32 v233, v194, v233, 1.0
	v_rcp_f32_e32 v194, v232
	s_nop 0
	v_fma_f32 v203, -v232, v194, 1.0
	v_fmac_f32_e32 v194, v203, v194
	v_div_fixup_f32 v232, v194, v232, 1.0
	v_lshlrev_b32_e32 v2, 16, v195
	v_mul_f32_e32 v2, 0xbfb8aa3b, v2
	v_exp_f32_e32 v194, v2
	v_and_b32_e32 v2, 0xffff0000, v195
	v_mul_f32_e32 v2, 0xbfb8aa3b, v2
	v_exp_f32_e32 v195, v2
	v_pk_mul_f32 v[170:171], v[170:171], v[232:233]
	v_pk_add_f32 v[194:195], v[194:195], 1.0 op_sel_hi:[1,0]
	s_nop 0
	v_rcp_f32_e32 v203, v195
	s_nop 0
	v_fma_f32 v232, -v195, v203, 1.0
	v_fmac_f32_e32 v203, v232, v203
	v_div_fixup_f32 v195, v203, v195, 1.0
	v_rcp_f32_e32 v203, v194
	s_nop 0
	v_fma_f32 v232, -v194, v203, 1.0
	v_fmac_f32_e32 v203, v232, v203
	v_div_fixup_f32 v194, v203, v194, 1.0
	v_lshlrev_b32_e32 v2, 16, v196
	v_mul_f32_e32 v2, 0xbfb8aa3b, v2
	v_pk_mul_f32 v[172:173], v[172:173], v[194:195]
	v_exp_f32_e32 v194, v2
	v_and_b32_e32 v2, 0xffff0000, v196
	v_mul_f32_e32 v2, 0xbfb8aa3b, v2
	v_exp_f32_e32 v195, v2
	s_nop 0
	v_pk_add_f32 v[194:195], v[194:195], 1.0 op_sel_hi:[1,0]
	s_nop 0
	v_rcp_f32_e32 v196, v195
	s_nop 0
	v_fma_f32 v203, -v195, v196, 1.0
	v_fmac_f32_e32 v196, v203, v196
	v_div_fixup_f32 v195, v196, v195, 1.0
	v_rcp_f32_e32 v196, v194
	s_nop 0
	v_fma_f32 v203, -v194, v196, 1.0
	v_fmac_f32_e32 v196, v203, v196
	v_div_fixup_f32 v194, v196, v194, 1.0
	v_lshlrev_b32_e32 v2, 16, v197
	v_mul_f32_e32 v2, 0xbfb8aa3b, v2
	v_pk_mul_f32 v[166:167], v[166:167], v[194:195]
	v_exp_f32_e32 v194, v2
	v_and_b32_e32 v2, 0xffff0000, v197
	v_mul_f32_e32 v2, 0xbfb8aa3b, v2
	v_exp_f32_e32 v195, v2
	s_nop 0
	v_pk_add_f32 v[194:195], v[194:195], 1.0 op_sel_hi:[1,0]
	s_nop 0
	v_rcp_f32_e32 v196, v195
	s_nop 0
	v_fma_f32 v197, -v195, v196, 1.0
	v_fmac_f32_e32 v196, v197, v196
	v_div_fixup_f32 v195, v196, v195, 1.0
	v_rcp_f32_e32 v196, v194
	s_nop 0
	v_fma_f32 v197, -v194, v196, 1.0
	v_fmac_f32_e32 v196, v197, v196
	v_div_fixup_f32 v194, v196, v194, 1.0
	v_pk_mul_f32 v[194:195], v[168:169], v[194:195]
	v_cvt_pk_bf16_f32 v168, v170, v171
	v_cvt_pk_bf16_f32 v170, v166, v167
	v_lshl_add_u64 v[166:167], s[12:13], 0, v[224:225]
	v_lshlrev_b32_e32 v2, 16, v190
	v_cvt_pk_bf16_f32 v169, v172, v173
	v_cvt_pk_bf16_f32 v171, v194, v195
	v_lshl_add_u64 v[166:167], v[166:167], 0, v[4:5]
	v_mul_f32_e32 v2, 0xbfb8aa3b, v2
	global_store_dwordx4 v[166:167], v[168:171], off
	s_nop 1
	v_exp_f32_e32 v168, v2
	v_and_b32_e32 v2, 0xffff0000, v190
	v_mul_f32_e32 v2, 0xbfb8aa3b, v2
	v_exp_f32_e32 v169, v2
	s_nop 0
	v_pk_add_f32 v[168:169], v[168:169], 1.0 op_sel_hi:[1,0]
	s_nop 0
	v_rcp_f32_e32 v170, v169
	s_nop 0
	v_fma_f32 v171, -v169, v170, 1.0
	v_fmac_f32_e32 v170, v171, v170
	v_div_fixup_f32 v169, v170, v169, 1.0
	v_rcp_f32_e32 v170, v168
	s_nop 0
	v_fma_f32 v171, -v168, v170, 1.0
	v_fmac_f32_e32 v170, v171, v170
	v_div_fixup_f32 v168, v170, v168, 1.0
	v_lshlrev_b32_e32 v2, 16, v191
	v_mul_f32_e32 v2, 0xbfb8aa3b, v2
	v_pk_mul_f32 v[158:159], v[158:159], v[168:169]
	v_exp_f32_e32 v168, v2
	v_and_b32_e32 v2, 0xffff0000, v191
	v_mul_f32_e32 v2, 0xbfb8aa3b, v2
	v_exp_f32_e32 v169, v2
	s_nop 0
	v_pk_add_f32 v[168:169], v[168:169], 1.0 op_sel_hi:[1,0]
	s_nop 0
	v_rcp_f32_e32 v170, v169
	s_nop 0
	v_fma_f32 v171, -v169, v170, 1.0
	v_fmac_f32_e32 v170, v171, v170
	v_div_fixup_f32 v169, v170, v169, 1.0
	v_rcp_f32_e32 v170, v168
	s_nop 0
	v_fma_f32 v171, -v168, v170, 1.0
	v_fmac_f32_e32 v170, v171, v170
	v_div_fixup_f32 v168, v170, v168, 1.0
	v_lshlrev_b32_e32 v2, 16, v192
	v_mul_f32_e32 v2, 0xbfb8aa3b, v2
	v_pk_mul_f32 v[160:161], v[160:161], v[168:169]
	v_exp_f32_e32 v168, v2
	v_and_b32_e32 v2, 0xffff0000, v192
	v_mul_f32_e32 v2, 0xbfb8aa3b, v2
	v_exp_f32_e32 v169, v2
	s_nop 0
	v_pk_add_f32 v[168:169], v[168:169], 1.0 op_sel_hi:[1,0]
	s_nop 0
	v_rcp_f32_e32 v170, v169
	s_nop 0
	v_fma_f32 v171, -v169, v170, 1.0
	v_fmac_f32_e32 v170, v171, v170
	v_div_fixup_f32 v169, v170, v169, 1.0
	v_rcp_f32_e32 v170, v168
	s_nop 0
	v_fma_f32 v171, -v168, v170, 1.0
	v_fmac_f32_e32 v170, v171, v170
	v_div_fixup_f32 v168, v170, v168, 1.0
	v_lshlrev_b32_e32 v2, 16, v193
	v_mul_f32_e32 v2, 0xbfb8aa3b, v2
	v_pk_mul_f32 v[168:169], v[154:155], v[168:169]
	v_exp_f32_e32 v154, v2
	v_and_b32_e32 v2, 0xffff0000, v193
	v_mul_f32_e32 v2, 0xbfb8aa3b, v2
	v_exp_f32_e32 v155, v2
	s_nop 0
	v_pk_add_f32 v[154:155], v[154:155], 1.0 op_sel_hi:[1,0]
	s_nop 0
	v_rcp_f32_e32 v170, v155
	s_nop 0
	v_fma_f32 v171, -v155, v170, 1.0
	v_fmac_f32_e32 v170, v171, v170
	v_div_fixup_f32 v155, v170, v155, 1.0
	v_rcp_f32_e32 v170, v154
	s_nop 0
	v_fma_f32 v171, -v154, v170, 1.0
	v_fmac_f32_e32 v170, v171, v170
	v_div_fixup_f32 v154, v170, v154, 1.0
	v_pk_mul_f32 v[170:171], v[156:157], v[154:155]
	v_lshlrev_b32_e32 v2, 16, v186
	v_cvt_pk_bf16_f32 v154, v158, v159
	v_cvt_pk_bf16_f32 v155, v160, v161
	v_cvt_pk_bf16_f32 v156, v168, v169
	v_cvt_pk_bf16_f32 v157, v170, v171
	v_mul_f32_e32 v2, 0xbfb8aa3b, v2
	global_store_dwordx4 v[166:167], v[154:157], off offset:256
	s_nop 1
	v_exp_f32_e32 v156, v2
	v_and_b32_e32 v2, 0xffff0000, v186
	v_mul_f32_e32 v2, 0xbfb8aa3b, v2
	v_exp_f32_e32 v157, v2
	v_lshlrev_b64 v[154:155], 12, v[230:231]
	v_pk_add_f32 v[156:157], v[156:157], 1.0 op_sel_hi:[1,0]
	s_nop 0
	v_rcp_f32_e32 v158, v157
	s_nop 0
	v_fma_f32 v159, -v157, v158, 1.0
	v_fmac_f32_e32 v158, v159, v158
	v_div_fixup_f32 v157, v158, v157, 1.0
	v_rcp_f32_e32 v158, v156
	s_nop 0
	v_fma_f32 v159, -v156, v158, 1.0
	v_fmac_f32_e32 v158, v159, v158
	v_div_fixup_f32 v156, v158, v156, 1.0
	v_lshlrev_b32_e32 v2, 16, v187
	v_mul_f32_e32 v2, 0xbfb8aa3b, v2
	v_pk_mul_f32 v[146:147], v[146:147], v[156:157]
	v_exp_f32_e32 v156, v2
	v_and_b32_e32 v2, 0xffff0000, v187
	v_mul_f32_e32 v2, 0xbfb8aa3b, v2
	v_exp_f32_e32 v157, v2
	v_cvt_pk_bf16_f32 v146, v146, v147
	v_pk_add_f32 v[156:157], v[156:157], 1.0 op_sel_hi:[1,0]
	s_nop 0
	v_rcp_f32_e32 v158, v157
	s_nop 0
	v_fma_f32 v159, -v157, v158, 1.0
	v_fmac_f32_e32 v158, v159, v158
	v_div_fixup_f32 v157, v158, v157, 1.0
	v_rcp_f32_e32 v158, v156
	s_nop 0
	v_fma_f32 v159, -v156, v158, 1.0
	v_fmac_f32_e32 v158, v159, v158
	v_div_fixup_f32 v156, v158, v156, 1.0
	v_lshlrev_b32_e32 v2, 16, v188
	v_mul_f32_e32 v2, 0xbfb8aa3b, v2
	v_pk_mul_f32 v[148:149], v[148:149], v[156:157]
	v_exp_f32_e32 v156, v2
	v_and_b32_e32 v2, 0xffff0000, v188
	v_mul_f32_e32 v2, 0xbfb8aa3b, v2
	v_exp_f32_e32 v157, v2
	v_cvt_pk_bf16_f32 v147, v148, v149
	v_pk_add_f32 v[156:157], v[156:157], 1.0 op_sel_hi:[1,0]
	s_nop 0
	v_rcp_f32_e32 v158, v157
	s_nop 0
	v_fma_f32 v159, -v157, v158, 1.0
	v_fmac_f32_e32 v158, v159, v158
	v_div_fixup_f32 v157, v158, v157, 1.0
	v_rcp_f32_e32 v158, v156
	s_nop 0
	v_fma_f32 v159, -v156, v158, 1.0
	v_fmac_f32_e32 v158, v159, v158
	v_div_fixup_f32 v156, v158, v156, 1.0
	v_lshlrev_b32_e32 v2, 16, v189
	v_mul_f32_e32 v2, 0xbfb8aa3b, v2
	v_pk_mul_f32 v[138:139], v[138:139], v[156:157]
	v_exp_f32_e32 v156, v2
	v_and_b32_e32 v2, 0xffff0000, v189
	v_mul_f32_e32 v2, 0xbfb8aa3b, v2
	v_exp_f32_e32 v157, v2
	v_cvt_pk_bf16_f32 v148, v138, v139
	v_lshl_add_u64 v[138:139], s[12:13], 0, v[154:155]
	v_lshl_add_u64 v[138:139], v[138:139], 0, v[4:5]
	v_pk_add_f32 v[156:157], v[156:157], 1.0 op_sel_hi:[1,0]
	s_nop 0
	v_rcp_f32_e32 v158, v157
	s_nop 0
	v_fma_f32 v159, -v157, v158, 1.0
	v_fmac_f32_e32 v158, v159, v158
	v_div_fixup_f32 v157, v158, v157, 1.0
	v_rcp_f32_e32 v158, v156
	s_nop 0
	v_fma_f32 v159, -v156, v158, 1.0
	v_fmac_f32_e32 v158, v159, v158
	v_div_fixup_f32 v156, v158, v156, 1.0
	v_lshlrev_b32_e32 v2, 16, v182
	v_pk_mul_f32 v[140:141], v[140:141], v[156:157]
	v_mul_f32_e32 v2, 0xbfb8aa3b, v2
	v_cvt_pk_bf16_f32 v149, v140, v141
	v_exp_f32_e32 v140, v2
	v_and_b32_e32 v2, 0xffff0000, v182
	v_mul_f32_e32 v2, 0xbfb8aa3b, v2
	v_exp_f32_e32 v141, v2
	global_store_dwordx4 v[138:139], v[146:149], off
	v_pk_add_f32 v[140:141], v[140:141], 1.0 op_sel_hi:[1,0]
	s_nop 0
	v_rcp_f32_e32 v146, v141
	s_nop 0
	v_fma_f32 v147, -v141, v146, 1.0
	v_fmac_f32_e32 v146, v147, v146
	v_div_fixup_f32 v141, v146, v141, 1.0
	v_rcp_f32_e32 v146, v140
	s_nop 0
	v_fma_f32 v147, -v140, v146, 1.0
	v_fmac_f32_e32 v146, v147, v146
	v_div_fixup_f32 v140, v146, v140, 1.0
	v_lshlrev_b32_e32 v2, 16, v183
	v_mul_f32_e32 v2, 0xbfb8aa3b, v2
	v_pk_mul_f32 v[134:135], v[134:135], v[140:141]
	v_exp_f32_e32 v140, v2
	v_and_b32_e32 v2, 0xffff0000, v183
	v_mul_f32_e32 v2, 0xbfb8aa3b, v2
	v_exp_f32_e32 v141, v2
	s_nop 0
	v_pk_add_f32 v[140:141], v[140:141], 1.0 op_sel_hi:[1,0]
	s_nop 0
	v_rcp_f32_e32 v146, v141
	s_nop 0
	v_fma_f32 v147, -v141, v146, 1.0
	v_fmac_f32_e32 v146, v147, v146
	v_div_fixup_f32 v141, v146, v141, 1.0
	v_rcp_f32_e32 v146, v140
	s_nop 0
	v_fma_f32 v147, -v140, v146, 1.0
	v_fmac_f32_e32 v146, v147, v146
	v_div_fixup_f32 v140, v146, v140, 1.0
	v_lshlrev_b32_e32 v2, 16, v184
	v_mul_f32_e32 v2, 0xbfb8aa3b, v2
	v_pk_mul_f32 v[136:137], v[136:137], v[140:141]
	v_exp_f32_e32 v140, v2
	v_and_b32_e32 v2, 0xffff0000, v184
	v_mul_f32_e32 v2, 0xbfb8aa3b, v2
	v_exp_f32_e32 v141, v2
	s_nop 0
	v_pk_add_f32 v[140:141], v[140:141], 1.0 op_sel_hi:[1,0]
	s_nop 0
	v_rcp_f32_e32 v146, v141
	s_nop 0
	v_fma_f32 v147, -v141, v146, 1.0
	v_fmac_f32_e32 v146, v147, v146
	v_div_fixup_f32 v141, v146, v141, 1.0
	v_rcp_f32_e32 v146, v140
	s_nop 0
	v_fma_f32 v147, -v140, v146, 1.0
	v_fmac_f32_e32 v146, v147, v146
	v_div_fixup_f32 v140, v146, v140, 1.0
	v_lshlrev_b32_e32 v2, 16, v185
	v_mul_f32_e32 v2, 0xbfb8aa3b, v2
	v_pk_mul_f32 v[140:141], v[126:127], v[140:141]
	v_exp_f32_e32 v126, v2
	v_and_b32_e32 v2, 0xffff0000, v185
	v_mul_f32_e32 v2, 0xbfb8aa3b, v2
	v_exp_f32_e32 v127, v2
	s_nop 0
	v_pk_add_f32 v[126:127], v[126:127], 1.0 op_sel_hi:[1,0]
	s_nop 0
	v_rcp_f32_e32 v146, v127
	s_nop 0
	v_fma_f32 v147, -v127, v146, 1.0
	v_fmac_f32_e32 v146, v147, v146
	v_div_fixup_f32 v127, v146, v127, 1.0
	v_rcp_f32_e32 v146, v126
	s_nop 0
	v_fma_f32 v147, -v126, v146, 1.0
	v_fmac_f32_e32 v146, v147, v146
	v_div_fixup_f32 v126, v146, v126, 1.0
	v_pk_mul_f32 v[146:147], v[128:129], v[126:127]
	v_lshlrev_b32_e32 v2, 16, v178
	v_cvt_pk_bf16_f32 v126, v134, v135
	v_cvt_pk_bf16_f32 v127, v136, v137
	v_cvt_pk_bf16_f32 v128, v140, v141
	v_cvt_pk_bf16_f32 v129, v146, v147
	v_mul_f32_e32 v2, 0xbfb8aa3b, v2
	global_store_dwordx4 v[138:139], v[126:129], off offset:256
	s_nop 1
	v_exp_f32_e32 v128, v2
	v_and_b32_e32 v2, 0xffff0000, v178
	v_mul_f32_e32 v2, 0xbfb8aa3b, v2
	v_exp_f32_e32 v129, v2
	v_lshlrev_b64 v[126:127], 12, v[228:229]
	v_pk_add_f32 v[128:129], v[128:129], 1.0 op_sel_hi:[1,0]
	s_nop 0
	v_rcp_f32_e32 v134, v129
	s_nop 0
	v_fma_f32 v135, -v129, v134, 1.0
	v_fmac_f32_e32 v134, v135, v134
	v_div_fixup_f32 v129, v134, v129, 1.0
	v_rcp_f32_e32 v134, v128
	s_nop 0
	v_fma_f32 v135, -v128, v134, 1.0
	v_fmac_f32_e32 v134, v135, v134
	v_div_fixup_f32 v128, v134, v128, 1.0
	v_lshlrev_b32_e32 v2, 16, v179
	v_mul_f32_e32 v2, 0xbfb8aa3b, v2
	v_pk_mul_f32 v[122:123], v[122:123], v[128:129]
	v_exp_f32_e32 v128, v2
	v_and_b32_e32 v2, 0xffff0000, v179
	v_mul_f32_e32 v2, 0xbfb8aa3b, v2
	v_exp_f32_e32 v129, v2
	v_cvt_pk_bf16_f32 v122, v122, v123
	v_pk_add_f32 v[128:129], v[128:129], 1.0 op_sel_hi:[1,0]
	s_nop 0
	v_rcp_f32_e32 v134, v129
	s_nop 0
	v_fma_f32 v135, -v129, v134, 1.0
	v_fmac_f32_e32 v134, v135, v134
	v_div_fixup_f32 v129, v134, v129, 1.0
	v_rcp_f32_e32 v134, v128
	s_nop 0
	v_fma_f32 v135, -v128, v134, 1.0
	v_fmac_f32_e32 v134, v135, v134
	v_div_fixup_f32 v128, v134, v128, 1.0
	v_lshlrev_b32_e32 v2, 16, v180
	v_mul_f32_e32 v2, 0xbfb8aa3b, v2
	v_pk_mul_f32 v[124:125], v[124:125], v[128:129]
	v_exp_f32_e32 v128, v2
	v_and_b32_e32 v2, 0xffff0000, v180
	v_mul_f32_e32 v2, 0xbfb8aa3b, v2
	v_exp_f32_e32 v129, v2
	v_cvt_pk_bf16_f32 v123, v124, v125
	v_pk_add_f32 v[128:129], v[128:129], 1.0 op_sel_hi:[1,0]
	s_nop 0
	v_rcp_f32_e32 v134, v129
	s_nop 0
	v_fma_f32 v135, -v129, v134, 1.0
	v_fmac_f32_e32 v134, v135, v134
	v_div_fixup_f32 v129, v134, v129, 1.0
	v_rcp_f32_e32 v134, v128
	s_nop 0
	v_fma_f32 v135, -v128, v134, 1.0
	v_fmac_f32_e32 v134, v135, v134
	v_div_fixup_f32 v128, v134, v128, 1.0
	v_lshlrev_b32_e32 v2, 16, v181
	v_mul_f32_e32 v2, 0xbfb8aa3b, v2
	v_pk_mul_f32 v[114:115], v[114:115], v[128:129]
	v_exp_f32_e32 v128, v2
	v_and_b32_e32 v2, 0xffff0000, v181
	v_mul_f32_e32 v2, 0xbfb8aa3b, v2
	v_exp_f32_e32 v129, v2
	v_cvt_pk_bf16_f32 v124, v114, v115
	v_lshl_add_u64 v[114:115], s[12:13], 0, v[126:127]
	v_lshl_add_u64 v[114:115], v[114:115], 0, v[4:5]
	v_pk_add_f32 v[128:129], v[128:129], 1.0 op_sel_hi:[1,0]
	s_nop 0
	v_rcp_f32_e32 v134, v129
	s_nop 0
	v_fma_f32 v135, -v129, v134, 1.0
	v_fmac_f32_e32 v134, v135, v134
	v_div_fixup_f32 v129, v134, v129, 1.0
	v_rcp_f32_e32 v134, v128
	s_nop 0
	v_fma_f32 v135, -v128, v134, 1.0
	v_fmac_f32_e32 v134, v135, v134
	v_div_fixup_f32 v128, v134, v128, 1.0
	v_lshlrev_b32_e32 v2, 16, v174
	v_pk_mul_f32 v[116:117], v[116:117], v[128:129]
	v_mul_f32_e32 v2, 0xbfb8aa3b, v2
	v_cvt_pk_bf16_f32 v125, v116, v117
	v_exp_f32_e32 v116, v2
	v_and_b32_e32 v2, 0xffff0000, v174
	v_mul_f32_e32 v2, 0xbfb8aa3b, v2
	v_exp_f32_e32 v117, v2
	global_store_dwordx4 v[114:115], v[122:125], off
	v_pk_add_f32 v[116:117], v[116:117], 1.0 op_sel_hi:[1,0]
	s_nop 0
	v_rcp_f32_e32 v122, v117
	s_nop 0
	v_fma_f32 v123, -v117, v122, 1.0
	v_fmac_f32_e32 v122, v123, v122
	v_div_fixup_f32 v117, v122, v117, 1.0
	v_rcp_f32_e32 v122, v116
	s_nop 0
	v_fma_f32 v123, -v116, v122, 1.0
	v_fmac_f32_e32 v122, v123, v122
	v_div_fixup_f32 v116, v122, v116, 1.0
	v_lshlrev_b32_e32 v2, 16, v175
	v_mul_f32_e32 v2, 0xbfb8aa3b, v2
	v_pk_mul_f32 v[110:111], v[110:111], v[116:117]
	v_exp_f32_e32 v116, v2
	v_and_b32_e32 v2, 0xffff0000, v175
	v_mul_f32_e32 v2, 0xbfb8aa3b, v2
	v_exp_f32_e32 v117, v2
	s_nop 0
	v_pk_add_f32 v[116:117], v[116:117], 1.0 op_sel_hi:[1,0]
	s_nop 0
	v_rcp_f32_e32 v122, v117
	s_nop 0
	v_fma_f32 v123, -v117, v122, 1.0
	v_fmac_f32_e32 v122, v123, v122
	v_div_fixup_f32 v117, v122, v117, 1.0
	v_rcp_f32_e32 v122, v116
	s_nop 0
	v_fma_f32 v123, -v116, v122, 1.0
	v_fmac_f32_e32 v122, v123, v122
	v_div_fixup_f32 v116, v122, v116, 1.0
	v_lshlrev_b32_e32 v2, 16, v176
	v_mul_f32_e32 v2, 0xbfb8aa3b, v2
	v_pk_mul_f32 v[112:113], v[112:113], v[116:117]
	v_exp_f32_e32 v116, v2
	v_and_b32_e32 v2, 0xffff0000, v176
	v_mul_f32_e32 v2, 0xbfb8aa3b, v2
	v_exp_f32_e32 v117, v2
	s_nop 0
	v_pk_add_f32 v[116:117], v[116:117], 1.0 op_sel_hi:[1,0]
	s_nop 0
	v_rcp_f32_e32 v122, v117
	s_nop 0
	v_fma_f32 v123, -v117, v122, 1.0
	v_fmac_f32_e32 v122, v123, v122
	v_div_fixup_f32 v117, v122, v117, 1.0
	v_rcp_f32_e32 v122, v116
	s_nop 0
	v_fma_f32 v123, -v116, v122, 1.0
	v_fmac_f32_e32 v122, v123, v122
	v_div_fixup_f32 v116, v122, v116, 1.0
	v_lshlrev_b32_e32 v2, 16, v177
	v_mul_f32_e32 v2, 0xbfb8aa3b, v2
	v_pk_mul_f32 v[116:117], v[102:103], v[116:117]
	v_exp_f32_e32 v102, v2
	v_and_b32_e32 v2, 0xffff0000, v177
	v_mul_f32_e32 v2, 0xbfb8aa3b, v2
	v_exp_f32_e32 v103, v2
	s_nop 0
	v_pk_add_f32 v[102:103], v[102:103], 1.0 op_sel_hi:[1,0]
	s_nop 0
	v_rcp_f32_e32 v122, v103
	s_nop 0
	v_fma_f32 v123, -v103, v122, 1.0
	v_fmac_f32_e32 v122, v123, v122
	v_div_fixup_f32 v103, v122, v103, 1.0
	v_rcp_f32_e32 v122, v102
	s_nop 0
	v_fma_f32 v123, -v102, v122, 1.0
	v_fmac_f32_e32 v122, v123, v122
	v_div_fixup_f32 v102, v122, v102, 1.0
	v_pk_mul_f32 v[122:123], v[104:105], v[102:103]
	v_lshlrev_b32_e32 v2, 16, v162
	v_cvt_pk_bf16_f32 v102, v110, v111
	v_cvt_pk_bf16_f32 v103, v112, v113
	v_cvt_pk_bf16_f32 v104, v116, v117
	v_cvt_pk_bf16_f32 v105, v122, v123
	v_mul_f32_e32 v2, 0xbfb8aa3b, v2
	global_store_dwordx4 v[114:115], v[102:105], off offset:256
	s_nop 1
	v_exp_f32_e32 v104, v2
	v_and_b32_e32 v2, 0xffff0000, v162
	v_mul_f32_e32 v2, 0xbfb8aa3b, v2
	v_exp_f32_e32 v105, v2
	v_lshlrev_b64 v[102:103], 12, v[226:227]
	v_pk_add_f32 v[104:105], v[104:105], 1.0 op_sel_hi:[1,0]
	s_nop 0
	v_rcp_f32_e32 v110, v105
	s_nop 0
	v_fma_f32 v111, -v105, v110, 1.0
	v_fmac_f32_e32 v110, v111, v110
	v_div_fixup_f32 v105, v110, v105, 1.0
	v_rcp_f32_e32 v110, v104
	s_nop 0
	v_fma_f32 v111, -v104, v110, 1.0
	v_fmac_f32_e32 v110, v111, v110
	v_div_fixup_f32 v104, v110, v104, 1.0
	v_lshlrev_b32_e32 v2, 16, v163
	v_mul_f32_e32 v2, 0xbfb8aa3b, v2
	v_pk_mul_f32 v[98:99], v[98:99], v[104:105]
	v_exp_f32_e32 v104, v2
	v_and_b32_e32 v2, 0xffff0000, v163
	v_mul_f32_e32 v2, 0xbfb8aa3b, v2
	v_exp_f32_e32 v105, v2
	v_cvt_pk_bf16_f32 v98, v98, v99
	v_pk_add_f32 v[104:105], v[104:105], 1.0 op_sel_hi:[1,0]
	s_nop 0
	v_rcp_f32_e32 v110, v105
	s_nop 0
	v_fma_f32 v111, -v105, v110, 1.0
	v_fmac_f32_e32 v110, v111, v110
	v_div_fixup_f32 v105, v110, v105, 1.0
	v_rcp_f32_e32 v110, v104
	s_nop 0
	v_fma_f32 v111, -v104, v110, 1.0
	v_fmac_f32_e32 v110, v111, v110
	v_div_fixup_f32 v104, v110, v104, 1.0
	v_lshlrev_b32_e32 v2, 16, v164
	v_mul_f32_e32 v2, 0xbfb8aa3b, v2
	v_pk_mul_f32 v[100:101], v[100:101], v[104:105]
	v_exp_f32_e32 v104, v2
	v_and_b32_e32 v2, 0xffff0000, v164
	v_mul_f32_e32 v2, 0xbfb8aa3b, v2
	v_exp_f32_e32 v105, v2
	v_cvt_pk_bf16_f32 v99, v100, v101
	v_pk_add_f32 v[104:105], v[104:105], 1.0 op_sel_hi:[1,0]
	s_nop 0
	v_rcp_f32_e32 v110, v105
	s_nop 0
	v_fma_f32 v111, -v105, v110, 1.0
	v_fmac_f32_e32 v110, v111, v110
	v_div_fixup_f32 v105, v110, v105, 1.0
	v_rcp_f32_e32 v110, v104
	s_nop 0
	v_fma_f32 v111, -v104, v110, 1.0
	v_fmac_f32_e32 v110, v111, v110
	v_div_fixup_f32 v104, v110, v104, 1.0
	v_lshlrev_b32_e32 v2, 16, v165
	v_mul_f32_e32 v2, 0xbfb8aa3b, v2
	v_pk_mul_f32 v[90:91], v[90:91], v[104:105]
	v_exp_f32_e32 v104, v2
	v_and_b32_e32 v2, 0xffff0000, v165
	v_mul_f32_e32 v2, 0xbfb8aa3b, v2
	v_exp_f32_e32 v105, v2
	v_cvt_pk_bf16_f32 v100, v90, v91
	v_lshl_add_u64 v[90:91], s[12:13], 0, v[102:103]
	v_lshl_add_u64 v[90:91], v[90:91], 0, v[4:5]
	v_pk_add_f32 v[104:105], v[104:105], 1.0 op_sel_hi:[1,0]
	s_nop 0
	v_rcp_f32_e32 v110, v105
	s_nop 0
	v_fma_f32 v111, -v105, v110, 1.0
	v_fmac_f32_e32 v110, v111, v110
	v_div_fixup_f32 v105, v110, v105, 1.0
	v_rcp_f32_e32 v110, v104
	s_nop 0
	v_fma_f32 v111, -v104, v110, 1.0
	v_fmac_f32_e32 v110, v111, v110
	v_div_fixup_f32 v104, v110, v104, 1.0
	v_lshlrev_b32_e32 v2, 16, v150
	v_pk_mul_f32 v[92:93], v[92:93], v[104:105]
	v_mul_f32_e32 v2, 0xbfb8aa3b, v2
	v_cvt_pk_bf16_f32 v101, v92, v93
	v_exp_f32_e32 v92, v2
	v_and_b32_e32 v2, 0xffff0000, v150
	v_mul_f32_e32 v2, 0xbfb8aa3b, v2
	v_exp_f32_e32 v93, v2
	global_store_dwordx4 v[90:91], v[98:101], off
	v_pk_add_f32 v[92:93], v[92:93], 1.0 op_sel_hi:[1,0]
	s_nop 0
	v_rcp_f32_e32 v98, v93
	s_nop 0
	v_fma_f32 v99, -v93, v98, 1.0
	v_fmac_f32_e32 v98, v99, v98
	v_div_fixup_f32 v93, v98, v93, 1.0
	v_rcp_f32_e32 v98, v92
	s_nop 0
	v_fma_f32 v99, -v92, v98, 1.0
	v_fmac_f32_e32 v98, v99, v98
	v_div_fixup_f32 v92, v98, v92, 1.0
	v_lshlrev_b32_e32 v2, 16, v151
	v_mul_f32_e32 v2, 0xbfb8aa3b, v2
	v_pk_mul_f32 v[86:87], v[86:87], v[92:93]
	v_exp_f32_e32 v92, v2
	v_and_b32_e32 v2, 0xffff0000, v151
	v_mul_f32_e32 v2, 0xbfb8aa3b, v2
	v_exp_f32_e32 v93, v2
	s_nop 0
	v_pk_add_f32 v[92:93], v[92:93], 1.0 op_sel_hi:[1,0]
	s_nop 0
	v_rcp_f32_e32 v98, v93
	s_nop 0
	v_fma_f32 v99, -v93, v98, 1.0
	v_fmac_f32_e32 v98, v99, v98
	v_div_fixup_f32 v93, v98, v93, 1.0
	v_rcp_f32_e32 v98, v92
	s_nop 0
	v_fma_f32 v99, -v92, v98, 1.0
	v_fmac_f32_e32 v98, v99, v98
	v_div_fixup_f32 v92, v98, v92, 1.0
	v_lshlrev_b32_e32 v2, 16, v152
	v_mul_f32_e32 v2, 0xbfb8aa3b, v2
	v_pk_mul_f32 v[88:89], v[88:89], v[92:93]
	v_exp_f32_e32 v92, v2
	v_and_b32_e32 v2, 0xffff0000, v152
	v_mul_f32_e32 v2, 0xbfb8aa3b, v2
	v_exp_f32_e32 v93, v2
	s_nop 0
	v_pk_add_f32 v[92:93], v[92:93], 1.0 op_sel_hi:[1,0]
	s_nop 0
	v_rcp_f32_e32 v98, v93
	s_nop 0
	v_fma_f32 v99, -v93, v98, 1.0
	v_fmac_f32_e32 v98, v99, v98
	v_div_fixup_f32 v93, v98, v93, 1.0
	v_rcp_f32_e32 v98, v92
	s_nop 0
	v_fma_f32 v99, -v92, v98, 1.0
	v_fmac_f32_e32 v98, v99, v98
	v_div_fixup_f32 v92, v98, v92, 1.0
	v_lshlrev_b32_e32 v2, 16, v153
	v_mul_f32_e32 v2, 0xbfb8aa3b, v2
	v_pk_mul_f32 v[92:93], v[78:79], v[92:93]
	v_exp_f32_e32 v78, v2
	v_and_b32_e32 v2, 0xffff0000, v153
	v_mul_f32_e32 v2, 0xbfb8aa3b, v2
	v_exp_f32_e32 v79, v2
	s_nop 0
	v_pk_add_f32 v[78:79], v[78:79], 1.0 op_sel_hi:[1,0]
	s_nop 0
	v_rcp_f32_e32 v98, v79
	s_nop 0
	v_fma_f32 v99, -v79, v98, 1.0
	v_fmac_f32_e32 v98, v99, v98
	v_div_fixup_f32 v79, v98, v79, 1.0
	v_rcp_f32_e32 v98, v78
	s_nop 0
	v_fma_f32 v99, -v78, v98, 1.0
	v_fmac_f32_e32 v98, v99, v98
	v_div_fixup_f32 v78, v98, v78, 1.0
	v_pk_mul_f32 v[98:99], v[80:81], v[78:79]
	v_lshlrev_b32_e32 v2, 16, v142
	v_cvt_pk_bf16_f32 v78, v86, v87
	v_cvt_pk_bf16_f32 v79, v88, v89
	v_cvt_pk_bf16_f32 v80, v92, v93
	v_cvt_pk_bf16_f32 v81, v98, v99
	v_mul_f32_e32 v2, 0xbfb8aa3b, v2
	global_store_dwordx4 v[90:91], v[78:81], off offset:256
	s_nop 1
	v_exp_f32_e32 v80, v2
	v_and_b32_e32 v2, 0xffff0000, v142
	v_mul_f32_e32 v2, 0xbfb8aa3b, v2
	v_exp_f32_e32 v81, v2
	v_lshlrev_b64 v[78:79], 12, v[222:223]
	v_pk_add_f32 v[80:81], v[80:81], 1.0 op_sel_hi:[1,0]
	s_nop 0
	v_rcp_f32_e32 v86, v81
	s_nop 0
	v_fma_f32 v87, -v81, v86, 1.0
	v_fmac_f32_e32 v86, v87, v86
	v_div_fixup_f32 v81, v86, v81, 1.0
	v_rcp_f32_e32 v86, v80
	s_nop 0
	v_fma_f32 v87, -v80, v86, 1.0
	v_fmac_f32_e32 v86, v87, v86
	v_div_fixup_f32 v80, v86, v80, 1.0
	v_lshlrev_b32_e32 v2, 16, v143
	v_mul_f32_e32 v2, 0xbfb8aa3b, v2
	v_pk_mul_f32 v[70:71], v[70:71], v[80:81]
	v_exp_f32_e32 v80, v2
	v_and_b32_e32 v2, 0xffff0000, v143
	v_mul_f32_e32 v2, 0xbfb8aa3b, v2
	v_exp_f32_e32 v81, v2
	s_nop 0
	v_pk_add_f32 v[80:81], v[80:81], 1.0 op_sel_hi:[1,0]
	s_nop 0
	v_rcp_f32_e32 v86, v81
	s_nop 0
	v_fma_f32 v87, -v81, v86, 1.0
	v_fmac_f32_e32 v86, v87, v86
	v_div_fixup_f32 v81, v86, v81, 1.0
	v_rcp_f32_e32 v86, v80
	s_nop 0
	v_fma_f32 v87, -v80, v86, 1.0
	v_fmac_f32_e32 v86, v87, v86
	v_div_fixup_f32 v80, v86, v80, 1.0
	v_lshlrev_b32_e32 v2, 16, v144
	v_mul_f32_e32 v2, 0xbfb8aa3b, v2
	v_pk_mul_f32 v[72:73], v[72:73], v[80:81]
	v_exp_f32_e32 v80, v2
	v_and_b32_e32 v2, 0xffff0000, v144
	v_mul_f32_e32 v2, 0xbfb8aa3b, v2
	v_exp_f32_e32 v81, v2
	s_nop 0
	v_pk_add_f32 v[80:81], v[80:81], 1.0 op_sel_hi:[1,0]
	s_nop 0
	v_rcp_f32_e32 v86, v81
	s_nop 0
	v_fma_f32 v87, -v81, v86, 1.0
	v_fmac_f32_e32 v86, v87, v86
	v_div_fixup_f32 v81, v86, v81, 1.0
	v_rcp_f32_e32 v86, v80
	s_nop 0
	v_fma_f32 v87, -v80, v86, 1.0
	v_fmac_f32_e32 v86, v87, v86
	v_div_fixup_f32 v80, v86, v80, 1.0
	v_lshlrev_b32_e32 v2, 16, v145
	v_mul_f32_e32 v2, 0xbfb8aa3b, v2
	v_pk_mul_f32 v[66:67], v[66:67], v[80:81]
	v_exp_f32_e32 v80, v2
	v_and_b32_e32 v2, 0xffff0000, v145
	v_mul_f32_e32 v2, 0xbfb8aa3b, v2
	v_exp_f32_e32 v81, v2
	s_nop 0
	v_pk_add_f32 v[80:81], v[80:81], 1.0 op_sel_hi:[1,0]
	s_nop 0
	v_rcp_f32_e32 v86, v81
	s_nop 0
	v_fma_f32 v87, -v81, v86, 1.0
	v_fmac_f32_e32 v86, v87, v86
	v_div_fixup_f32 v81, v86, v81, 1.0
	v_rcp_f32_e32 v86, v80
	s_nop 0
	v_fma_f32 v87, -v80, v86, 1.0
	v_fmac_f32_e32 v86, v87, v86
	v_div_fixup_f32 v80, v86, v80, 1.0
	v_pk_mul_f32 v[80:81], v[68:69], v[80:81]
	v_cvt_pk_bf16_f32 v68, v70, v71
	v_cvt_pk_bf16_f32 v70, v66, v67
	v_lshl_add_u64 v[66:67], s[12:13], 0, v[78:79]
	v_lshlrev_b32_e32 v2, 16, v130
	v_cvt_pk_bf16_f32 v69, v72, v73
	v_cvt_pk_bf16_f32 v71, v80, v81
	v_lshl_add_u64 v[66:67], v[66:67], 0, v[4:5]
	v_mul_f32_e32 v2, 0xbfb8aa3b, v2
	global_store_dwordx4 v[66:67], v[68:71], off
	s_nop 1
	v_exp_f32_e32 v68, v2
	v_and_b32_e32 v2, 0xffff0000, v130
	v_mul_f32_e32 v2, 0xbfb8aa3b, v2
	v_exp_f32_e32 v69, v2
	s_nop 0
	v_pk_add_f32 v[68:69], v[68:69], 1.0 op_sel_hi:[1,0]
	s_nop 0
	v_rcp_f32_e32 v70, v69
	s_nop 0
	v_fma_f32 v71, -v69, v70, 1.0
	v_fmac_f32_e32 v70, v71, v70
	v_div_fixup_f32 v69, v70, v69, 1.0
	v_rcp_f32_e32 v70, v68
	s_nop 0
	v_fma_f32 v71, -v68, v70, 1.0
	v_fmac_f32_e32 v70, v71, v70
	v_div_fixup_f32 v68, v70, v68, 1.0
	v_lshlrev_b32_e32 v2, 16, v131
	v_mul_f32_e32 v2, 0xbfb8aa3b, v2
	v_pk_mul_f32 v[58:59], v[58:59], v[68:69]
	v_exp_f32_e32 v68, v2
	v_and_b32_e32 v2, 0xffff0000, v131
	v_mul_f32_e32 v2, 0xbfb8aa3b, v2
	v_exp_f32_e32 v69, v2
	s_nop 0
	v_pk_add_f32 v[68:69], v[68:69], 1.0 op_sel_hi:[1,0]
	s_nop 0
	v_rcp_f32_e32 v70, v69
	s_nop 0
	v_fma_f32 v71, -v69, v70, 1.0
	v_fmac_f32_e32 v70, v71, v70
	v_div_fixup_f32 v69, v70, v69, 1.0
	v_rcp_f32_e32 v70, v68
	s_nop 0
	v_fma_f32 v71, -v68, v70, 1.0
	v_fmac_f32_e32 v70, v71, v70
	v_div_fixup_f32 v68, v70, v68, 1.0
	v_lshlrev_b32_e32 v2, 16, v132
	v_mul_f32_e32 v2, 0xbfb8aa3b, v2
	v_pk_mul_f32 v[60:61], v[60:61], v[68:69]
	v_exp_f32_e32 v68, v2
	v_and_b32_e32 v2, 0xffff0000, v132
	v_mul_f32_e32 v2, 0xbfb8aa3b, v2
	v_exp_f32_e32 v69, v2
	s_nop 0
	v_pk_add_f32 v[68:69], v[68:69], 1.0 op_sel_hi:[1,0]
	s_nop 0
	v_rcp_f32_e32 v70, v69
	s_nop 0
	v_fma_f32 v71, -v69, v70, 1.0
	v_fmac_f32_e32 v70, v71, v70
	v_div_fixup_f32 v69, v70, v69, 1.0
	v_rcp_f32_e32 v70, v68
	s_nop 0
	v_fma_f32 v71, -v68, v70, 1.0
	v_fmac_f32_e32 v70, v71, v70
	v_div_fixup_f32 v68, v70, v68, 1.0
	v_lshlrev_b32_e32 v2, 16, v133
	v_mul_f32_e32 v2, 0xbfb8aa3b, v2
	v_pk_mul_f32 v[68:69], v[54:55], v[68:69]
	v_exp_f32_e32 v54, v2
	v_and_b32_e32 v2, 0xffff0000, v133
	v_mul_f32_e32 v2, 0xbfb8aa3b, v2
	v_exp_f32_e32 v55, v2
	s_nop 0
	v_pk_add_f32 v[54:55], v[54:55], 1.0 op_sel_hi:[1,0]
	s_nop 0
	v_rcp_f32_e32 v70, v55
	s_nop 0
	v_fma_f32 v71, -v55, v70, 1.0
	v_fmac_f32_e32 v70, v71, v70
	v_div_fixup_f32 v55, v70, v55, 1.0
	v_rcp_f32_e32 v70, v54
	s_nop 0
	v_fma_f32 v71, -v54, v70, 1.0
	v_fmac_f32_e32 v70, v71, v70
	v_div_fixup_f32 v54, v70, v54, 1.0
	v_pk_mul_f32 v[70:71], v[56:57], v[54:55]
	v_lshlrev_b32_e32 v2, 16, v118
	v_cvt_pk_bf16_f32 v54, v58, v59
	v_cvt_pk_bf16_f32 v55, v60, v61
	v_cvt_pk_bf16_f32 v56, v68, v69
	v_cvt_pk_bf16_f32 v57, v70, v71
	v_mul_f32_e32 v2, 0xbfb8aa3b, v2
	global_store_dwordx4 v[66:67], v[54:57], off offset:256
	s_nop 1
	v_exp_f32_e32 v56, v2
	v_and_b32_e32 v2, 0xffff0000, v118
	v_mul_f32_e32 v2, 0xbfb8aa3b, v2
	v_exp_f32_e32 v57, v2
	v_lshlrev_b64 v[54:55], 12, v[220:221]
	v_pk_add_f32 v[56:57], v[56:57], 1.0 op_sel_hi:[1,0]
	s_nop 0
	v_rcp_f32_e32 v58, v57
	s_nop 0
	v_fma_f32 v59, -v57, v58, 1.0
	v_fmac_f32_e32 v58, v59, v58
	v_div_fixup_f32 v57, v58, v57, 1.0
	v_rcp_f32_e32 v58, v56
	s_nop 0
	v_fma_f32 v59, -v56, v58, 1.0
	v_fmac_f32_e32 v58, v59, v58
	v_div_fixup_f32 v56, v58, v56, 1.0
	v_lshlrev_b32_e32 v2, 16, v119
	v_mul_f32_e32 v2, 0xbfb8aa3b, v2
	v_pk_mul_f32 v[50:51], v[50:51], v[56:57]
	v_exp_f32_e32 v56, v2
	v_and_b32_e32 v2, 0xffff0000, v119
	v_mul_f32_e32 v2, 0xbfb8aa3b, v2
	v_exp_f32_e32 v57, v2
	s_nop 0
	v_pk_add_f32 v[56:57], v[56:57], 1.0 op_sel_hi:[1,0]
	s_nop 0
	v_rcp_f32_e32 v58, v57
	s_nop 0
	v_fma_f32 v59, -v57, v58, 1.0
	v_fmac_f32_e32 v58, v59, v58
	v_div_fixup_f32 v57, v58, v57, 1.0
	v_rcp_f32_e32 v58, v56
	s_nop 0
	v_fma_f32 v59, -v56, v58, 1.0
	v_fmac_f32_e32 v58, v59, v58
	v_div_fixup_f32 v56, v58, v56, 1.0
	v_lshlrev_b32_e32 v2, 16, v120
	v_mul_f32_e32 v2, 0xbfb8aa3b, v2
	v_pk_mul_f32 v[52:53], v[52:53], v[56:57]
	v_exp_f32_e32 v56, v2
	v_and_b32_e32 v2, 0xffff0000, v120
	v_mul_f32_e32 v2, 0xbfb8aa3b, v2
	v_exp_f32_e32 v57, v2
	s_nop 0
	v_pk_add_f32 v[56:57], v[56:57], 1.0 op_sel_hi:[1,0]
	s_nop 0
	v_rcp_f32_e32 v58, v57
	s_nop 0
	v_fma_f32 v59, -v57, v58, 1.0
	v_fmac_f32_e32 v58, v59, v58
	v_div_fixup_f32 v57, v58, v57, 1.0
	v_rcp_f32_e32 v58, v56
	s_nop 0
	v_fma_f32 v59, -v56, v58, 1.0
	v_fmac_f32_e32 v58, v59, v58
	v_div_fixup_f32 v56, v58, v56, 1.0
	v_lshlrev_b32_e32 v2, 16, v121
	v_mul_f32_e32 v2, 0xbfb8aa3b, v2
	v_pk_mul_f32 v[46:47], v[46:47], v[56:57]
	v_exp_f32_e32 v56, v2
	v_and_b32_e32 v2, 0xffff0000, v121
	v_mul_f32_e32 v2, 0xbfb8aa3b, v2
	v_exp_f32_e32 v57, v2
	s_nop 0
	v_pk_add_f32 v[56:57], v[56:57], 1.0 op_sel_hi:[1,0]
	s_nop 0
	v_rcp_f32_e32 v58, v57
	s_nop 0
	v_fma_f32 v59, -v57, v58, 1.0
	v_fmac_f32_e32 v58, v59, v58
	v_div_fixup_f32 v57, v58, v57, 1.0
	v_rcp_f32_e32 v58, v56
	s_nop 0
	v_fma_f32 v59, -v56, v58, 1.0
	v_fmac_f32_e32 v58, v59, v58
	v_div_fixup_f32 v56, v58, v56, 1.0
	v_pk_mul_f32 v[56:57], v[48:49], v[56:57]
	v_cvt_pk_bf16_f32 v48, v50, v51
	v_cvt_pk_bf16_f32 v50, v46, v47
	v_lshl_add_u64 v[46:47], s[12:13], 0, v[54:55]
	v_lshlrev_b32_e32 v2, 16, v106
	v_cvt_pk_bf16_f32 v49, v52, v53
	v_cvt_pk_bf16_f32 v51, v56, v57
	v_lshl_add_u64 v[46:47], v[46:47], 0, v[4:5]
	v_mul_f32_e32 v2, 0xbfb8aa3b, v2
	global_store_dwordx4 v[46:47], v[48:51], off
	s_nop 1
	v_exp_f32_e32 v48, v2
	v_and_b32_e32 v2, 0xffff0000, v106
	v_mul_f32_e32 v2, 0xbfb8aa3b, v2
	v_exp_f32_e32 v49, v2
	s_nop 0
	v_pk_add_f32 v[48:49], v[48:49], 1.0 op_sel_hi:[1,0]
	s_nop 0
	v_rcp_f32_e32 v50, v49
	s_nop 0
	v_fma_f32 v51, -v49, v50, 1.0
	v_fmac_f32_e32 v50, v51, v50
	v_div_fixup_f32 v49, v50, v49, 1.0
	v_rcp_f32_e32 v50, v48
	s_nop 0
	v_fma_f32 v51, -v48, v50, 1.0
	v_fmac_f32_e32 v50, v51, v50
	v_div_fixup_f32 v48, v50, v48, 1.0
	v_lshlrev_b32_e32 v2, 16, v107
	v_mul_f32_e32 v2, 0xbfb8aa3b, v2
	v_pk_mul_f32 v[42:43], v[42:43], v[48:49]
	v_exp_f32_e32 v48, v2
	v_and_b32_e32 v2, 0xffff0000, v107
	v_mul_f32_e32 v2, 0xbfb8aa3b, v2
	v_exp_f32_e32 v49, v2
	s_nop 0
	v_pk_add_f32 v[48:49], v[48:49], 1.0 op_sel_hi:[1,0]
	s_nop 0
	v_rcp_f32_e32 v50, v49
	s_nop 0
	v_fma_f32 v51, -v49, v50, 1.0
	v_fmac_f32_e32 v50, v51, v50
	v_div_fixup_f32 v49, v50, v49, 1.0
	v_rcp_f32_e32 v50, v48
	s_nop 0
	v_fma_f32 v51, -v48, v50, 1.0
	v_fmac_f32_e32 v50, v51, v50
	v_div_fixup_f32 v48, v50, v48, 1.0
	v_lshlrev_b32_e32 v2, 16, v108
	v_mul_f32_e32 v2, 0xbfb8aa3b, v2
	v_pk_mul_f32 v[44:45], v[44:45], v[48:49]
	v_exp_f32_e32 v48, v2
	v_and_b32_e32 v2, 0xffff0000, v108
	v_mul_f32_e32 v2, 0xbfb8aa3b, v2
	v_exp_f32_e32 v49, v2
	s_nop 0
	v_pk_add_f32 v[48:49], v[48:49], 1.0 op_sel_hi:[1,0]
	s_nop 0
	v_rcp_f32_e32 v50, v49
	s_nop 0
	v_fma_f32 v51, -v49, v50, 1.0
	v_fmac_f32_e32 v50, v51, v50
	v_div_fixup_f32 v49, v50, v49, 1.0
	v_rcp_f32_e32 v50, v48
	s_nop 0
	v_fma_f32 v51, -v48, v50, 1.0
	v_fmac_f32_e32 v50, v51, v50
	v_div_fixup_f32 v48, v50, v48, 1.0
	v_lshlrev_b32_e32 v2, 16, v109
	v_mul_f32_e32 v2, 0xbfb8aa3b, v2
	v_pk_mul_f32 v[48:49], v[38:39], v[48:49]
	v_exp_f32_e32 v38, v2
	v_and_b32_e32 v2, 0xffff0000, v109
	v_mul_f32_e32 v2, 0xbfb8aa3b, v2
	v_exp_f32_e32 v39, v2
	s_nop 0
	v_pk_add_f32 v[38:39], v[38:39], 1.0 op_sel_hi:[1,0]
	s_nop 0
	v_rcp_f32_e32 v50, v39
	s_nop 0
	v_fma_f32 v51, -v39, v50, 1.0
	v_fmac_f32_e32 v50, v51, v50
	v_div_fixup_f32 v39, v50, v39, 1.0
	v_rcp_f32_e32 v50, v38
	s_nop 0
	v_fma_f32 v51, -v38, v50, 1.0
	v_fmac_f32_e32 v50, v51, v50
	v_div_fixup_f32 v38, v50, v38, 1.0
	v_pk_mul_f32 v[50:51], v[40:41], v[38:39]
	v_lshlrev_b32_e32 v2, 16, v94
	v_cvt_pk_bf16_f32 v38, v42, v43
	v_cvt_pk_bf16_f32 v39, v44, v45
	v_cvt_pk_bf16_f32 v40, v48, v49
	v_cvt_pk_bf16_f32 v41, v50, v51
	v_mul_f32_e32 v2, 0xbfb8aa3b, v2
	global_store_dwordx4 v[46:47], v[38:41], off offset:256
	s_nop 1
	v_exp_f32_e32 v40, v2
	v_and_b32_e32 v2, 0xffff0000, v94
	v_mul_f32_e32 v2, 0xbfb8aa3b, v2
	v_exp_f32_e32 v41, v2
	v_lshlrev_b64 v[38:39], 12, v[218:219]
	v_pk_add_f32 v[40:41], v[40:41], 1.0 op_sel_hi:[1,0]
	s_nop 0
	v_rcp_f32_e32 v42, v41
	s_nop 0
	v_fma_f32 v43, -v41, v42, 1.0
	v_fmac_f32_e32 v42, v43, v42
	v_div_fixup_f32 v41, v42, v41, 1.0
	v_rcp_f32_e32 v42, v40
	s_nop 0
	v_fma_f32 v43, -v40, v42, 1.0
	v_fmac_f32_e32 v42, v43, v42
	v_div_fixup_f32 v40, v42, v40, 1.0
	v_lshlrev_b32_e32 v2, 16, v95
	v_mul_f32_e32 v2, 0xbfb8aa3b, v2
	v_pk_mul_f32 v[34:35], v[34:35], v[40:41]
	v_exp_f32_e32 v40, v2
	v_and_b32_e32 v2, 0xffff0000, v95
	v_mul_f32_e32 v2, 0xbfb8aa3b, v2
	v_exp_f32_e32 v41, v2
	s_nop 0
	v_pk_add_f32 v[40:41], v[40:41], 1.0 op_sel_hi:[1,0]
	s_nop 0
	v_rcp_f32_e32 v42, v41
	s_nop 0
	v_fma_f32 v43, -v41, v42, 1.0
	v_fmac_f32_e32 v42, v43, v42
	v_div_fixup_f32 v41, v42, v41, 1.0
	v_rcp_f32_e32 v42, v40
	s_nop 0
	v_fma_f32 v43, -v40, v42, 1.0
	v_fmac_f32_e32 v42, v43, v42
	v_div_fixup_f32 v40, v42, v40, 1.0
	v_lshlrev_b32_e32 v2, 16, v96
	v_mul_f32_e32 v2, 0xbfb8aa3b, v2
	v_pk_mul_f32 v[36:37], v[36:37], v[40:41]
	v_exp_f32_e32 v40, v2
	v_and_b32_e32 v2, 0xffff0000, v96
	v_mul_f32_e32 v2, 0xbfb8aa3b, v2
	v_exp_f32_e32 v41, v2
	s_nop 0
	v_pk_add_f32 v[40:41], v[40:41], 1.0 op_sel_hi:[1,0]
	s_nop 0
	v_rcp_f32_e32 v42, v41
	s_nop 0
	v_fma_f32 v43, -v41, v42, 1.0
	v_fmac_f32_e32 v42, v43, v42
	v_div_fixup_f32 v41, v42, v41, 1.0
	v_rcp_f32_e32 v42, v40
	s_nop 0
	v_fma_f32 v43, -v40, v42, 1.0
	v_fmac_f32_e32 v42, v43, v42
	v_div_fixup_f32 v40, v42, v40, 1.0
	v_lshlrev_b32_e32 v2, 16, v97
	v_mul_f32_e32 v2, 0xbfb8aa3b, v2
	v_pk_mul_f32 v[30:31], v[30:31], v[40:41]
	v_exp_f32_e32 v40, v2
	v_and_b32_e32 v2, 0xffff0000, v97
	v_mul_f32_e32 v2, 0xbfb8aa3b, v2
	v_exp_f32_e32 v41, v2
	s_nop 0
	v_pk_add_f32 v[40:41], v[40:41], 1.0 op_sel_hi:[1,0]
	s_nop 0
	v_rcp_f32_e32 v42, v41
	s_nop 0
	v_fma_f32 v43, -v41, v42, 1.0
	v_fmac_f32_e32 v42, v43, v42
	v_div_fixup_f32 v41, v42, v41, 1.0
	v_rcp_f32_e32 v42, v40
	s_nop 0
	v_fma_f32 v43, -v40, v42, 1.0
	v_fmac_f32_e32 v42, v43, v42
	v_div_fixup_f32 v40, v42, v40, 1.0
	v_pk_mul_f32 v[40:41], v[32:33], v[40:41]
	v_cvt_pk_bf16_f32 v32, v34, v35
	v_cvt_pk_bf16_f32 v34, v30, v31
	v_lshl_add_u64 v[30:31], s[12:13], 0, v[38:39]
	v_lshlrev_b32_e32 v2, 16, v82
	v_cvt_pk_bf16_f32 v33, v36, v37
	v_cvt_pk_bf16_f32 v35, v40, v41
	v_lshl_add_u64 v[30:31], v[30:31], 0, v[4:5]
	v_mul_f32_e32 v2, 0xbfb8aa3b, v2
	global_store_dwordx4 v[30:31], v[32:35], off
	s_nop 1
	v_exp_f32_e32 v32, v2
	v_and_b32_e32 v2, 0xffff0000, v82
	v_mul_f32_e32 v2, 0xbfb8aa3b, v2
	v_exp_f32_e32 v33, v2
	s_nop 0
	v_pk_add_f32 v[32:33], v[32:33], 1.0 op_sel_hi:[1,0]
	s_nop 0
	v_rcp_f32_e32 v34, v33
	s_nop 0
	v_fma_f32 v35, -v33, v34, 1.0
	v_fmac_f32_e32 v34, v35, v34
	v_div_fixup_f32 v33, v34, v33, 1.0
	v_rcp_f32_e32 v34, v32
	s_nop 0
	v_fma_f32 v35, -v32, v34, 1.0
	v_fmac_f32_e32 v34, v35, v34
	v_div_fixup_f32 v32, v34, v32, 1.0
	v_lshlrev_b32_e32 v2, 16, v83
	v_mul_f32_e32 v2, 0xbfb8aa3b, v2
	v_pk_mul_f32 v[26:27], v[26:27], v[32:33]
	v_exp_f32_e32 v32, v2
	v_and_b32_e32 v2, 0xffff0000, v83
	v_mul_f32_e32 v2, 0xbfb8aa3b, v2
	v_exp_f32_e32 v33, v2
	s_nop 0
	v_pk_add_f32 v[32:33], v[32:33], 1.0 op_sel_hi:[1,0]
	s_nop 0
	v_rcp_f32_e32 v34, v33
	s_nop 0
	v_fma_f32 v35, -v33, v34, 1.0
	v_fmac_f32_e32 v34, v35, v34
	v_div_fixup_f32 v33, v34, v33, 1.0
	v_rcp_f32_e32 v34, v32
	s_nop 0
	v_fma_f32 v35, -v32, v34, 1.0
	v_fmac_f32_e32 v34, v35, v34
	v_div_fixup_f32 v32, v34, v32, 1.0
	v_lshlrev_b32_e32 v2, 16, v84
	v_mul_f32_e32 v2, 0xbfb8aa3b, v2
	v_pk_mul_f32 v[28:29], v[28:29], v[32:33]
	v_exp_f32_e32 v32, v2
	v_and_b32_e32 v2, 0xffff0000, v84
	v_mul_f32_e32 v2, 0xbfb8aa3b, v2
	v_exp_f32_e32 v33, v2
	s_nop 0
	v_pk_add_f32 v[32:33], v[32:33], 1.0 op_sel_hi:[1,0]
	s_nop 0
	v_rcp_f32_e32 v34, v33
	s_nop 0
	v_fma_f32 v35, -v33, v34, 1.0
	v_fmac_f32_e32 v34, v35, v34
	v_div_fixup_f32 v33, v34, v33, 1.0
	v_rcp_f32_e32 v34, v32
	s_nop 0
	v_fma_f32 v35, -v32, v34, 1.0
	v_fmac_f32_e32 v34, v35, v34
	v_div_fixup_f32 v32, v34, v32, 1.0
	v_lshlrev_b32_e32 v2, 16, v85
	v_mul_f32_e32 v2, 0xbfb8aa3b, v2
	v_pk_mul_f32 v[32:33], v[22:23], v[32:33]
	v_exp_f32_e32 v22, v2
	v_and_b32_e32 v2, 0xffff0000, v85
	v_mul_f32_e32 v2, 0xbfb8aa3b, v2
	v_exp_f32_e32 v23, v2
	s_nop 0
	v_pk_add_f32 v[22:23], v[22:23], 1.0 op_sel_hi:[1,0]
	s_nop 0
	v_rcp_f32_e32 v34, v23
	s_nop 0
	v_fma_f32 v35, -v23, v34, 1.0
	v_fmac_f32_e32 v34, v35, v34
	v_div_fixup_f32 v23, v34, v23, 1.0
	v_rcp_f32_e32 v34, v22
	s_nop 0
	v_fma_f32 v35, -v22, v34, 1.0
	v_fmac_f32_e32 v34, v35, v34
	v_div_fixup_f32 v22, v34, v22, 1.0
	v_pk_mul_f32 v[34:35], v[24:25], v[22:23]
	v_lshlrev_b32_e32 v2, 16, v74
	v_cvt_pk_bf16_f32 v22, v26, v27
	v_cvt_pk_bf16_f32 v23, v28, v29
	v_cvt_pk_bf16_f32 v24, v32, v33
	v_cvt_pk_bf16_f32 v25, v34, v35
	v_mul_f32_e32 v2, 0xbfb8aa3b, v2
	global_store_dwordx4 v[30:31], v[22:25], off offset:256
	s_nop 1
	v_exp_f32_e32 v24, v2
	v_and_b32_e32 v2, 0xffff0000, v74
	v_mul_f32_e32 v2, 0xbfb8aa3b, v2
	v_exp_f32_e32 v25, v2
	v_lshlrev_b64 v[22:23], 12, v[216:217]
	v_pk_add_f32 v[24:25], v[24:25], 1.0 op_sel_hi:[1,0]
	s_nop 0
	v_rcp_f32_e32 v26, v25
	s_nop 0
	v_fma_f32 v27, -v25, v26, 1.0
	v_fmac_f32_e32 v26, v27, v26
	v_div_fixup_f32 v25, v26, v25, 1.0
	v_rcp_f32_e32 v26, v24
	s_nop 0
	v_fma_f32 v27, -v24, v26, 1.0
	v_fmac_f32_e32 v26, v27, v26
	v_div_fixup_f32 v24, v26, v24, 1.0
	v_lshlrev_b32_e32 v2, 16, v75
	v_mul_f32_e32 v2, 0xbfb8aa3b, v2
	v_pk_mul_f32 v[18:19], v[18:19], v[24:25]
	v_exp_f32_e32 v24, v2
	v_and_b32_e32 v2, 0xffff0000, v75
	v_mul_f32_e32 v2, 0xbfb8aa3b, v2
	v_exp_f32_e32 v25, v2
	s_nop 0
	v_pk_add_f32 v[24:25], v[24:25], 1.0 op_sel_hi:[1,0]
	s_nop 0
	v_rcp_f32_e32 v26, v25
	s_nop 0
	v_fma_f32 v27, -v25, v26, 1.0
	v_fmac_f32_e32 v26, v27, v26
	v_div_fixup_f32 v25, v26, v25, 1.0
	v_rcp_f32_e32 v26, v24
	s_nop 0
	v_fma_f32 v27, -v24, v26, 1.0
	v_fmac_f32_e32 v26, v27, v26
	v_div_fixup_f32 v24, v26, v24, 1.0
	v_lshlrev_b32_e32 v2, 16, v76
	v_mul_f32_e32 v2, 0xbfb8aa3b, v2
	v_pk_mul_f32 v[20:21], v[20:21], v[24:25]
	v_exp_f32_e32 v24, v2
	v_and_b32_e32 v2, 0xffff0000, v76
	v_mul_f32_e32 v2, 0xbfb8aa3b, v2
	v_exp_f32_e32 v25, v2
	s_nop 0
	v_pk_add_f32 v[24:25], v[24:25], 1.0 op_sel_hi:[1,0]
	s_nop 0
	v_rcp_f32_e32 v26, v25
	s_nop 0
	v_fma_f32 v27, -v25, v26, 1.0
	v_fmac_f32_e32 v26, v27, v26
	v_div_fixup_f32 v25, v26, v25, 1.0
	v_rcp_f32_e32 v26, v24
	s_nop 0
	v_fma_f32 v27, -v24, v26, 1.0
	v_fmac_f32_e32 v26, v27, v26
	v_div_fixup_f32 v24, v26, v24, 1.0
	v_lshlrev_b32_e32 v2, 16, v77
	v_mul_f32_e32 v2, 0xbfb8aa3b, v2
	v_pk_mul_f32 v[24:25], v[14:15], v[24:25]
	v_exp_f32_e32 v14, v2
	v_and_b32_e32 v2, 0xffff0000, v77
	v_mul_f32_e32 v2, 0xbfb8aa3b, v2
	v_exp_f32_e32 v15, v2
	s_nop 0
	v_pk_add_f32 v[14:15], v[14:15], 1.0 op_sel_hi:[1,0]
	s_nop 0
	v_rcp_f32_e32 v26, v15
	s_nop 0
	v_fma_f32 v27, -v15, v26, 1.0
	v_fmac_f32_e32 v26, v27, v26
	v_div_fixup_f32 v15, v26, v15, 1.0
	v_rcp_f32_e32 v26, v14
	s_nop 0
	v_fma_f32 v27, -v14, v26, 1.0
	v_fmac_f32_e32 v26, v27, v26
	v_div_fixup_f32 v14, v26, v14, 1.0
	v_pk_mul_f32 v[26:27], v[16:17], v[14:15]
	v_cvt_pk_bf16_f32 v14, v18, v19
	v_lshl_add_u64 v[18:19], s[12:13], 0, v[22:23]
	v_lshlrev_b32_e32 v2, 16, v62
	v_cvt_pk_bf16_f32 v15, v20, v21
	v_cvt_pk_bf16_f32 v16, v24, v25
	v_cvt_pk_bf16_f32 v17, v26, v27
	v_lshl_add_u64 v[4:5], v[18:19], 0, v[4:5]
	v_mul_f32_e32 v2, 0xbfb8aa3b, v2
	global_store_dwordx4 v[4:5], v[14:17], off
	s_nop 1
	v_exp_f32_e32 v14, v2
	v_and_b32_e32 v2, 0xffff0000, v62
	v_mul_f32_e32 v2, 0xbfb8aa3b, v2
	v_exp_f32_e32 v15, v2
	s_nop 0
	v_pk_add_f32 v[14:15], v[14:15], 1.0 op_sel_hi:[1,0]
	s_nop 0
	v_rcp_f32_e32 v16, v15
	s_nop 0
	v_fma_f32 v17, -v15, v16, 1.0
	v_fmac_f32_e32 v16, v17, v16
	v_div_fixup_f32 v15, v16, v15, 1.0
	v_rcp_f32_e32 v16, v14
	s_nop 0
	v_fma_f32 v17, -v14, v16, 1.0
	v_fmac_f32_e32 v16, v17, v16
	v_div_fixup_f32 v14, v16, v14, 1.0
	v_lshlrev_b32_e32 v2, 16, v63
	v_mul_f32_e32 v2, 0xbfb8aa3b, v2
	v_pk_mul_f32 v[10:11], v[10:11], v[14:15]
	v_exp_f32_e32 v14, v2
	v_and_b32_e32 v2, 0xffff0000, v63
	v_mul_f32_e32 v2, 0xbfb8aa3b, v2
	v_exp_f32_e32 v15, v2
	s_nop 0
	v_pk_add_f32 v[14:15], v[14:15], 1.0 op_sel_hi:[1,0]
	s_nop 0
	v_rcp_f32_e32 v16, v15
	s_nop 0
	v_fma_f32 v17, -v15, v16, 1.0
	v_fmac_f32_e32 v16, v17, v16
	v_div_fixup_f32 v15, v16, v15, 1.0
	v_rcp_f32_e32 v16, v14
	s_nop 0
	v_fma_f32 v17, -v14, v16, 1.0
	v_fmac_f32_e32 v16, v17, v16
	v_div_fixup_f32 v14, v16, v14, 1.0
	v_lshlrev_b32_e32 v2, 16, v64
	v_mul_f32_e32 v2, 0xbfb8aa3b, v2
	v_pk_mul_f32 v[12:13], v[12:13], v[14:15]
	v_exp_f32_e32 v14, v2
	v_and_b32_e32 v2, 0xffff0000, v64
	v_mul_f32_e32 v2, 0xbfb8aa3b, v2
	v_exp_f32_e32 v15, v2
	s_nop 0
	v_pk_add_f32 v[14:15], v[14:15], 1.0 op_sel_hi:[1,0]
	s_nop 0
	v_rcp_f32_e32 v16, v15
	s_nop 0
	v_fma_f32 v17, -v15, v16, 1.0
	v_fmac_f32_e32 v16, v17, v16
	v_div_fixup_f32 v15, v16, v15, 1.0
	v_rcp_f32_e32 v16, v14
	s_nop 0
	v_fma_f32 v17, -v14, v16, 1.0
	v_fmac_f32_e32 v16, v17, v16
	v_div_fixup_f32 v14, v16, v14, 1.0
	v_lshlrev_b32_e32 v2, 16, v65
	v_mul_f32_e32 v2, 0xbfb8aa3b, v2
	v_pk_mul_f32 v[14:15], v[6:7], v[14:15]
	v_exp_f32_e32 v6, v2
	v_and_b32_e32 v2, 0xffff0000, v65
	v_mul_f32_e32 v2, 0xbfb8aa3b, v2
	v_exp_f32_e32 v7, v2
	s_nop 0
	v_pk_add_f32 v[6:7], v[6:7], 1.0 op_sel_hi:[1,0]
	s_nop 0
	v_rcp_f32_e32 v16, v7
	s_nop 0
	v_fma_f32 v17, -v7, v16, 1.0
	v_fmac_f32_e32 v16, v17, v16
	v_div_fixup_f32 v7, v16, v7, 1.0
	v_rcp_f32_e32 v16, v6
	s_mov_b64 s[14:15], s[6:7]
	v_fma_f32 v17, -v6, v16, 1.0
	v_fmac_f32_e32 v16, v17, v16
	v_div_fixup_f32 v6, v16, v6, 1.0
	v_pk_mul_f32 v[16:17], v[8:9], v[6:7]
	v_cvt_pk_bf16_f32 v6, v10, v11
	v_cvt_pk_bf16_f32 v7, v12, v13
	v_cvt_pk_bf16_f32 v8, v14, v15
	v_cvt_pk_bf16_f32 v9, v16, v17
	global_store_dwordx4 v[4:5], v[6:9], off offset:256
	s_and_b64 vcc, exec, s[4:5]
	s_cbranch_vccnz .LBB0_818

.LBB0_1002:
	s_add_u32 s28, s26, 0x100
	s_addc_u32 s29, s27, 0
	s_add_i32 s58, 0, 0x10000
	v_add_u32_e32 v56, s58, v1
	ds_read_b128 v[44:47], v56
	ds_read_b128 v[48:51], v56 offset:1024
	ds_read_b128 v[52:55], v56 offset:2048
	ds_read_b128 v[56:59], v56 offset:3072
	s_cmp_eq_u32 s57, 28
	s_cselect_b32 s35, s21, s29
	s_cselect_b32 s34, s53, s28
	s_cselect_b32 s31, s19, s56
	s_cselect_b32 s30, s54, s55
	v_lshl_add_u64 v[190:191], s[26:27], 0, v[178:179]
	s_add_i32 m0, s42, 0xc000
	ds_read_b128 v[68:71], v200
	ds_read_b128 v[72:75], v200 offset:1024
	ds_read_b128 v[76:79], v200 offset:2048
	ds_read_b128 v[80:83], v200 offset:3072
	ds_read_b128 v[164:167], v200 offset:4096
	ds_read_b128 v[168:171], v200 offset:5120
	ds_read_b128 v[182:185], v200 offset:6144
	ds_read_b128 v[186:189], v200 offset:7168
	global_load_lds_dwordx4 v[190:191], off
	v_lshl_add_u64 v[190:191], s[26:27], 0, v[180:181]
	s_add_i32 m0, s42, 0xe000
	s_nop 0
	global_load_lds_dwordx4 v[190:191], off
	s_waitcnt lgkmcnt(8)
	s_barrier
	s_waitcnt lgkmcnt(0)
	s_setprio 1
	s_waitcnt lgkmcnt(0)
	v_mfma_f32_16x16x32_bf16 v[160:163], v[44:47], v[68:71], v[160:163]
	v_mfma_f32_16x16x32_bf16 v[160:163], v[48:51], v[72:75], v[160:163]
	v_mfma_f32_16x16x32_bf16 v[148:151], v[48:51], v[80:83], v[148:151]
	v_mfma_f32_16x16x32_bf16 v[148:151], v[44:47], v[76:79], v[148:151]
	v_mfma_f32_16x16x32_bf16 v[132:135], v[44:47], v[164:167], v[132:135]
	v_mfma_f32_16x16x32_bf16 v[132:135], v[48:51], v[168:171], v[132:135]
	v_mfma_f32_16x16x32_bf16 v[116:119], v[48:51], v[186:189], v[116:119]
	v_mfma_f32_16x16x32_bf16 v[116:119], v[44:47], v[182:185], v[116:119]
	v_mfma_f32_16x16x32_bf16 v[108:111], v[52:55], v[182:185], v[108:111]
	v_mfma_f32_16x16x32_bf16 v[108:111], v[56:59], v[186:189], v[108:111]
	v_mfma_f32_16x16x32_bf16 v[124:127], v[56:59], v[168:171], v[124:127]
	v_mfma_f32_16x16x32_bf16 v[124:127], v[52:55], v[164:167], v[124:127]
	v_mfma_f32_16x16x32_bf16 v[140:143], v[52:55], v[76:79], v[140:143]
	v_mfma_f32_16x16x32_bf16 v[140:143], v[56:59], v[80:83], v[140:143]
	v_mfma_f32_16x16x32_bf16 v[156:159], v[56:59], v[72:75], v[156:159]
	s_barrier
	v_mfma_f32_16x16x32_bf16 v[156:159], v[52:55], v[68:71], v[156:159]
	s_setprio 0
	s_add_i32 s59, 0, 0x14000
	v_add_u32_e32 v194, s59, v1
	s_add_i32 s26, s58, s41
	ds_read_b128 v[190:193], v194
	ds_read_b128 v[202:205], v194 offset:1024
	ds_read_b128 v[206:209], v194 offset:2048
	ds_read_b128 v[210:213], v194 offset:3072
	v_lshl_add_u64 v[194:195], s[30:31], 0, v[2:3]
	s_mov_b32 m0, s26
	v_lshl_add_u64 v[222:223], s[30:31], 0, v[172:173]
	global_load_lds_dwordx4 v[194:195], off
	s_add_i32 m0, s26, 0x2000
	s_nop 0
	global_load_lds_dwordx4 v[222:223], off
	s_barrier
	s_waitcnt lgkmcnt(0)
	s_setprio 1
	s_waitcnt lgkmcnt(0)
	v_mfma_f32_16x16x32_bf16 v[152:155], v[190:193], v[68:71], v[152:155]
	v_mfma_f32_16x16x32_bf16 v[152:155], v[202:205], v[72:75], v[152:155]
	v_mfma_f32_16x16x32_bf16 v[68:71], v[206:209], v[68:71], v[144:147]
	v_mfma_f32_16x16x32_bf16 v[68:71], v[210:213], v[72:75], v[68:71]
	v_mfma_f32_16x16x32_bf16 v[72:75], v[190:193], v[76:79], v[136:139]
	v_mfma_f32_16x16x32_bf16 v[72:75], v[202:205], v[80:83], v[72:75]
	v_mfma_f32_16x16x32_bf16 v[76:79], v[206:209], v[76:79], v[128:131]
	v_mfma_f32_16x16x32_bf16 v[76:79], v[210:213], v[80:83], v[76:79]
	v_mfma_f32_16x16x32_bf16 v[112:115], v[206:209], v[164:167], v[112:115]
	v_mfma_f32_16x16x32_bf16 v[112:115], v[210:213], v[168:171], v[112:115]
	v_mfma_f32_16x16x32_bf16 v[104:107], v[190:193], v[182:185], v[104:107]
	v_mfma_f32_16x16x32_bf16 v[104:107], v[202:205], v[186:189], v[104:107]
	v_mfma_f32_16x16x32_bf16 v[96:99], v[206:209], v[182:185], v[96:99]
	v_mfma_f32_16x16x32_bf16 v[96:99], v[210:213], v[186:189], v[96:99]
	v_mfma_f32_16x16x32_bf16 v[80:83], v[190:193], v[164:167], v[120:123]
	s_barrier
	v_mfma_f32_16x16x32_bf16 v[80:83], v[202:205], v[168:171], v[80:83]
	s_setprio 0
	s_mov_b32 m0, s42
	v_lshl_add_u64 v[224:225], s[34:35], 0, v[176:177]
	ds_read_b128 v[120:123], v200 offset:16384
	ds_read_b128 v[128:131], v200 offset:17408
	ds_read_b128 v[136:139], v200 offset:18432
	ds_read_b128 v[144:147], v200 offset:19456
	ds_read_b128 v[164:167], v200 offset:20480
	ds_read_b128 v[168:171], v200 offset:21504
	ds_read_b128 v[182:185], v200 offset:22528
	ds_read_b128 v[186:189], v200 offset:23552
	global_load_lds_dwordx4 v[224:225], off
	v_lshl_add_u64 v[226:227], s[34:35], 0, v[174:175]
	s_mov_b32 m0, s43
	s_nop 0
	global_load_lds_dwordx4 v[226:227], off
	s_waitcnt vmcnt(10)
	s_barrier
	s_waitcnt lgkmcnt(0)
	s_setprio 1
	s_waitcnt lgkmcnt(0)
	v_mfma_f32_16x16x32_bf16 v[100:103], v[44:47], v[120:123], v[100:103]
	v_mfma_f32_16x16x32_bf16 v[100:103], v[48:51], v[128:131], v[100:103]
	v_mfma_f32_16x16x32_bf16 v[84:87], v[48:51], v[144:147], v[84:87]
	v_mfma_f32_16x16x32_bf16 v[84:87], v[44:47], v[136:139], v[84:87]
	v_mfma_f32_16x16x32_bf16 v[36:39], v[44:47], v[164:167], v[36:39]
	v_mfma_f32_16x16x32_bf16 v[36:39], v[48:51], v[168:171], v[36:39]
	v_mfma_f32_16x16x32_bf16 v[16:19], v[48:51], v[186:189], v[16:19]
	v_mfma_f32_16x16x32_bf16 v[16:19], v[44:47], v[182:185], v[16:19]
	v_mfma_f32_16x16x32_bf16 v[12:15], v[52:55], v[182:185], v[12:15]
	v_mfma_f32_16x16x32_bf16 v[12:15], v[56:59], v[186:189], v[12:15]
	v_mfma_f32_16x16x32_bf16 v[28:31], v[56:59], v[168:171], v[28:31]
	v_mfma_f32_16x16x32_bf16 v[28:31], v[52:55], v[164:167], v[28:31]
	v_mfma_f32_16x16x32_bf16 v[60:63], v[52:55], v[136:139], v[60:63]
	v_mfma_f32_16x16x32_bf16 v[60:63], v[56:59], v[144:147], v[60:63]
	v_mfma_f32_16x16x32_bf16 v[92:95], v[56:59], v[128:131], v[92:95]
	s_barrier
	v_mfma_f32_16x16x32_bf16 v[92:95], v[52:55], v[120:123], v[92:95]
	s_setprio 0
	s_add_u32 s26, s30, 0x80000
	s_addc_u32 s27, s31, 0
	s_add_i32 s58, s59, s41
	v_lshl_add_u64 v[44:45], s[26:27], 0, v[2:3]
	s_mov_b32 m0, s58
	s_nop 0
	global_load_lds_dwordx4 v[44:45], off
	v_lshl_add_u64 v[44:45], s[26:27], 0, v[172:173]
	s_add_i32 m0, s58, 0x2000
	s_nop 0
	global_load_lds_dwordx4 v[44:45], off
	s_add_i32 s58, 0, 0x18000
	v_add_u32_e32 v44, s58, v1
	ds_read_b128 v[52:55], v44
	ds_read_b128 v[56:59], v44 offset:1024
	s_waitcnt vmcnt(6)
	s_barrier
	s_setprio 1
	v_mfma_f32_16x16x32_bf16 v[40:43], v[190:193], v[136:139], v[40:43]
	v_mfma_f32_16x16x32_bf16 v[40:43], v[202:205], v[144:147], v[40:43]
	v_mfma_f32_16x16x32_bf16 v[24:27], v[202:205], v[168:171], v[24:27]
	v_mfma_f32_16x16x32_bf16 v[24:27], v[190:193], v[164:167], v[24:27]
	v_mfma_f32_16x16x32_bf16 v[8:11], v[190:193], v[182:185], v[8:11]
	v_mfma_f32_16x16x32_bf16 v[8:11], v[202:205], v[186:189], v[8:11]
	v_mfma_f32_16x16x32_bf16 v[44:47], v[202:205], v[128:131], v[88:91]
	v_mfma_f32_16x16x32_bf16 v[44:47], v[190:193], v[120:123], v[44:47]
	v_mfma_f32_16x16x32_bf16 v[48:51], v[206:209], v[120:123], v[64:67]
	v_mfma_f32_16x16x32_bf16 v[48:51], v[210:213], v[128:131], v[48:51]
	v_mfma_f32_16x16x32_bf16 v[4:7], v[210:213], v[186:189], v[4:7]
	v_mfma_f32_16x16x32_bf16 v[4:7], v[206:209], v[182:185], v[4:7]
	v_mfma_f32_16x16x32_bf16 v[20:23], v[206:209], v[164:167], v[20:23]
	v_mfma_f32_16x16x32_bf16 v[20:23], v[210:213], v[168:171], v[20:23]
	v_mfma_f32_16x16x32_bf16 v[32:35], v[210:213], v[144:147], v[32:35]
	s_barrier
	v_mfma_f32_16x16x32_bf16 v[32:35], v[206:209], v[136:139], v[32:35]
	s_setprio 0
	v_add_u32_e32 v88, s58, v1
	ds_read_b128 v[64:67], v88 offset:2048
	ds_read_b128 v[88:91], v88 offset:3072
	s_add_u32 s26, s34, 0x4000
	s_addc_u32 s27, s35, 0
	s_mov_b32 m0, s44
	v_lshl_add_u64 v[136:137], s[26:27], 0, v[176:177]
	ds_read_b128 v[120:123], v200 offset:32768
	ds_read_b128 v[128:131], v200 offset:33792
	ds_read_b128 v[164:167], v200 offset:34816
	ds_read_b128 v[168:171], v200 offset:35840
	ds_read_b128 v[182:185], v200 offset:36864
	ds_read_b128 v[186:189], v200 offset:37888
	ds_read_b128 v[190:193], v200 offset:38912
	ds_read_b128 v[202:205], v200 offset:39936
	global_load_lds_dwordx4 v[136:137], off
	v_lshl_add_u64 v[136:137], s[26:27], 0, v[174:175]
	s_mov_b32 m0, s45
	s_nop 0
	global_load_lds_dwordx4 v[136:137], off
	s_waitcnt lgkmcnt(8)
	s_barrier
	s_waitcnt lgkmcnt(0)
	s_setprio 1
	s_waitcnt lgkmcnt(0)
	v_mfma_f32_16x16x32_bf16 v[136:139], v[52:55], v[120:123], v[160:163]
	v_mfma_f32_16x16x32_bf16 v[160:163], v[56:59], v[128:131], v[136:139]
	v_mfma_f32_16x16x32_bf16 v[136:139], v[64:67], v[120:123], v[156:159]
	v_mfma_f32_16x16x32_bf16 v[156:159], v[88:91], v[128:131], v[136:139]
	v_mfma_f32_16x16x32_bf16 v[136:139], v[52:55], v[164:167], v[148:151]
	v_mfma_f32_16x16x32_bf16 v[148:151], v[56:59], v[168:171], v[136:139]
	v_mfma_f32_16x16x32_bf16 v[136:139], v[64:67], v[164:167], v[140:143]
	v_mfma_f32_16x16x32_bf16 v[140:143], v[88:91], v[168:171], v[136:139]
	v_mfma_f32_16x16x32_bf16 v[132:135], v[52:55], v[182:185], v[132:135]
	v_mfma_f32_16x16x32_bf16 v[132:135], v[56:59], v[186:189], v[132:135]
	v_mfma_f32_16x16x32_bf16 v[124:127], v[64:67], v[182:185], v[124:127]
	v_mfma_f32_16x16x32_bf16 v[124:127], v[88:91], v[186:189], v[124:127]
	v_mfma_f32_16x16x32_bf16 v[116:119], v[52:55], v[190:193], v[116:119]
	v_mfma_f32_16x16x32_bf16 v[116:119], v[56:59], v[202:205], v[116:119]
	v_mfma_f32_16x16x32_bf16 v[108:111], v[64:67], v[190:193], v[108:111]
	s_barrier
	v_mfma_f32_16x16x32_bf16 v[108:111], v[88:91], v[202:205], v[108:111]
	s_setprio 0
	s_add_i32 s34, 0, 0x1c000
	v_add_u32_e32 v136, s34, v1
	s_add_i32 s26, s58, s41
	ds_read_b128 v[206:209], v136
	ds_read_b128 v[210:213], v136 offset:1024
	ds_read_b128 v[214:217], v136 offset:2048
	ds_read_b128 v[218:221], v136 offset:3072
	v_lshl_add_u64 v[136:137], v[194:195], 0, s[2:3]
	s_mov_b32 m0, s26
	s_nop 0
	global_load_lds_dwordx4 v[136:137], off
	v_lshl_add_u64 v[136:137], v[222:223], 0, s[2:3]
	s_add_i32 m0, s26, 0x2000
	s_nop 0
	global_load_lds_dwordx4 v[136:137], off
	s_barrier
	s_waitcnt lgkmcnt(0)
	s_setprio 1
	s_waitcnt lgkmcnt(0)
	v_mfma_f32_16x16x32_bf16 v[68:71], v[214:217], v[120:123], v[68:71]
	v_mfma_f32_16x16x32_bf16 v[144:147], v[218:221], v[128:131], v[68:71]
	v_mfma_f32_16x16x32_bf16 v[136:139], v[206:209], v[120:123], v[152:155]
	v_mfma_f32_16x16x32_bf16 v[152:155], v[210:213], v[128:131], v[136:139]
	v_mfma_f32_16x16x32_bf16 v[68:71], v[206:209], v[164:167], v[72:75]
	v_mfma_f32_16x16x32_bf16 v[136:139], v[210:213], v[168:171], v[68:71]
	v_mfma_f32_16x16x32_bf16 v[68:71], v[214:217], v[164:167], v[76:79]
	v_mfma_f32_16x16x32_bf16 v[128:131], v[218:221], v[168:171], v[68:71]
	v_mfma_f32_16x16x32_bf16 v[68:71], v[206:209], v[182:185], v[80:83]
	v_mfma_f32_16x16x32_bf16 v[120:123], v[210:213], v[186:189], v[68:71]
	v_mfma_f32_16x16x32_bf16 v[68:71], v[214:217], v[182:185], v[112:115]
	v_mfma_f32_16x16x32_bf16 v[112:115], v[218:221], v[186:189], v[68:71]
	v_mfma_f32_16x16x32_bf16 v[68:71], v[206:209], v[190:193], v[104:107]
	v_mfma_f32_16x16x32_bf16 v[104:107], v[210:213], v[202:205], v[68:71]
	v_mfma_f32_16x16x32_bf16 v[68:71], v[214:217], v[190:193], v[96:99]
	s_barrier
	v_mfma_f32_16x16x32_bf16 v[96:99], v[218:221], v[202:205], v[68:71]
	s_setprio 0
	s_mov_b32 m0, s48
	v_lshl_add_u64 v[190:191], v[224:225], 0, s[2:3]
	s_nop 2
	ds_read_b128 v[68:71], v200 offset:49152
	ds_read_b128 v[72:75], v200 offset:50176
	ds_read_b128 v[76:79], v200 offset:51200
	ds_read_b128 v[80:83], v200 offset:52224
	ds_read_b128 v[164:167], v200 offset:53248
	ds_read_b128 v[168:171], v200 offset:54272
	ds_read_b128 v[182:185], v200 offset:55296
	ds_read_b128 v[186:189], v200 offset:56320
	global_load_lds_dwordx4 v[190:191], off
	v_lshl_add_u64 v[190:191], v[226:227], 0, s[2:3]
	s_mov_b32 m0, s49
	s_nop 0
	global_load_lds_dwordx4 v[190:191], off
	s_barrier
	s_waitcnt lgkmcnt(0)
	s_setprio 1
	s_waitcnt lgkmcnt(0)
	v_mfma_f32_16x16x32_bf16 v[100:103], v[52:55], v[68:71], v[100:103]
	v_mfma_f32_16x16x32_bf16 v[100:103], v[56:59], v[72:75], v[100:103]
	v_mfma_f32_16x16x32_bf16 v[84:87], v[56:59], v[80:83], v[84:87]
	v_mfma_f32_16x16x32_bf16 v[84:87], v[52:55], v[76:79], v[84:87]
	v_mfma_f32_16x16x32_bf16 v[36:39], v[52:55], v[164:167], v[36:39]
	v_mfma_f32_16x16x32_bf16 v[36:39], v[56:59], v[168:171], v[36:39]
	v_mfma_f32_16x16x32_bf16 v[16:19], v[56:59], v[186:189], v[16:19]
	v_mfma_f32_16x16x32_bf16 v[16:19], v[52:55], v[182:185], v[16:19]
	v_mfma_f32_16x16x32_bf16 v[12:15], v[64:67], v[182:185], v[12:15]
	v_mfma_f32_16x16x32_bf16 v[12:15], v[88:91], v[186:189], v[12:15]
	v_mfma_f32_16x16x32_bf16 v[28:31], v[88:91], v[168:171], v[28:31]
	v_mfma_f32_16x16x32_bf16 v[28:31], v[64:67], v[164:167], v[28:31]
	v_mfma_f32_16x16x32_bf16 v[60:63], v[64:67], v[76:79], v[60:63]
	v_mfma_f32_16x16x32_bf16 v[60:63], v[88:91], v[80:83], v[60:63]
	v_mfma_f32_16x16x32_bf16 v[92:95], v[88:91], v[72:75], v[92:95]
	s_barrier
	v_mfma_f32_16x16x32_bf16 v[92:95], v[64:67], v[68:71], v[92:95]
	s_setprio 0
	s_add_u32 s26, s30, 0x80080
	s_addc_u32 s27, s31, 0
	s_add_i32 s30, s34, s41
	s_mov_b32 m0, s30
	s_nop 0
	global_load_lds_dwordx4 v2, s[26:27]
	s_add_i32 m0, s30, 0x2000
	s_nop 0
	global_load_lds_dwordx4 v172, s[26:27]
	s_waitcnt vmcnt(6)
	s_barrier
	s_setprio 1
	v_mfma_f32_16x16x32_bf16 v[44:47], v[206:209], v[68:71], v[44:47]
	v_mfma_f32_16x16x32_bf16 v[88:91], v[210:213], v[72:75], v[44:47]
	v_mfma_f32_16x16x32_bf16 v[44:47], v[214:217], v[68:71], v[48:51]
	v_mfma_f32_16x16x32_bf16 v[64:67], v[218:221], v[72:75], v[44:47]
	v_mfma_f32_16x16x32_bf16 v[40:43], v[206:209], v[76:79], v[40:43]
	v_mfma_f32_16x16x32_bf16 v[40:43], v[210:213], v[80:83], v[40:43]
	v_mfma_f32_16x16x32_bf16 v[32:35], v[214:217], v[76:79], v[32:35]
	v_mfma_f32_16x16x32_bf16 v[32:35], v[218:221], v[80:83], v[32:35]
	v_mfma_f32_16x16x32_bf16 v[24:27], v[206:209], v[164:167], v[24:27]
	v_mfma_f32_16x16x32_bf16 v[24:27], v[210:213], v[168:171], v[24:27]
	v_mfma_f32_16x16x32_bf16 v[20:23], v[214:217], v[164:167], v[20:23]
	v_mfma_f32_16x16x32_bf16 v[20:23], v[218:221], v[168:171], v[20:23]
	v_mfma_f32_16x16x32_bf16 v[8:11], v[206:209], v[182:185], v[8:11]
	v_mfma_f32_16x16x32_bf16 v[8:11], v[210:213], v[186:189], v[8:11]
	v_mfma_f32_16x16x32_bf16 v[4:7], v[214:217], v[182:185], v[4:7]
	s_barrier
	v_mfma_f32_16x16x32_bf16 v[4:7], v[218:221], v[186:189], v[4:7]
	s_setprio 0
	s_add_i32 s57, s57, 2
	s_add_u32 s55, s55, 0x100
	s_addc_u32 s56, s56, 0
	s_cmp_gt_u32 s57, 29
	s_mov_b64 s[26:27], s[28:29]
	s_cbranch_scc0 .LBB0_1002
	v_lshl_or_b32 v182, s52, 7, v197
	v_ashrrev_i32_e32 v183, 31, v182
	v_lshlrev_b64 v[56:57], 2, v[182:183]
	v_lshl_add_u64 v[48:49], s[10:11], 0, v[56:57]
	global_load_dwordx4 v[44:47], v[48:49], off offset:16
	global_load_dwordx4 v[68:71], v[48:49], off
	v_lshl_add_u64 v[52:53], s[14:15], 0, v[56:57]
	global_load_dwordx4 v[48:51], v[52:53], off offset:16
	global_load_dwordx4 v[72:75], v[52:53], off
	v_lshl_add_u64 v[58:59], s[16:17], 0, v[56:57]
	global_load_dwordx4 v[52:55], v[58:59], off offset:16
	global_load_dwordx4 v[76:79], v[58:59], off
	v_lshl_add_u64 v[80:81], s[12:13], 0, v[56:57]
	global_load_dwordx4 v[56:59], v[80:81], off offset:16
	s_nop 0
	global_load_dwordx4 v[80:83], v[80:81], off
	v_mov_b32_dpp v164, v8 row_shr:1 row_mask:0xf bank_mask:0xf bound_ctrl:1
	v_mov_b32_dpp v165, v9 row_shr:1 row_mask:0xf bank_mask:0xf bound_ctrl:1
	v_mov_b32_dpp v166, v10 row_shr:1 row_mask:0xf bank_mask:0xf bound_ctrl:1
	v_mov_b32_dpp v167, v11 row_shr:1 row_mask:0xf bank_mask:0xf bound_ctrl:1
	v_mov_b32_dpp v168, v4 row_shr:1 row_mask:0xf bank_mask:0xf bound_ctrl:1
	v_mov_b32_dpp v169, v5 row_shr:1 row_mask:0xf bank_mask:0xf bound_ctrl:1
	v_mov_b32_dpp v170, v6 row_shr:1 row_mask:0xf bank_mask:0xf bound_ctrl:1
	v_mov_b32_dpp v171, v7 row_shr:1 row_mask:0xf bank_mask:0xf bound_ctrl:1
	v_lshl_add_u32 v201, s33, 8, v196
	s_movk_i32 s21, 0x2c00
	s_lshl_b32 s19, s33, 2
	v_mov_b32_dpp v190, v152 row_shl:1 row_mask:0xf bank_mask:0xf bound_ctrl:1
	v_mov_b32_dpp v191, v153 row_shl:1 row_mask:0xf bank_mask:0xf bound_ctrl:1
	v_mov_b32_dpp v188, v154 row_shl:1 row_mask:0xf bank_mask:0xf bound_ctrl:1
	v_mov_b32_dpp v189, v155 row_shl:1 row_mask:0xf bank_mask:0xf bound_ctrl:1
	v_mov_b32_dpp v186, v144 row_shl:1 row_mask:0xf bank_mask:0xf bound_ctrl:1
	v_mov_b32_dpp v187, v145 row_shl:1 row_mask:0xf bank_mask:0xf bound_ctrl:1
	v_mov_b32_dpp v184, v146 row_shl:1 row_mask:0xf bank_mask:0xf bound_ctrl:1
	v_mov_b32_dpp v185, v147 row_shl:1 row_mask:0xf bank_mask:0xf bound_ctrl:1
	s_add_i32 s19, s19, s50
	s_waitcnt vmcnt(0)
	v_pk_mul_f32 v[168:169], v[44:45], v[168:169]
	v_pk_mul_f32 v[164:165], v[68:69], v[164:165]
	v_pk_mul_f32 v[166:167], v[70:71], v[166:167]
	v_pk_fma_f32 v[164:165], v[152:153], v[72:73], v[164:165]
	v_pk_fma_f32 v[166:167], v[154:155], v[74:75], v[166:167]
	v_pk_fma_f32 v[164:165], v[136:137], v[76:77], v[164:165]
	v_pk_fma_f32 v[166:167], v[138:139], v[78:79], v[166:167]
	v_pk_add_f32 v[164:165], v[80:81], v[164:165]
	v_pk_add_f32 v[166:167], v[82:83], v[166:167]
	v_mul_f32_e32 v192, 0xbfb8aa3b, v164
	v_mul_f32_e32 v193, 0xbfb8aa3b, v165
	v_exp_f32_e32 v192, v192
	v_exp_f32_e32 v193, v193
	v_pk_fma_f32 v[168:169], v[144:145], v[48:49], v[168:169]
	v_pk_mul_f32 v[170:171], v[46:47], v[170:171]
	v_pk_fma_f32 v[168:169], v[128:129], v[52:53], v[168:169]
	v_pk_add_f32 v[192:193], v[192:193], 1.0 op_sel_hi:[1,0]
	v_pk_add_f32 v[168:169], v[56:57], v[168:169]
	v_rcp_f32_e32 v195, v193
	v_pk_fma_f32 v[170:171], v[146:147], v[50:51], v[170:171]
	v_fma_f32 v202, -v193, v195, 1.0
	v_fmac_f32_e32 v195, v202, v195
	v_div_fixup_f32 v193, v195, v193, 1.0
	v_rcp_f32_e32 v195, v192
	v_pk_fma_f32 v[170:171], v[130:131], v[54:55], v[170:171]
	v_fma_f32 v202, -v192, v195, 1.0
	v_fmac_f32_e32 v195, v202, v195
	v_div_fixup_f32 v192, v195, v192, 1.0
	v_mul_f32_e32 v194, 0xbfb8aa3b, v166
	v_mul_f32_e32 v195, 0xbfb8aa3b, v167
	v_exp_f32_e32 v194, v194
	v_exp_f32_e32 v195, v195
	v_pk_add_f32 v[170:171], v[58:59], v[170:171]
	v_pk_mul_f32 v[192:193], v[164:165], v[192:193]
	v_pk_add_f32 v[194:195], v[194:195], 1.0 op_sel_hi:[1,0]
	s_nop 0
	v_rcp_f32_e32 v203, v195
	v_pk_mul_f32 v[192:193], v[160:161], v[192:193]
	v_fma_f32 v204, -v195, v203, 1.0
	v_fmac_f32_e32 v203, v204, v203
	v_div_fixup_f32 v195, v203, v195, 1.0
	v_rcp_f32_e32 v203, v194
	v_cvt_pk_bf16_f32 v192, v192, v193
	v_fma_f32 v204, -v194, v203, 1.0
	v_fmac_f32_e32 v203, v204, v203
	v_div_fixup_f32 v194, v203, v194, 1.0
	v_mul_f32_e32 v202, 0xbfb8aa3b, v168
	v_mul_f32_e32 v203, 0xbfb8aa3b, v169
	v_exp_f32_e32 v202, v202
	v_exp_f32_e32 v203, v203
	v_pk_mul_f32 v[194:195], v[166:167], v[194:195]
	v_pk_add_f32 v[202:203], v[202:203], 1.0 op_sel_hi:[1,0]
	s_nop 0
	v_rcp_f32_e32 v205, v203
	v_pk_mul_f32 v[194:195], v[162:163], v[194:195]
	v_fma_f32 v206, -v203, v205, 1.0
	v_fmac_f32_e32 v205, v206, v205
	v_div_fixup_f32 v203, v205, v203, 1.0
	v_rcp_f32_e32 v205, v202
	v_cvt_pk_bf16_f32 v193, v194, v195
	v_fma_f32 v206, -v202, v205, 1.0
	v_fmac_f32_e32 v205, v206, v205
	v_div_fixup_f32 v202, v205, v202, 1.0
	v_mul_f32_e32 v204, 0xbfb8aa3b, v170
	v_mul_f32_e32 v205, 0xbfb8aa3b, v171
	v_exp_f32_e32 v204, v204
	v_exp_f32_e32 v205, v205
	v_pk_mul_f32 v[202:203], v[168:169], v[202:203]
	v_pk_add_f32 v[204:205], v[204:205], 1.0 op_sel_hi:[1,0]
	s_nop 0
	v_rcp_f32_e32 v207, v205
	v_pk_mul_f32 v[202:203], v[156:157], v[202:203]
	v_fma_f32 v208, -v205, v207, 1.0
	v_fmac_f32_e32 v207, v208, v207
	v_div_fixup_f32 v205, v207, v205, 1.0
	v_rcp_f32_e32 v207, v204
	v_cvt_pk_bf16_f32 v194, v202, v203
	v_mov_b64_e32 v[202:203], s[0:1]
	v_mad_i64_i32 v[202:203], s[26:27], v201, s21, v[202:203]
	v_fma_f32 v208, -v204, v207, 1.0
	v_fmac_f32_e32 v207, v208, v207
	v_div_fixup_f32 v204, v207, v204, 1.0
	v_pk_mul_f32 v[204:205], v[170:171], v[204:205]
	v_lshl_add_u64 v[202:203], v[182:183], 1, v[202:203]
	v_pk_mul_f32 v[204:205], v[158:159], v[204:205]
	s_nop 0
	v_cvt_pk_bf16_f32 v195, v204, v205
	global_store_dwordx4 v[202:203], v[192:195], off
	s_and_saveexec_b64 s[26:27], s[6:7]
	s_cbranch_execz .LBB0_1005
	s_mul_i32 s28, s19, 0x10800
	s_mul_hi_i32 s21, s19, 0x10800
	s_add_u32 s28, s46, s28
	s_addc_u32 s29, s47, s21
	v_lshl_add_u64 v[192:193], v[182:183], 2, s[28:29]
	global_store_dwordx4 v[192:193], v[164:167], off
	global_store_dwordx4 v[192:193], v[168:171], off offset:16
	s_nop 0
	v_add_co_u32_e32 v164, vcc, 0x5000, v192
	s_nop 1
	v_addc_co_u32_e32 v165, vcc, 0, v193, vcc
	global_store_dwordx4 v[164:165], v[160:163], off offset:2048
	global_store_dwordx4 v[164:165], v[156:159], off offset:2064
	s_nop 1
	v_add_co_u32_e32 v156, vcc, 0xb000, v192
	s_nop 1
	v_addc_co_u32_e32 v157, vcc, 0, v193, vcc
	global_store_dwordx4 v[156:157], v[152:155], off
	global_store_dwordx4 v[156:157], v[144:147], off offset:16
.LBB0_1005:
	s_or_b64 exec, exec, s[26:27]
	v_pk_mul_f32 v[156:157], v[136:137], v[72:73]
	s_movk_i32 s21, 0x2c00
	v_pk_fma_f32 v[152:153], v[152:153], v[68:69], v[156:157]
	s_nop 0
	v_pk_fma_f32 v[152:153], v[120:121], v[76:77], v[152:153]
	s_nop 0
	v_pk_add_f32 v[152:153], v[80:81], v[152:153]
	s_nop 0
	v_mul_f32_e32 v156, 0xbfb8aa3b, v152
	v_mul_f32_e32 v157, 0xbfb8aa3b, v153
	v_exp_f32_e32 v156, v156
	v_exp_f32_e32 v157, v157
	s_nop 0
	v_pk_add_f32 v[156:157], v[156:157], 1.0 op_sel_hi:[1,0]
	s_nop 0
	v_rcp_f32_e32 v159, v157
	s_nop 0
	v_fma_f32 v160, -v157, v159, 1.0
	v_fmac_f32_e32 v159, v160, v159
	v_div_fixup_f32 v157, v159, v157, 1.0
	v_rcp_f32_e32 v159, v156
	s_nop 0
	v_fma_f32 v160, -v156, v159, 1.0
	v_fmac_f32_e32 v159, v160, v159
	v_div_fixup_f32 v156, v159, v156, 1.0
	v_pk_mul_f32 v[152:153], v[152:153], v[156:157]
	s_nop 0
	v_pk_mul_f32 v[148:149], v[148:149], v[152:153]
	v_pk_mul_f32 v[152:153], v[138:139], v[74:75]
	s_nop 0
	v_pk_fma_f32 v[152:153], v[154:155], v[70:71], v[152:153]
	s_nop 0
	v_pk_fma_f32 v[152:153], v[122:123], v[78:79], v[152:153]
	s_nop 0
	v_pk_add_f32 v[152:153], v[82:83], v[152:153]
	s_nop 0
	v_mul_f32_e32 v154, 0xbfb8aa3b, v152
	v_mul_f32_e32 v155, 0xbfb8aa3b, v153
	v_exp_f32_e32 v154, v154
	v_exp_f32_e32 v155, v155
	s_nop 0
	v_pk_add_f32 v[154:155], v[154:155], 1.0 op_sel_hi:[1,0]
	s_nop 0
	v_rcp_f32_e32 v157, v155
	s_nop 0
	v_fma_f32 v158, -v155, v157, 1.0
	v_fmac_f32_e32 v157, v158, v157
	v_div_fixup_f32 v155, v157, v155, 1.0
	v_rcp_f32_e32 v157, v154
	s_nop 0
	v_fma_f32 v158, -v154, v157, 1.0
	v_fmac_f32_e32 v157, v158, v157
	v_div_fixup_f32 v154, v157, v154, 1.0
	v_pk_mul_f32 v[152:153], v[152:153], v[154:155]
	s_nop 0
	v_pk_mul_f32 v[150:151], v[150:151], v[152:153]
	v_pk_mul_f32 v[152:153], v[128:129], v[48:49]
	s_nop 0
	v_pk_fma_f32 v[144:145], v[144:145], v[44:45], v[152:153]
	s_nop 0
	v_pk_fma_f32 v[144:145], v[112:113], v[52:53], v[144:145]
	s_nop 0
	v_pk_add_f32 v[144:145], v[56:57], v[144:145]
	s_nop 0
	v_mul_f32_e32 v152, 0xbfb8aa3b, v144
	v_mul_f32_e32 v153, 0xbfb8aa3b, v145
	v_exp_f32_e32 v152, v152
	v_exp_f32_e32 v153, v153
	s_nop 0
	v_pk_add_f32 v[152:153], v[152:153], 1.0 op_sel_hi:[1,0]
	s_nop 0
	v_rcp_f32_e32 v155, v153
	s_nop 0
	v_fma_f32 v156, -v153, v155, 1.0
	v_fmac_f32_e32 v155, v156, v155
	v_div_fixup_f32 v153, v155, v153, 1.0
	v_rcp_f32_e32 v155, v152
	s_nop 0
	v_fma_f32 v156, -v152, v155, 1.0
	v_fmac_f32_e32 v155, v156, v155
	v_div_fixup_f32 v152, v155, v152, 1.0
	v_pk_mul_f32 v[144:145], v[144:145], v[152:153]
	s_nop 0
	v_pk_mul_f32 v[140:141], v[140:141], v[144:145]
	v_pk_mul_f32 v[144:145], v[130:131], v[50:51]
	s_nop 0
	v_pk_fma_f32 v[144:145], v[146:147], v[46:47], v[144:145]
	s_nop 0
	v_pk_fma_f32 v[144:145], v[114:115], v[54:55], v[144:145]
	s_nop 0
	v_pk_add_f32 v[144:145], v[58:59], v[144:145]
	s_nop 0
	v_mul_f32_e32 v146, 0xbfb8aa3b, v144
	v_mul_f32_e32 v147, 0xbfb8aa3b, v145
	v_exp_f32_e32 v146, v146
	v_exp_f32_e32 v147, v147
	s_nop 0
	v_pk_add_f32 v[146:147], v[146:147], 1.0 op_sel_hi:[1,0]
	s_nop 0
	v_rcp_f32_e32 v153, v147
	s_nop 0
	v_fma_f32 v154, -v147, v153, 1.0
	v_fmac_f32_e32 v153, v154, v153
	v_div_fixup_f32 v147, v153, v147, 1.0
	v_rcp_f32_e32 v153, v146
	s_nop 0
	v_fma_f32 v154, -v146, v153, 1.0
	v_fmac_f32_e32 v153, v154, v153
	v_div_fixup_f32 v146, v153, v146, 1.0
	v_pk_mul_f32 v[144:145], v[144:145], v[146:147]
	v_cvt_pk_bf16_f32 v146, v140, v141
	v_pk_mul_f32 v[142:143], v[142:143], v[144:145]
	v_mov_b64_e32 v[140:141], s[0:1]
	v_cvt_pk_bf16_f32 v147, v142, v143
	v_or_b32_e32 v142, 1, v201
	v_cvt_pk_bf16_f32 v144, v148, v149
	v_mad_i64_i32 v[148:149], s[26:27], v142, s21, v[140:141]
	v_lshlrev_b64 v[142:143], 1, v[182:183]
	v_cvt_pk_bf16_f32 v145, v150, v151
	v_lshl_add_u64 v[148:149], v[148:149], 0, v[142:143]
	global_store_dwordx4 v[148:149], v[144:147], off
	s_nop 1
	v_pk_mul_f32 v[144:145], v[120:121], v[72:73]
	s_nop 0
	v_pk_fma_f32 v[136:137], v[136:137], v[68:69], v[144:145]
	s_nop 0
	v_pk_fma_f32 v[136:137], v[104:105], v[76:77], v[136:137]
	s_nop 0
	v_pk_add_f32 v[136:137], v[80:81], v[136:137]
	s_nop 0
	v_mul_f32_e32 v144, 0xbfb8aa3b, v136
	v_mul_f32_e32 v145, 0xbfb8aa3b, v137
	v_exp_f32_e32 v144, v144
	v_exp_f32_e32 v145, v145
	s_nop 0
	v_pk_add_f32 v[144:145], v[144:145], 1.0 op_sel_hi:[1,0]
	s_nop 0
	v_rcp_f32_e32 v147, v145
	s_nop 0
	v_fma_f32 v148, -v145, v147, 1.0
	v_fmac_f32_e32 v147, v148, v147
	v_div_fixup_f32 v145, v147, v145, 1.0
	v_rcp_f32_e32 v147, v144
	s_nop 0
	v_fma_f32 v148, -v144, v147, 1.0
	v_fmac_f32_e32 v147, v148, v147
	v_div_fixup_f32 v144, v147, v144, 1.0
	v_pk_mul_f32 v[136:137], v[136:137], v[144:145]
	s_nop 0
	v_pk_mul_f32 v[132:133], v[132:133], v[136:137]
	v_pk_mul_f32 v[136:137], v[122:123], v[74:75]
	s_nop 0
	v_pk_fma_f32 v[136:137], v[138:139], v[70:71], v[136:137]
	s_nop 0
	v_pk_fma_f32 v[136:137], v[106:107], v[78:79], v[136:137]
	s_nop 0
	v_pk_add_f32 v[136:137], v[82:83], v[136:137]
	s_nop 0
	v_mul_f32_e32 v138, 0xbfb8aa3b, v136
	v_mul_f32_e32 v139, 0xbfb8aa3b, v137
	v_exp_f32_e32 v138, v138
	v_exp_f32_e32 v139, v139
	s_nop 0
	v_pk_add_f32 v[138:139], v[138:139], 1.0 op_sel_hi:[1,0]
	s_nop 0
	v_rcp_f32_e32 v145, v139
	s_nop 0
	v_fma_f32 v146, -v139, v145, 1.0
	v_fmac_f32_e32 v145, v146, v145
	v_div_fixup_f32 v139, v145, v139, 1.0
	v_rcp_f32_e32 v145, v138
	s_nop 0
	v_fma_f32 v146, -v138, v145, 1.0
	v_fmac_f32_e32 v145, v146, v145
	v_div_fixup_f32 v138, v145, v138, 1.0
	v_pk_mul_f32 v[136:137], v[136:137], v[138:139]
	s_nop 0
	v_pk_mul_f32 v[134:135], v[134:135], v[136:137]
	v_pk_mul_f32 v[136:137], v[112:113], v[48:49]
	s_nop 0
	v_pk_fma_f32 v[128:129], v[128:129], v[44:45], v[136:137]
	s_nop 0
	v_pk_fma_f32 v[128:129], v[96:97], v[52:53], v[128:129]
	s_nop 0
	v_pk_add_f32 v[128:129], v[56:57], v[128:129]
	s_nop 0
	v_mul_f32_e32 v136, 0xbfb8aa3b, v128
	v_mul_f32_e32 v137, 0xbfb8aa3b, v129
	v_exp_f32_e32 v136, v136
	v_exp_f32_e32 v137, v137
	s_nop 0
	v_pk_add_f32 v[136:137], v[136:137], 1.0 op_sel_hi:[1,0]
	s_nop 0
	v_rcp_f32_e32 v139, v137
	s_nop 0
	v_fma_f32 v144, -v137, v139, 1.0
	v_fmac_f32_e32 v139, v144, v139
	v_div_fixup_f32 v137, v139, v137, 1.0
	v_rcp_f32_e32 v139, v136
	s_nop 0
	v_fma_f32 v144, -v136, v139, 1.0
	v_fmac_f32_e32 v139, v144, v139
	v_div_fixup_f32 v136, v139, v136, 1.0
	v_pk_mul_f32 v[128:129], v[128:129], v[136:137]
	s_nop 0
	v_pk_mul_f32 v[128:129], v[124:125], v[128:129]
	v_pk_mul_f32 v[124:125], v[114:115], v[50:51]
	s_nop 0
	v_pk_fma_f32 v[124:125], v[130:131], v[46:47], v[124:125]
	s_nop 0
	v_pk_fma_f32 v[124:125], v[98:99], v[54:55], v[124:125]
	s_nop 0
	v_pk_add_f32 v[124:125], v[58:59], v[124:125]
	s_nop 0
	v_mul_f32_e32 v130, 0xbfb8aa3b, v124
	v_mul_f32_e32 v131, 0xbfb8aa3b, v125
	v_exp_f32_e32 v130, v130
	v_exp_f32_e32 v131, v131
	s_nop 0
	v_pk_add_f32 v[130:131], v[130:131], 1.0 op_sel_hi:[1,0]
	s_nop 0
	v_rcp_f32_e32 v137, v131
	s_nop 0
	v_fma_f32 v138, -v131, v137, 1.0
	v_fmac_f32_e32 v137, v138, v137
	v_div_fixup_f32 v131, v137, v131, 1.0
	v_rcp_f32_e32 v137, v130
	s_nop 0
	v_fma_f32 v138, -v130, v137, 1.0
	v_fmac_f32_e32 v137, v138, v137
	v_div_fixup_f32 v130, v137, v130, 1.0
	v_pk_mul_f32 v[124:125], v[124:125], v[130:131]
	s_nop 0
	v_pk_mul_f32 v[130:131], v[126:127], v[124:125]
	v_cvt_pk_bf16_f32 v126, v128, v129
	v_or_b32_e32 v128, 2, v201
	v_mad_i64_i32 v[128:129], s[26:27], v128, s21, v[140:141]
	v_cvt_pk_bf16_f32 v124, v132, v133
	v_cvt_pk_bf16_f32 v125, v134, v135
	v_cvt_pk_bf16_f32 v127, v130, v131
	v_lshl_add_u64 v[128:129], v[128:129], 0, v[142:143]
	global_store_dwordx4 v[128:129], v[124:127], off
	s_nop 1
	v_pk_mul_f32 v[124:125], v[104:105], v[72:73]
	s_nop 0
	v_pk_fma_f32 v[120:121], v[120:121], v[68:69], v[124:125]
	s_nop 0
	v_pk_fma_f32 v[120:121], v[88:89], v[76:77], v[120:121]
	s_nop 0
	v_pk_add_f32 v[120:121], v[80:81], v[120:121]
	s_nop 0
	v_mul_f32_e32 v124, 0xbfb8aa3b, v120
	v_mul_f32_e32 v125, 0xbfb8aa3b, v121
	v_exp_f32_e32 v124, v124
	v_exp_f32_e32 v125, v125
	s_nop 0
	v_pk_add_f32 v[124:125], v[124:125], 1.0 op_sel_hi:[1,0]
	s_nop 0
	v_rcp_f32_e32 v127, v125
	s_nop 0
	v_fma_f32 v128, -v125, v127, 1.0
	v_fmac_f32_e32 v127, v128, v127
	v_div_fixup_f32 v125, v127, v125, 1.0
	v_rcp_f32_e32 v127, v124
	s_nop 0
	v_fma_f32 v128, -v124, v127, 1.0
	v_fmac_f32_e32 v127, v128, v127
	v_div_fixup_f32 v124, v127, v124, 1.0
	v_pk_mul_f32 v[120:121], v[120:121], v[124:125]
	s_nop 0
	v_pk_mul_f32 v[116:117], v[116:117], v[120:121]
	v_pk_mul_f32 v[120:121], v[106:107], v[74:75]
	s_nop 0
	v_pk_fma_f32 v[120:121], v[122:123], v[70:71], v[120:121]
	s_nop 0
	v_pk_fma_f32 v[120:121], v[90:91], v[78:79], v[120:121]
	s_nop 0
	v_pk_add_f32 v[120:121], v[82:83], v[120:121]
	s_nop 0
	v_mul_f32_e32 v122, 0xbfb8aa3b, v120
	v_mul_f32_e32 v123, 0xbfb8aa3b, v121
	v_exp_f32_e32 v122, v122
	v_exp_f32_e32 v123, v123
	s_nop 0
	v_pk_add_f32 v[122:123], v[122:123], 1.0 op_sel_hi:[1,0]
	s_nop 0
	v_rcp_f32_e32 v125, v123
	s_nop 0
	v_fma_f32 v126, -v123, v125, 1.0
	v_fmac_f32_e32 v125, v126, v125
	v_div_fixup_f32 v123, v125, v123, 1.0
	v_rcp_f32_e32 v125, v122
	s_nop 0
	v_fma_f32 v126, -v122, v125, 1.0
	v_fmac_f32_e32 v125, v126, v125
	v_div_fixup_f32 v122, v125, v122, 1.0
	v_pk_mul_f32 v[120:121], v[120:121], v[122:123]
	s_nop 0
	v_pk_mul_f32 v[118:119], v[118:119], v[120:121]
	v_pk_mul_f32 v[120:121], v[96:97], v[48:49]
	s_nop 0
	v_pk_fma_f32 v[112:113], v[112:113], v[44:45], v[120:121]
	s_nop 0
	v_pk_fma_f32 v[112:113], v[64:65], v[52:53], v[112:113]
	s_nop 0
	v_pk_add_f32 v[112:113], v[56:57], v[112:113]
	s_nop 0
	v_mul_f32_e32 v120, 0xbfb8aa3b, v112
	v_mul_f32_e32 v121, 0xbfb8aa3b, v113
	v_exp_f32_e32 v120, v120
	v_exp_f32_e32 v121, v121
	s_nop 0
	v_pk_add_f32 v[120:121], v[120:121], 1.0 op_sel_hi:[1,0]
	s_nop 0
	v_rcp_f32_e32 v123, v121
	s_nop 0
	v_fma_f32 v124, -v121, v123, 1.0
	v_fmac_f32_e32 v123, v124, v123
	v_div_fixup_f32 v121, v123, v121, 1.0
	v_rcp_f32_e32 v123, v120
	s_nop 0
	v_fma_f32 v124, -v120, v123, 1.0
	v_fmac_f32_e32 v123, v124, v123
	v_div_fixup_f32 v120, v123, v120, 1.0
	v_pk_mul_f32 v[112:113], v[112:113], v[120:121]
	s_nop 0
	v_pk_mul_f32 v[112:113], v[108:109], v[112:113]
	v_pk_mul_f32 v[108:109], v[98:99], v[50:51]
	s_nop 0
	v_pk_fma_f32 v[108:109], v[114:115], v[46:47], v[108:109]
	s_nop 0
	v_pk_fma_f32 v[108:109], v[66:67], v[54:55], v[108:109]
	s_nop 0
	v_pk_add_f32 v[108:109], v[58:59], v[108:109]
	s_nop 0
	v_mul_f32_e32 v114, 0xbfb8aa3b, v108
	v_mul_f32_e32 v115, 0xbfb8aa3b, v109
	v_exp_f32_e32 v114, v114
	v_exp_f32_e32 v115, v115
	s_nop 0
	v_pk_add_f32 v[114:115], v[114:115], 1.0 op_sel_hi:[1,0]
	s_nop 0
	v_rcp_f32_e32 v121, v115
	s_nop 0
	v_fma_f32 v122, -v115, v121, 1.0
	v_fmac_f32_e32 v121, v122, v121
	v_div_fixup_f32 v115, v121, v115, 1.0
	v_rcp_f32_e32 v121, v114
	s_nop 0
	v_fma_f32 v122, -v114, v121, 1.0
	v_fmac_f32_e32 v121, v122, v121
	v_div_fixup_f32 v114, v121, v114, 1.0
	v_pk_mul_f32 v[108:109], v[108:109], v[114:115]
	s_nop 0
	v_pk_mul_f32 v[114:115], v[110:111], v[108:109]
	v_cvt_pk_bf16_f32 v110, v112, v113
	v_or_b32_e32 v112, 3, v201
	v_mad_i64_i32 v[112:113], s[26:27], v112, s21, v[140:141]
	v_cvt_pk_bf16_f32 v108, v116, v117
	v_cvt_pk_bf16_f32 v109, v118, v119
	v_cvt_pk_bf16_f32 v111, v114, v115
	v_lshl_add_u64 v[112:113], v[112:113], 0, v[142:143]
	global_store_dwordx4 v[112:113], v[108:111], off
	s_nop 1
	v_pk_mul_f32 v[108:109], v[88:89], v[72:73]
	s_nop 0
	v_pk_fma_f32 v[104:105], v[104:105], v[68:69], v[108:109]
	s_nop 0
	v_pk_fma_f32 v[104:105], v[40:41], v[76:77], v[104:105]
	s_nop 0
	v_pk_add_f32 v[104:105], v[80:81], v[104:105]
	s_nop 0
	v_mul_f32_e32 v108, 0xbfb8aa3b, v104
	v_mul_f32_e32 v109, 0xbfb8aa3b, v105
	v_exp_f32_e32 v108, v108
	v_exp_f32_e32 v109, v109
	s_nop 0
	v_pk_add_f32 v[108:109], v[108:109], 1.0 op_sel_hi:[1,0]
	s_nop 0
	v_rcp_f32_e32 v111, v109
	s_nop 0
	v_fma_f32 v112, -v109, v111, 1.0
	v_fmac_f32_e32 v111, v112, v111
	v_div_fixup_f32 v109, v111, v109, 1.0
	v_rcp_f32_e32 v111, v108
	s_nop 0
	v_fma_f32 v112, -v108, v111, 1.0
	v_fmac_f32_e32 v111, v112, v111
	v_div_fixup_f32 v108, v111, v108, 1.0
	v_pk_mul_f32 v[104:105], v[104:105], v[108:109]
	s_nop 0
	v_pk_mul_f32 v[100:101], v[100:101], v[104:105]
	v_pk_mul_f32 v[104:105], v[90:91], v[74:75]
	s_nop 0
	v_pk_fma_f32 v[104:105], v[106:107], v[70:71], v[104:105]
	s_nop 0
	v_pk_fma_f32 v[104:105], v[42:43], v[78:79], v[104:105]
	s_nop 0
	v_pk_add_f32 v[104:105], v[82:83], v[104:105]
	s_nop 0
	v_mul_f32_e32 v106, 0xbfb8aa3b, v104
	v_mul_f32_e32 v107, 0xbfb8aa3b, v105
	v_exp_f32_e32 v106, v106
	v_exp_f32_e32 v107, v107
	s_nop 0
	v_pk_add_f32 v[106:107], v[106:107], 1.0 op_sel_hi:[1,0]
	s_nop 0
	v_rcp_f32_e32 v109, v107
	s_nop 0
	v_fma_f32 v110, -v107, v109, 1.0
	v_fmac_f32_e32 v109, v110, v109
	v_div_fixup_f32 v107, v109, v107, 1.0
	v_rcp_f32_e32 v109, v106
	s_nop 0
	v_fma_f32 v110, -v106, v109, 1.0
	v_fmac_f32_e32 v109, v110, v109
	v_div_fixup_f32 v106, v109, v106, 1.0
	v_pk_mul_f32 v[104:105], v[104:105], v[106:107]
	s_nop 0
	v_pk_mul_f32 v[102:103], v[102:103], v[104:105]
	v_pk_mul_f32 v[104:105], v[64:65], v[48:49]
	s_nop 0
	v_pk_fma_f32 v[96:97], v[96:97], v[44:45], v[104:105]
	s_nop 0
	v_pk_fma_f32 v[96:97], v[32:33], v[52:53], v[96:97]
	s_nop 0
	v_pk_add_f32 v[96:97], v[56:57], v[96:97]
	s_nop 0
	v_mul_f32_e32 v104, 0xbfb8aa3b, v96
	v_mul_f32_e32 v105, 0xbfb8aa3b, v97
	v_exp_f32_e32 v104, v104
	v_exp_f32_e32 v105, v105
	s_nop 0
	v_pk_add_f32 v[104:105], v[104:105], 1.0 op_sel_hi:[1,0]
	s_nop 0
	v_rcp_f32_e32 v107, v105
	s_nop 0
	v_fma_f32 v108, -v105, v107, 1.0
	v_fmac_f32_e32 v107, v108, v107
	v_div_fixup_f32 v105, v107, v105, 1.0
	v_rcp_f32_e32 v107, v104
	s_nop 0
	v_fma_f32 v108, -v104, v107, 1.0
	v_fmac_f32_e32 v107, v108, v107
	v_div_fixup_f32 v104, v107, v104, 1.0
	v_pk_mul_f32 v[96:97], v[96:97], v[104:105]
	s_nop 0
	v_pk_mul_f32 v[96:97], v[92:93], v[96:97]
	v_pk_mul_f32 v[92:93], v[66:67], v[50:51]
	s_nop 0
	v_pk_fma_f32 v[92:93], v[98:99], v[46:47], v[92:93]
	s_nop 0
	v_pk_fma_f32 v[92:93], v[34:35], v[54:55], v[92:93]
	s_nop 0
	v_pk_add_f32 v[92:93], v[58:59], v[92:93]
	s_nop 0
	v_mul_f32_e32 v98, 0xbfb8aa3b, v92
	v_mul_f32_e32 v99, 0xbfb8aa3b, v93
	v_exp_f32_e32 v98, v98
	v_exp_f32_e32 v99, v99
	s_nop 0
	v_pk_add_f32 v[98:99], v[98:99], 1.0 op_sel_hi:[1,0]
	s_nop 0
	v_rcp_f32_e32 v105, v99
	s_nop 0
	v_fma_f32 v106, -v99, v105, 1.0
	v_fmac_f32_e32 v105, v106, v105
	v_div_fixup_f32 v99, v105, v99, 1.0
	v_rcp_f32_e32 v105, v98
	s_nop 0
	v_fma_f32 v106, -v98, v105, 1.0
	v_fmac_f32_e32 v105, v106, v105
	v_div_fixup_f32 v98, v105, v98, 1.0
	v_pk_mul_f32 v[92:93], v[92:93], v[98:99]
	s_nop 0
	v_pk_mul_f32 v[98:99], v[94:95], v[92:93]
	v_cvt_pk_bf16_f32 v94, v96, v97
	v_or_b32_e32 v96, 4, v201
	v_mad_i64_i32 v[96:97], s[26:27], v96, s21, v[140:141]
	v_cvt_pk_bf16_f32 v92, v100, v101
	v_cvt_pk_bf16_f32 v93, v102, v103
	v_cvt_pk_bf16_f32 v95, v98, v99
	v_lshl_add_u64 v[96:97], v[96:97], 0, v[142:143]
	global_store_dwordx4 v[96:97], v[92:95], off
	s_nop 1
	v_pk_mul_f32 v[92:93], v[40:41], v[72:73]
	s_nop 0
	v_pk_fma_f32 v[88:89], v[88:89], v[68:69], v[92:93]
	s_nop 0
	v_pk_fma_f32 v[88:89], v[24:25], v[76:77], v[88:89]
	s_nop 0
	v_pk_add_f32 v[88:89], v[80:81], v[88:89]
	s_nop 0
	v_mul_f32_e32 v92, 0xbfb8aa3b, v88
	v_mul_f32_e32 v93, 0xbfb8aa3b, v89
	v_exp_f32_e32 v92, v92
	v_exp_f32_e32 v93, v93
	s_nop 0
	v_pk_add_f32 v[92:93], v[92:93], 1.0 op_sel_hi:[1,0]
	s_nop 0
	v_rcp_f32_e32 v95, v93
	s_nop 0
	v_fma_f32 v96, -v93, v95, 1.0
	v_fmac_f32_e32 v95, v96, v95
	v_div_fixup_f32 v93, v95, v93, 1.0
	v_rcp_f32_e32 v95, v92
	s_nop 0
	v_fma_f32 v96, -v92, v95, 1.0
	v_fmac_f32_e32 v95, v96, v95
	v_div_fixup_f32 v92, v95, v92, 1.0
	v_pk_mul_f32 v[88:89], v[88:89], v[92:93]
	s_nop 0
	v_pk_mul_f32 v[84:85], v[84:85], v[88:89]
	v_pk_mul_f32 v[88:89], v[42:43], v[74:75]
	s_nop 0
	v_pk_fma_f32 v[88:89], v[90:91], v[70:71], v[88:89]
	s_nop 0
	v_pk_fma_f32 v[88:89], v[26:27], v[78:79], v[88:89]
	s_nop 0
	v_pk_add_f32 v[88:89], v[82:83], v[88:89]
	s_nop 0
	v_mul_f32_e32 v90, 0xbfb8aa3b, v88
	v_mul_f32_e32 v91, 0xbfb8aa3b, v89
	v_exp_f32_e32 v90, v90
	v_exp_f32_e32 v91, v91
	s_nop 0
	v_pk_add_f32 v[90:91], v[90:91], 1.0 op_sel_hi:[1,0]
	s_nop 0
	v_rcp_f32_e32 v93, v91
	s_nop 0
	v_fma_f32 v94, -v91, v93, 1.0
	v_fmac_f32_e32 v93, v94, v93
	v_div_fixup_f32 v91, v93, v91, 1.0
	v_rcp_f32_e32 v93, v90
	s_nop 0
	v_fma_f32 v94, -v90, v93, 1.0
	v_fmac_f32_e32 v93, v94, v93
	v_div_fixup_f32 v90, v93, v90, 1.0
	v_pk_mul_f32 v[88:89], v[88:89], v[90:91]
	s_nop 0
	v_pk_mul_f32 v[86:87], v[86:87], v[88:89]
	v_pk_mul_f32 v[88:89], v[32:33], v[48:49]
	s_nop 0
	v_pk_fma_f32 v[64:65], v[64:65], v[44:45], v[88:89]
	s_nop 0
	v_pk_fma_f32 v[64:65], v[20:21], v[52:53], v[64:65]
	s_nop 0
	v_pk_add_f32 v[64:65], v[56:57], v[64:65]
	s_nop 0
	v_mul_f32_e32 v88, 0xbfb8aa3b, v64
	v_mul_f32_e32 v89, 0xbfb8aa3b, v65
	v_exp_f32_e32 v88, v88
	v_exp_f32_e32 v89, v89
	s_nop 0
	v_pk_add_f32 v[88:89], v[88:89], 1.0 op_sel_hi:[1,0]
	s_nop 0
	v_rcp_f32_e32 v91, v89
	s_nop 0
	v_fma_f32 v92, -v89, v91, 1.0
	v_fmac_f32_e32 v91, v92, v91
	v_div_fixup_f32 v89, v91, v89, 1.0
	v_rcp_f32_e32 v91, v88
	s_nop 0
	v_fma_f32 v92, -v88, v91, 1.0
	v_fmac_f32_e32 v91, v92, v91
	v_div_fixup_f32 v88, v91, v88, 1.0
	v_pk_mul_f32 v[64:65], v[64:65], v[88:89]
	s_nop 0
	v_pk_mul_f32 v[64:65], v[60:61], v[64:65]
	v_pk_mul_f32 v[60:61], v[34:35], v[50:51]
	s_nop 0
	v_pk_fma_f32 v[60:61], v[66:67], v[46:47], v[60:61]
	s_nop 0
	v_pk_fma_f32 v[60:61], v[22:23], v[54:55], v[60:61]
	s_nop 0
	v_pk_add_f32 v[60:61], v[58:59], v[60:61]
	s_nop 0
	v_mul_f32_e32 v66, 0xbfb8aa3b, v60
	v_mul_f32_e32 v67, 0xbfb8aa3b, v61
	v_exp_f32_e32 v66, v66
	v_exp_f32_e32 v67, v67
	s_nop 0
	v_pk_add_f32 v[66:67], v[66:67], 1.0 op_sel_hi:[1,0]
	s_nop 0
	v_rcp_f32_e32 v89, v67
	s_nop 0
	v_fma_f32 v90, -v67, v89, 1.0
	v_fmac_f32_e32 v89, v90, v89
	v_div_fixup_f32 v67, v89, v67, 1.0
	v_rcp_f32_e32 v89, v66
	s_nop 0
	v_fma_f32 v90, -v66, v89, 1.0
	v_fmac_f32_e32 v89, v90, v89
	v_div_fixup_f32 v66, v89, v66, 1.0
	v_pk_mul_f32 v[60:61], v[60:61], v[66:67]
	s_nop 0
	v_pk_mul_f32 v[66:67], v[62:63], v[60:61]
	v_cvt_pk_bf16_f32 v62, v64, v65
	v_or_b32_e32 v64, 5, v201
	v_mad_i64_i32 v[64:65], s[26:27], v64, s21, v[140:141]
	v_cvt_pk_bf16_f32 v60, v84, v85
	v_cvt_pk_bf16_f32 v61, v86, v87
	v_cvt_pk_bf16_f32 v63, v66, v67
	v_lshl_add_u64 v[64:65], v[64:65], 0, v[142:143]
	global_store_dwordx4 v[64:65], v[60:63], off
	s_nop 1
	v_pk_mul_f32 v[60:61], v[24:25], v[72:73]
	s_nop 0
	v_pk_fma_f32 v[40:41], v[40:41], v[68:69], v[60:61]
	s_nop 0
	v_pk_fma_f32 v[40:41], v[8:9], v[76:77], v[40:41]
	s_nop 0
	v_pk_add_f32 v[40:41], v[80:81], v[40:41]
	s_nop 0
	v_mul_f32_e32 v60, 0xbfb8aa3b, v40
	v_mul_f32_e32 v61, 0xbfb8aa3b, v41
	v_exp_f32_e32 v60, v60
	v_exp_f32_e32 v61, v61
	s_nop 0
	v_pk_add_f32 v[60:61], v[60:61], 1.0 op_sel_hi:[1,0]
	s_nop 0
	v_rcp_f32_e32 v63, v61
	s_nop 0
	v_fma_f32 v64, -v61, v63, 1.0
	v_fmac_f32_e32 v63, v64, v63
	v_div_fixup_f32 v61, v63, v61, 1.0
	v_rcp_f32_e32 v63, v60
	s_nop 0
	v_fma_f32 v64, -v60, v63, 1.0
	v_fmac_f32_e32 v63, v64, v63
	v_div_fixup_f32 v60, v63, v60, 1.0
	v_pk_mul_f32 v[40:41], v[40:41], v[60:61]
	s_nop 0
	v_pk_mul_f32 v[36:37], v[36:37], v[40:41]
	v_pk_mul_f32 v[40:41], v[26:27], v[74:75]
	s_nop 0
	v_pk_fma_f32 v[40:41], v[42:43], v[70:71], v[40:41]
	s_nop 0
	v_pk_fma_f32 v[40:41], v[10:11], v[78:79], v[40:41]
	s_nop 0
	v_pk_add_f32 v[40:41], v[82:83], v[40:41]
	s_nop 0
	v_mul_f32_e32 v42, 0xbfb8aa3b, v40
	v_mul_f32_e32 v43, 0xbfb8aa3b, v41
	v_exp_f32_e32 v42, v42
	v_exp_f32_e32 v43, v43
	s_nop 0
	v_pk_add_f32 v[42:43], v[42:43], 1.0 op_sel_hi:[1,0]
	s_nop 0
	v_rcp_f32_e32 v61, v43
	s_nop 0
	v_fma_f32 v62, -v43, v61, 1.0
	v_fmac_f32_e32 v61, v62, v61
	v_div_fixup_f32 v43, v61, v43, 1.0
	v_rcp_f32_e32 v61, v42
	s_nop 0
	v_fma_f32 v62, -v42, v61, 1.0
	v_fmac_f32_e32 v61, v62, v61
	v_div_fixup_f32 v42, v61, v42, 1.0
	v_pk_mul_f32 v[40:41], v[40:41], v[42:43]
	s_nop 0
	v_pk_mul_f32 v[38:39], v[38:39], v[40:41]
	v_pk_mul_f32 v[40:41], v[20:21], v[48:49]
	s_nop 0
	v_pk_fma_f32 v[32:33], v[32:33], v[44:45], v[40:41]
	s_nop 0
	v_pk_fma_f32 v[32:33], v[4:5], v[52:53], v[32:33]
	s_nop 0
	v_pk_add_f32 v[32:33], v[56:57], v[32:33]
	s_nop 0
	v_mul_f32_e32 v40, 0xbfb8aa3b, v32
	v_mul_f32_e32 v41, 0xbfb8aa3b, v33
	v_exp_f32_e32 v40, v40
	v_exp_f32_e32 v41, v41
	s_nop 0
	v_pk_add_f32 v[40:41], v[40:41], 1.0 op_sel_hi:[1,0]
	s_nop 0
	v_rcp_f32_e32 v43, v41
	s_nop 0
	v_fma_f32 v60, -v41, v43, 1.0
	v_fmac_f32_e32 v43, v60, v43
	v_div_fixup_f32 v41, v43, v41, 1.0
	v_rcp_f32_e32 v43, v40
	s_nop 0
	v_fma_f32 v60, -v40, v43, 1.0
	v_fmac_f32_e32 v43, v60, v43
	v_div_fixup_f32 v40, v43, v40, 1.0
	v_pk_mul_f32 v[32:33], v[32:33], v[40:41]
	s_nop 0
	v_pk_mul_f32 v[32:33], v[28:29], v[32:33]
	v_pk_mul_f32 v[28:29], v[22:23], v[50:51]
	s_nop 0
	v_pk_fma_f32 v[28:29], v[34:35], v[46:47], v[28:29]
	s_nop 0
	v_pk_fma_f32 v[28:29], v[6:7], v[54:55], v[28:29]
	s_nop 0
	v_pk_add_f32 v[28:29], v[58:59], v[28:29]
	s_nop 0
	v_mul_f32_e32 v34, 0xbfb8aa3b, v28
	v_mul_f32_e32 v35, 0xbfb8aa3b, v29
	v_exp_f32_e32 v34, v34
	v_exp_f32_e32 v35, v35
	s_nop 0
	v_pk_add_f32 v[34:35], v[34:35], 1.0 op_sel_hi:[1,0]
	s_nop 0
	v_rcp_f32_e32 v41, v35
	s_nop 0
	v_fma_f32 v42, -v35, v41, 1.0
	v_fmac_f32_e32 v41, v42, v41
	v_div_fixup_f32 v35, v41, v35, 1.0
	v_rcp_f32_e32 v41, v34
	s_nop 0
	v_fma_f32 v42, -v34, v41, 1.0
	v_fmac_f32_e32 v41, v42, v41
	v_div_fixup_f32 v34, v41, v34, 1.0
	v_pk_mul_f32 v[28:29], v[28:29], v[34:35]
	s_nop 0
	v_pk_mul_f32 v[34:35], v[30:31], v[28:29]
	v_cvt_pk_bf16_f32 v30, v32, v33
	v_or_b32_e32 v32, 6, v201
	v_mad_i64_i32 v[32:33], s[26:27], v32, s21, v[140:141]
	v_cvt_pk_bf16_f32 v28, v36, v37
	v_cvt_pk_bf16_f32 v29, v38, v39
	v_cvt_pk_bf16_f32 v31, v34, v35
	v_lshl_add_u64 v[32:33], v[32:33], 0, v[142:143]
	global_store_dwordx4 v[32:33], v[28:31], off
	s_nop 1
	v_pk_mul_f32 v[28:29], v[8:9], v[72:73]
	s_nop 0
	v_pk_fma_f32 v[24:25], v[24:25], v[68:69], v[28:29]
	s_nop 0
	v_pk_fma_f32 v[24:25], v[76:77], v[190:191], v[24:25]
	s_nop 0
	v_pk_add_f32 v[24:25], v[80:81], v[24:25]
	s_nop 0
	v_mul_f32_e32 v28, 0xbfb8aa3b, v24
	v_mul_f32_e32 v29, 0xbfb8aa3b, v25
	v_exp_f32_e32 v28, v28
	v_exp_f32_e32 v29, v29
	s_nop 0
	v_pk_add_f32 v[28:29], v[28:29], 1.0 op_sel_hi:[1,0]
	s_nop 0
	v_rcp_f32_e32 v31, v29
	s_nop 0
	v_fma_f32 v32, -v29, v31, 1.0
	v_fmac_f32_e32 v31, v32, v31
	v_div_fixup_f32 v29, v31, v29, 1.0
	v_rcp_f32_e32 v31, v28
	s_nop 0
	v_fma_f32 v32, -v28, v31, 1.0
	v_fmac_f32_e32 v31, v32, v31
	v_div_fixup_f32 v28, v31, v28, 1.0
	v_pk_mul_f32 v[30:31], v[10:11], v[74:75]
	v_pk_mul_f32 v[28:29], v[24:25], v[28:29]
	v_pk_fma_f32 v[26:27], v[26:27], v[70:71], v[30:31]
	v_pk_mul_f32 v[28:29], v[16:17], v[28:29]
	v_pk_fma_f32 v[26:27], v[78:79], v[188:189], v[26:27]
	v_cvt_pk_bf16_f32 v28, v28, v29
	v_pk_add_f32 v[26:27], v[82:83], v[26:27]
	s_nop 0
	v_mul_f32_e32 v30, 0xbfb8aa3b, v26
	v_mul_f32_e32 v31, 0xbfb8aa3b, v27
	v_exp_f32_e32 v30, v30
	v_exp_f32_e32 v31, v31
	s_nop 0
	v_pk_add_f32 v[30:31], v[30:31], 1.0 op_sel_hi:[1,0]
	s_nop 0
	v_rcp_f32_e32 v33, v31
	s_nop 0
	v_fma_f32 v34, -v31, v33, 1.0
	v_fmac_f32_e32 v33, v34, v33
	v_div_fixup_f32 v31, v33, v31, 1.0
	v_rcp_f32_e32 v33, v30
	s_nop 0
	v_fma_f32 v34, -v30, v33, 1.0
	v_fmac_f32_e32 v33, v34, v33
	v_div_fixup_f32 v30, v33, v30, 1.0
	v_pk_mul_f32 v[32:33], v[4:5], v[48:49]
	v_pk_mul_f32 v[30:31], v[26:27], v[30:31]
	v_pk_fma_f32 v[20:21], v[20:21], v[44:45], v[32:33]
	v_pk_mul_f32 v[30:31], v[18:19], v[30:31]
	v_pk_fma_f32 v[20:21], v[52:53], v[186:187], v[20:21]
	v_cvt_pk_bf16_f32 v29, v30, v31
	v_pk_add_f32 v[20:21], v[56:57], v[20:21]
	s_nop 0
	v_mul_f32_e32 v32, 0xbfb8aa3b, v20
	v_mul_f32_e32 v33, 0xbfb8aa3b, v21
	v_exp_f32_e32 v32, v32
	v_exp_f32_e32 v33, v33
	s_nop 0
	v_pk_add_f32 v[32:33], v[32:33], 1.0 op_sel_hi:[1,0]
	s_nop 0
	v_rcp_f32_e32 v35, v33
	s_nop 0
	v_fma_f32 v36, -v33, v35, 1.0
	v_fmac_f32_e32 v35, v36, v35
	v_div_fixup_f32 v33, v35, v33, 1.0
	v_rcp_f32_e32 v35, v32
	s_nop 0
	v_fma_f32 v36, -v32, v35, 1.0
	v_fmac_f32_e32 v35, v36, v35
	v_div_fixup_f32 v32, v35, v32, 1.0
	v_pk_mul_f32 v[34:35], v[6:7], v[50:51]
	v_pk_mul_f32 v[32:33], v[20:21], v[32:33]
	v_pk_fma_f32 v[22:23], v[22:23], v[46:47], v[34:35]
	v_pk_mul_f32 v[32:33], v[12:13], v[32:33]
	v_pk_fma_f32 v[22:23], v[54:55], v[184:185], v[22:23]
	v_cvt_pk_bf16_f32 v30, v32, v33
	v_pk_add_f32 v[22:23], v[58:59], v[22:23]
	v_or_b32_e32 v32, 7, v201
	v_mul_f32_e32 v34, 0xbfb8aa3b, v22
	v_mul_f32_e32 v35, 0xbfb8aa3b, v23
	v_exp_f32_e32 v34, v34
	v_exp_f32_e32 v35, v35
	v_mad_i64_i32 v[32:33], s[26:27], v32, s21, v[140:141]
	v_lshl_add_u64 v[32:33], v[32:33], 0, v[142:143]
	v_pk_add_f32 v[34:35], v[34:35], 1.0 op_sel_hi:[1,0]
	s_nop 0
	v_rcp_f32_e32 v37, v35
	s_nop 0
	v_fma_f32 v38, -v35, v37, 1.0
	v_fmac_f32_e32 v37, v38, v37
	v_div_fixup_f32 v35, v37, v35, 1.0
	v_rcp_f32_e32 v37, v34
	s_nop 0
	v_fma_f32 v38, -v34, v37, 1.0
	v_fmac_f32_e32 v37, v38, v37
	v_div_fixup_f32 v34, v37, v34, 1.0
	v_pk_mul_f32 v[34:35], v[22:23], v[34:35]
	s_nop 0
	v_pk_mul_f32 v[34:35], v[14:15], v[34:35]
	s_nop 0
	v_cvt_pk_bf16_f32 v31, v34, v35
	global_store_dwordx4 v[32:33], v[28:31], off
	s_and_saveexec_b64 s[26:27], s[4:5]
	s_cbranch_execz .LBB0_998
	s_or_b32 s19, s19, 1
	s_mul_hi_i32 s21, s19, 0x10800
	s_mul_i32 s19, s19, 0x10800
	s_add_u32 s28, s46, s19
	s_addc_u32 s29, s47, s21
	v_lshl_add_u64 v[28:29], v[182:183], 2, s[28:29]
	global_store_dwordx4 v[28:29], v[24:27], off
	global_store_dwordx4 v[28:29], v[20:23], off offset:16
	s_nop 1
	v_add_co_u32_e32 v20, vcc, 0x5000, v28
	s_nop 1
	v_addc_co_u32_e32 v21, vcc, 0, v29, vcc
	global_store_dwordx4 v[20:21], v[16:19], off offset:2048
	global_store_dwordx4 v[20:21], v[12:15], off offset:2064
	s_nop 1
	v_add_co_u32_e32 v12, vcc, 0xb000, v28
	s_nop 1
	v_addc_co_u32_e32 v13, vcc, 0, v29, vcc
	global_store_dwordx4 v[12:13], v[8:11], off
	global_store_dwordx4 v[12:13], v[4:7], off offset:16
	s_branch .LBB0_998

.LBB0_1117:
	s_mov_b32 s14, 0x2e8ba2e9
	s_waitcnt vmcnt(0)
	v_mul_hi_i32 v4, v1, s14
	v_lshrrev_b32_e32 v5, 31, v4
	v_ashrrev_i32_e32 v4, 8, v4
	v_add_u32_e32 v4, v4, v5
	v_add_u32_e32 v5, 1, v4
	v_and_b32_e32 v6, 31, v5
	v_cmp_eq_u32_e32 vcc, 0, v6
	s_mov_b32 s14, 0x15a80
	s_nop 0
	v_cndmask_b32_e64 v6, 0, 1, vcc
	v_cmp_gt_i32_e32 vcc, s14, v1
	s_nop 1
	v_cndmask_b32_e32 v6, v6, v4, vcc
	v_and_b32_e32 v6, 1, v6
	v_cmp_eq_u32_e32 vcc, 1, v6
	s_xor_b64 s[18:19], vcc, -1
	s_and_saveexec_b64 s[14:15], s[18:19]
	s_cbranch_execz .LBB0_1116
	v_lshlrev_b32_e32 v24, 7, v5
	v_mul_i32_i24_e32 v5, 0x580, v4
	v_lshlrev_b32_e32 v5, 2, v5
	v_sub_u32_e32 v20, v2, v5
	v_mad_i32_i24 v5, v4, 6, 3
	v_mov_b64_e32 v[6:7], s[6:7]
	s_movk_i32 s17, 0x5800
	v_ashrrev_i32_e32 v21, 31, v20
	v_mad_i32_i24 v4, v4, 6, 6
	v_mad_i64_i32 v[8:9], s[18:19], v5, s17, v[6:7]
	v_lshlrev_b64 v[22:23], 2, v[20:21]
	v_mad_i64_i32 v[4:5], s[18:19], v4, s17, v[6:7]
	v_lshl_add_u64 v[12:13], v[8:9], 0, v[22:23]
	s_movk_i32 s18, 0x5000
	v_lshl_add_u64 v[30:31], v[4:5], 0, v[22:23]
	v_add_co_u32_e32 v4, vcc, s18, v12
	s_mov_b32 s17, 0xb000
	s_nop 0
	v_addc_co_u32_e32 v5, vcc, 0, v13, vcc
	global_load_dwordx4 v[26:29], v[12:13], off
	global_load_dwordx4 v[8:11], v[4:5], off offset:2048
	v_add_co_u32_e32 v4, vcc, s17, v12
	v_lshl_add_u64 v[34:35], s[8:9], 0, v[22:23]
	s_nop 0
	v_addc_co_u32_e32 v5, vcc, 0, v13, vcc
	global_load_dwordx4 v[12:15], v[4:5], off
	global_load_dwordx4 v[16:19], v[30:31], off
	v_add_co_u32_e32 v4, vcc, s18, v30
	v_lshl_add_u64 v[22:23], s[10:11], 0, v[22:23]
	s_nop 0
	v_addc_co_u32_e32 v5, vcc, 0, v31, vcc
	v_add_co_u32_e32 v30, vcc, s17, v30
	global_load_dwordx4 v[38:41], v[22:23], off
	s_nop 0
	v_addc_co_u32_e32 v31, vcc, 0, v31, vcc
	global_load_dwordx4 v[30:33], v[30:31], off
	s_movk_i32 s17, 0x2c00
	global_load_dwordx4 v[34:37], v[34:35], off
	s_waitcnt vmcnt(1)
	v_pk_fma_f32 v[26:27], v[30:31], v[38:39], v[26:27]
	global_load_dwordx4 v[4:7], v[4:5], off offset:2048
	v_mul_f32_e32 v25, 0xbfb8aa3b, v26
	v_pk_fma_f32 v[22:23], v[32:33], v[40:41], v[28:29]
	v_exp_f32_e32 v28, v25
	v_mul_f32_e32 v25, 0xbfb8aa3b, v27
	v_exp_f32_e32 v29, v25
	s_waitcnt vmcnt(1)
	v_pk_fma_f32 v[12:13], v[12:13], v[34:35], v[16:17]
	v_pk_fma_f32 v[14:15], v[14:15], v[36:37], v[18:19]
	v_mul_f32_e32 v16, 0xbfb8aa3b, v12
	v_pk_add_f32 v[28:29], v[28:29], 1.0 op_sel_hi:[1,0]
	v_mul_f32_e32 v17, 0xbfb8aa3b, v13
	v_rcp_f32_e32 v30, v29
	v_exp_f32_e32 v16, v16
	v_exp_f32_e32 v17, v17
	v_fma_f32 v31, -v29, v30, 1.0
	v_fmac_f32_e32 v30, v31, v30
	v_div_fixup_f32 v29, v30, v29, 1.0
	v_rcp_f32_e32 v30, v28
	v_pk_add_f32 v[16:17], v[16:17], 1.0 op_sel_hi:[1,0]
	v_fma_f32 v31, -v28, v30, 1.0
	v_fmac_f32_e32 v30, v31, v30
	v_div_scale_f32 v18, s[18:19], v17, v17, 1.0
	v_rcp_f32_e32 v19, v18
	v_div_fixup_f32 v28, v30, v28, 1.0
	v_fma_f32 v25, -v18, v19, 1.0
	v_pk_mul_f32 v[26:27], v[26:27], v[28:29]
	v_fmac_f32_e32 v19, v25, v19
	v_div_scale_f32 v25, vcc, 1.0, v17, 1.0
	v_pk_mul_f32 v[8:9], v[8:9], v[26:27]
	v_mul_f32_e32 v26, v25, v19
	v_fma_f32 v27, -v18, v26, v25
	v_fmac_f32_e32 v26, v27, v19
	v_fma_f32 v18, -v18, v26, v25
	v_div_fmas_f32 v18, v18, v19, v26
	v_div_fixup_f32 v17, v18, v17, 1.0
	v_rcp_f32_e32 v19, v16
	v_cvt_pk_bf16_f32 v8, v8, v9
	v_fma_f32 v25, -v16, v19, 1.0
	v_fmac_f32_e32 v19, v25, v19
	v_div_fixup_f32 v16, v19, v16, 1.0
	v_pk_mul_f32 v[12:13], v[12:13], v[16:17]
	s_waitcnt vmcnt(0)
	v_pk_mul_f32 v[4:5], v[4:5], v[12:13]
	v_mul_f32_e32 v12, 0xbfb8aa3b, v22
	v_mul_f32_e32 v13, 0xbfb8aa3b, v23
	v_exp_f32_e32 v12, v12
	v_exp_f32_e32 v13, v13
	v_cvt_pk_bf16_f32 v4, v4, v5
	v_pk_add_f32 v[12:13], v[12:13], 1.0 op_sel_hi:[1,0]
	s_nop 0
	v_rcp_f32_e32 v17, v13
	s_nop 0
	v_fma_f32 v18, -v13, v17, 1.0
	v_fmac_f32_e32 v17, v18, v17
	v_div_fixup_f32 v13, v17, v13, 1.0
	v_rcp_f32_e32 v17, v12
	s_nop 0
	v_fma_f32 v18, -v12, v17, 1.0
	v_fmac_f32_e32 v17, v18, v17
	v_div_fixup_f32 v12, v17, v12, 1.0
	v_pk_mul_f32 v[12:13], v[22:23], v[12:13]
	s_nop 0
	v_pk_mul_f32 v[10:11], v[10:11], v[12:13]
	v_mul_f32_e32 v12, 0xbfb8aa3b, v14
	v_mul_f32_e32 v13, 0xbfb8aa3b, v15
	v_exp_f32_e32 v12, v12
	v_exp_f32_e32 v13, v13
	v_cvt_pk_bf16_f32 v9, v10, v11
	v_mov_b64_e32 v[10:11], s[4:5]
	v_pk_add_f32 v[12:13], v[12:13], 1.0 op_sel_hi:[1,0]
	s_nop 0
	v_rcp_f32_e32 v17, v13
	s_nop 0
	v_fma_f32 v18, -v13, v17, 1.0
	v_fmac_f32_e32 v17, v18, v17
	v_div_fixup_f32 v13, v17, v13, 1.0
	v_rcp_f32_e32 v17, v12
	s_nop 0
	v_fma_f32 v18, -v12, v17, 1.0
	v_fmac_f32_e32 v17, v18, v17
	v_div_fixup_f32 v12, v17, v12, 1.0
	v_pk_mul_f32 v[12:13], v[14:15], v[12:13]
	v_lshlrev_b64 v[14:15], 1, v[20:21]
	v_pk_mul_f32 v[6:7], v[6:7], v[12:13]
	v_add_u32_e32 v12, -1, v24
	v_mad_i64_i32 v[12:13], s[18:19], v12, s17, v[10:11]
	v_cvt_pk_bf16_f32 v5, v6, v7
	v_mad_i64_i32 v[6:7], s[18:19], v24, s17, v[10:11]
	v_lshl_add_u64 v[12:13], v[12:13], 0, v[14:15]
	v_lshl_add_u64 v[6:7], v[6:7], 0, v[14:15]
	global_store_dwordx2 v[12:13], v[8:9], off
	global_store_dwordx2 v[6:7], v[4:5], off
	s_branch .LBB0_1116

.LBB0_1313:
	v_ashrrev_i32_e32 v2, 31, v5
	v_lshrrev_b32_e32 v2, 21, v2
	v_add_u32_e32 v2, v5, v2
	s_waitcnt vmcnt(10)
	v_ashrrev_i32_e32 v7, 11, v2
	v_mul_i32_i24_e32 v7, 0x800, v7
	v_add_u32_e32 v6, 0x7ff, v5
	v_and_b32_e32 v2, 0xfffff800, v2
	v_sub_u32_e32 v7, v5, v7
	v_add3_u32 v2, v7, v2, s7
	v_cmp_gt_u32_e32 vcc, s6, v6
	s_nop 1
	v_cndmask_b32_e32 v6, v2, v7, vcc
	v_cndmask_b32_e64 v2, 56, 64, vcc
	v_lshl_add_u64 v[8:9], s[2:3], 0, v[2:3]
	global_load_dwordx2 v[8:9], v[8:9], off
	v_ashrrev_i32_e32 v7, 31, v6
	v_cmp_lt_i32_e32 vcc, s8, v5
	s_or_b64 s[4:5], vcc, s[4:5]
	v_add_u32_e32 v5, 0x200, v5
	s_waitcnt vmcnt(0)
	v_lshl_add_u64 v[6:7], v[6:7], 2, v[8:9]
	global_load_dword v2, v[6:7], off
	s_waitcnt vmcnt(0)
	v_mul_f32_e32 v6, 0xbfb8aa3b, v2
	v_exp_f32_e32 v6, v6
	s_nop 0
	v_add_f32_e32 v6, 1.0, v6
	v_rcp_f32_e32 v8, v6
	s_nop 0
	v_fma_f32 v10, -v6, v8, 1.0
	v_fmac_f32_e32 v8, v10, v8
	v_div_fixup_f32 v6, v8, v6, 1.0
	v_mul_f32_e32 v2, v2, v6
	ds_write_b32 v1, v2
	v_add_u32_e32 v1, 0x800, v1
	s_andn2_b64 exec, exec, s[4:5]
	s_cbranch_execnz .LBB0_1313
	s_or_b64 exec, exec, s[4:5]
